# attention v2: softmax scale folded into q in the projection epilogue (f32, before the bf16 rounding), reference-0 fast path without per-element subtraction plus running-max slow path taken when a tile
# speedup vs baseline: 1.0155x; 1.0155x over previous
.LBB0_503:
.LBB0_504:
	s_cmp_lt_i32 s50, 4
	s_cbranch_scc0 .Linb_noscale
	v_mul_f32_e32 v0, 0x3e38aa3b, v0
	v_mul_f32_e32 v1, 0x3e38aa3b, v1
	v_mul_f32_e32 v2, 0x3e38aa3b, v2
	v_mul_f32_e32 v3, 0x3e38aa3b, v3
	v_mul_f32_e32 v4, 0x3e38aa3b, v4
	v_mul_f32_e32 v5, 0x3e38aa3b, v5
	v_mul_f32_e32 v6, 0x3e38aa3b, v6
	v_mul_f32_e32 v7, 0x3e38aa3b, v7
	v_mul_f32_e32 v8, 0x3e38aa3b, v8
	v_mul_f32_e32 v9, 0x3e38aa3b, v9
	v_mul_f32_e32 v10, 0x3e38aa3b, v10
	v_mul_f32_e32 v11, 0x3e38aa3b, v11
	v_mul_f32_e32 v12, 0x3e38aa3b, v12
	v_mul_f32_e32 v13, 0x3e38aa3b, v13
	v_mul_f32_e32 v14, 0x3e38aa3b, v14
	v_mul_f32_e32 v15, 0x3e38aa3b, v15
	v_mul_f32_e32 v16, 0x3e38aa3b, v16
	v_mul_f32_e32 v17, 0x3e38aa3b, v17
	v_mul_f32_e32 v18, 0x3e38aa3b, v18
	v_mul_f32_e32 v19, 0x3e38aa3b, v19
	v_mul_f32_e32 v20, 0x3e38aa3b, v20
	v_mul_f32_e32 v21, 0x3e38aa3b, v21
	v_mul_f32_e32 v22, 0x3e38aa3b, v22
	v_mul_f32_e32 v23, 0x3e38aa3b, v23
	v_mul_f32_e32 v24, 0x3e38aa3b, v24
	v_mul_f32_e32 v25, 0x3e38aa3b, v25
	v_mul_f32_e32 v26, 0x3e38aa3b, v26
	v_mul_f32_e32 v27, 0x3e38aa3b, v27
	v_mul_f32_e32 v28, 0x3e38aa3b, v28
	v_mul_f32_e32 v29, 0x3e38aa3b, v29
	v_mul_f32_e32 v30, 0x3e38aa3b, v30
	v_mul_f32_e32 v31, 0x3e38aa3b, v31
	v_mul_f32_e32 v32, 0x3e38aa3b, v32
	v_mul_f32_e32 v33, 0x3e38aa3b, v33
	v_mul_f32_e32 v34, 0x3e38aa3b, v34
	v_mul_f32_e32 v35, 0x3e38aa3b, v35
	v_mul_f32_e32 v36, 0x3e38aa3b, v36
	v_mul_f32_e32 v37, 0x3e38aa3b, v37
	v_mul_f32_e32 v38, 0x3e38aa3b, v38
	v_mul_f32_e32 v39, 0x3e38aa3b, v39
	v_mul_f32_e32 v40, 0x3e38aa3b, v40
	v_mul_f32_e32 v41, 0x3e38aa3b, v41
	v_mul_f32_e32 v42, 0x3e38aa3b, v42
	v_mul_f32_e32 v43, 0x3e38aa3b, v43
	v_mul_f32_e32 v44, 0x3e38aa3b, v44
	v_mul_f32_e32 v45, 0x3e38aa3b, v45
	v_mul_f32_e32 v46, 0x3e38aa3b, v46
	v_mul_f32_e32 v47, 0x3e38aa3b, v47
	v_mul_f32_e32 v48, 0x3e38aa3b, v48
	v_mul_f32_e32 v49, 0x3e38aa3b, v49
	v_mul_f32_e32 v50, 0x3e38aa3b, v50
	v_mul_f32_e32 v51, 0x3e38aa3b, v51
	v_mul_f32_e32 v52, 0x3e38aa3b, v52
	v_mul_f32_e32 v53, 0x3e38aa3b, v53
	v_mul_f32_e32 v54, 0x3e38aa3b, v54
	v_mul_f32_e32 v55, 0x3e38aa3b, v55
	v_mul_f32_e32 v56, 0x3e38aa3b, v56
	v_mul_f32_e32 v57, 0x3e38aa3b, v57
	v_mul_f32_e32 v58, 0x3e38aa3b, v58
	v_mul_f32_e32 v59, 0x3e38aa3b, v59
	v_mul_f32_e32 v60, 0x3e38aa3b, v60
	v_mul_f32_e32 v61, 0x3e38aa3b, v61
	v_mul_f32_e32 v62, 0x3e38aa3b, v62
	v_mul_f32_e32 v63, 0x3e38aa3b, v63
	v_mul_f32_e32 v64, 0x3e38aa3b, v64
	v_mul_f32_e32 v65, 0x3e38aa3b, v65
	v_mul_f32_e32 v66, 0x3e38aa3b, v66
	v_mul_f32_e32 v67, 0x3e38aa3b, v67
	v_mul_f32_e32 v68, 0x3e38aa3b, v68
	v_mul_f32_e32 v69, 0x3e38aa3b, v69
	v_mul_f32_e32 v70, 0x3e38aa3b, v70
	v_mul_f32_e32 v71, 0x3e38aa3b, v71
	v_mul_f32_e32 v72, 0x3e38aa3b, v72
	v_mul_f32_e32 v73, 0x3e38aa3b, v73
	v_mul_f32_e32 v74, 0x3e38aa3b, v74
	v_mul_f32_e32 v75, 0x3e38aa3b, v75
	v_mul_f32_e32 v76, 0x3e38aa3b, v76
	v_mul_f32_e32 v77, 0x3e38aa3b, v77
	v_mul_f32_e32 v78, 0x3e38aa3b, v78
	v_mul_f32_e32 v79, 0x3e38aa3b, v79
	v_mul_f32_e32 v80, 0x3e38aa3b, v80
	v_mul_f32_e32 v81, 0x3e38aa3b, v81
	v_mul_f32_e32 v82, 0x3e38aa3b, v82
	v_mul_f32_e32 v83, 0x3e38aa3b, v83
	v_mul_f32_e32 v84, 0x3e38aa3b, v84
	v_mul_f32_e32 v85, 0x3e38aa3b, v85
	v_mul_f32_e32 v86, 0x3e38aa3b, v86
	v_mul_f32_e32 v87, 0x3e38aa3b, v87
	v_mul_f32_e32 v88, 0x3e38aa3b, v88
	v_mul_f32_e32 v89, 0x3e38aa3b, v89
	v_mul_f32_e32 v90, 0x3e38aa3b, v90
	v_mul_f32_e32 v91, 0x3e38aa3b, v91
	v_mul_f32_e32 v92, 0x3e38aa3b, v92
	v_mul_f32_e32 v93, 0x3e38aa3b, v93
	v_mul_f32_e32 v94, 0x3e38aa3b, v94
	v_mul_f32_e32 v95, 0x3e38aa3b, v95
	v_mul_f32_e32 v96, 0x3e38aa3b, v96
	v_mul_f32_e32 v97, 0x3e38aa3b, v97
	v_mul_f32_e32 v98, 0x3e38aa3b, v98
	v_mul_f32_e32 v99, 0x3e38aa3b, v99
	v_mul_f32_e32 v100, 0x3e38aa3b, v100
	v_mul_f32_e32 v101, 0x3e38aa3b, v101
	v_mul_f32_e32 v102, 0x3e38aa3b, v102
	v_mul_f32_e32 v103, 0x3e38aa3b, v103
	v_mul_f32_e32 v104, 0x3e38aa3b, v104
	v_mul_f32_e32 v105, 0x3e38aa3b, v105
	v_mul_f32_e32 v106, 0x3e38aa3b, v106
	v_mul_f32_e32 v107, 0x3e38aa3b, v107
	v_mul_f32_e32 v108, 0x3e38aa3b, v108
	v_mul_f32_e32 v109, 0x3e38aa3b, v109
	v_mul_f32_e32 v110, 0x3e38aa3b, v110
	v_mul_f32_e32 v111, 0x3e38aa3b, v111
	v_mul_f32_e32 v112, 0x3e38aa3b, v112
	v_mul_f32_e32 v113, 0x3e38aa3b, v113
	v_mul_f32_e32 v114, 0x3e38aa3b, v114
	v_mul_f32_e32 v115, 0x3e38aa3b, v115
	v_mul_f32_e32 v116, 0x3e38aa3b, v116
	v_mul_f32_e32 v117, 0x3e38aa3b, v117
	v_mul_f32_e32 v118, 0x3e38aa3b, v118
	v_mul_f32_e32 v119, 0x3e38aa3b, v119
	v_mul_f32_e32 v120, 0x3e38aa3b, v120
	v_mul_f32_e32 v121, 0x3e38aa3b, v121
	v_mul_f32_e32 v122, 0x3e38aa3b, v122
	v_mul_f32_e32 v123, 0x3e38aa3b, v123
	v_mul_f32_e32 v124, 0x3e38aa3b, v124
	v_mul_f32_e32 v125, 0x3e38aa3b, v125
	v_mul_f32_e32 v126, 0x3e38aa3b, v126
	v_mul_f32_e32 v127, 0x3e38aa3b, v127

.LBB0_629:
	s_lshl_b32 s30, s46, 4
	s_add_i32 s38, s1, s30
	v_readlane_b32 s30, v253, 52
	s_ashr_i32 s39, s2, 4
	v_readlane_b32 s31, v253, 53
	s_and_b64 s[30:31], s[30:31], exec
	s_cselect_b32 s39, s38, s39
	s_cselect_b32 s2, s4, s2
	s_ashr_i32 s40, s39, 3
	s_and_b32 s38, s2, 15
	s_ashr_i32 s41, s40, 31
	s_lshl_b64 s[42:43], s[40:41], 11
	v_lshl_or_b32 v0, s38, 7, v178
	v_or_b32_e32 v168, s42, v0
	v_mov_b64_e32 v[0:1], s[6:7]
	s_movk_i32 s47, 0x1100
	s_lshl_b32 s2, s39, 7
	v_mad_u64_u32 v[2:3], s[30:31], v168, s47, v[0:1]
	s_and_b32 s2, s2, 0x380
	v_mad_i32_i24 v3, s43, v242, v3
	s_lshl_b32 s30, s2, 1
	s_mov_b32 s31, s3
	v_lshl_add_u64 v[2:3], v[2:3], 0, s[30:31]
	v_lshl_add_u64 v[2:3], s[14:15], 1, v[2:3]
	v_lshl_add_u64 v[2:3], v[2:3], 0, v[192:193]
	global_load_dwordx4 v[128:131], v[2:3], off
	global_load_dwordx4 v[132:135], v[2:3], off offset:32
	global_load_dwordx4 v[136:139], v[2:3], off offset:64
	global_load_dwordx4 v[140:143], v[2:3], off offset:96
	v_lshl_add_u64 v[2:3], s[42:43], 0, v[160:161]
	v_mov_b32_e32 v169, s43
	v_mad_u64_u32 v[0:1], s[42:43], v2, s47, v[0:1]
	v_mad_i32_i24 v1, v3, s47, v1
	v_lshl_add_u64 v[0:1], v[0:1], 0, s[30:31]
	v_mov_b32_e32 v165, v193
	v_lshl_add_u64 v[170:171], v[0:1], 0, v[164:165]
	v_add_u32_e32 v2, s2, v160
	v_mov_b64_e32 v[0:1], s[10:11]
	v_mad_i64_i32 v[0:1], s[42:43], v2, s73, v[0:1]
	s_lshl_b64 s[40:41], s[40:41], 12
	v_lshl_add_u64 v[0:1], v[0:1], 0, s[40:41]
	s_mul_i32 s2, s38, 0x88000
	v_lshl_add_u64 v[172:173], v[0:1], 0, v[164:165]
	s_lshl_b32 s31, s38, 1
	s_not_b64 s[38:39], s[16:17]
	v_and_b32_e32 v34, 64, v240
	v_xor_b32_e32 v33, 32, v240
	v_add_u32_e32 v34, 64, v34
	v_cmp_lt_i32_e32 vcc, v33, v34
	s_nop 1
	v_cndmask_b32_e32 v33, v240, v33, vcc
	v_lshlrev_b32_e32 v165, 2, v33
	s_mov_b32 s42, s31
	s_add_i32 s2, s42, 0
	s_and_b32 s2, s2, 31
	s_mul_i32 s2, s2, 0x44000
	s_add_i32 m0, s5, 0
	v_lshl_add_u64 v[232:233], v[170:171], 0, s[2:3]
	v_lshl_add_u64 v[234:235], v[232:233], 0, s[18:19]
	global_load_lds_dwordx4 v[234:235], off
	s_add_i32 m0, s5, 8192
	v_lshl_add_u64 v[232:233], v[232:233], 0, s[20:21]
	global_load_lds_dwordx4 v[232:233], off
	s_add_i32 s2, s42, 1
	s_and_b32 s2, s2, 31
	s_mul_i32 s2, s2, 0x44000
	s_add_i32 m0, s5, 16384
	v_lshl_add_u64 v[232:233], v[170:171], 0, s[2:3]
	v_lshl_add_u64 v[234:235], v[232:233], 0, s[18:19]
	global_load_lds_dwordx4 v[234:235], off
	s_add_i32 m0, s5, 24576
	v_lshl_add_u64 v[232:233], v[232:233], 0, s[20:21]
	global_load_lds_dwordx4 v[232:233], off
	s_add_i32 s2, s42, 0
	s_and_b32 s2, s2, 31
	s_lshl_b32 s2, s2, 7
	s_add_i32 m0, s5, 65536
	v_lshl_add_u64 v[232:233], v[172:173], 0, s[2:3]
	global_load_lds_dwordx4 v[232:233], off
	s_add_i32 m0, s5, 73728
	v_lshl_add_u64 v[234:235], v[232:233], 0, s[22:23]
	global_load_lds_dwordx4 v[234:235], off
	s_add_i32 s2, s42, 2
	s_and_b32 s2, s2, 31
	s_mul_i32 s2, s2, 0x44000
	s_add_i32 m0, s5, 32768
	v_lshl_add_u64 v[232:233], v[170:171], 0, s[2:3]
	v_lshl_add_u64 v[234:235], v[232:233], 0, s[18:19]
	global_load_lds_dwordx4 v[234:235], off
	s_add_i32 m0, s5, 40960
	v_lshl_add_u64 v[232:233], v[232:233], 0, s[20:21]
	global_load_lds_dwordx4 v[232:233], off
	s_add_i32 s2, s42, 1
	s_and_b32 s2, s2, 31
	s_lshl_b32 s2, s2, 7
	s_add_i32 m0, s5, 81920
	v_lshl_add_u64 v[232:233], v[172:173], 0, s[2:3]
	global_load_lds_dwordx4 v[232:233], off
	s_add_i32 m0, s5, 90112
	v_lshl_add_u64 v[234:235], v[232:233], 0, s[22:23]
	global_load_lds_dwordx4 v[234:235], off
	v_mov_b32_e32 v0, 0
	v_mov_b32_e32 v1, 0
	v_mov_b32_e32 v2, 0
	v_mov_b32_e32 v3, 0
	v_mov_b32_e32 v4, 0
	v_mov_b32_e32 v5, 0
	v_mov_b32_e32 v6, 0
	v_mov_b32_e32 v7, 0
	v_mov_b32_e32 v8, 0
	v_mov_b32_e32 v9, 0
	v_mov_b32_e32 v10, 0
	v_mov_b32_e32 v11, 0
	v_mov_b32_e32 v12, 0
	v_mov_b32_e32 v13, 0
	v_mov_b32_e32 v14, 0
	v_mov_b32_e32 v15, 0
	v_mov_b32_e32 v16, 0
	v_mov_b32_e32 v17, 0
	v_mov_b32_e32 v18, 0
	v_mov_b32_e32 v19, 0
	v_mov_b32_e32 v20, 0
	v_mov_b32_e32 v21, 0
	v_mov_b32_e32 v22, 0
	v_mov_b32_e32 v23, 0
	v_mov_b32_e32 v24, 0
	v_mov_b32_e32 v25, 0
	v_mov_b32_e32 v26, 0
	v_mov_b32_e32 v27, 0
	v_mov_b32_e32 v28, 0
	v_mov_b32_e32 v29, 0
	v_mov_b32_e32 v30, 0
	v_mov_b32_e32 v31, 0
	v_mov_b32_e32 v32, 0
	v_mov_b32_e32 v33, 0
	v_mov_b32_e32 v34, 0
	v_mov_b32_e32 v35, 0
	v_mov_b32_e32 v36, 0
	v_mov_b32_e32 v37, 0
	v_mov_b32_e32 v38, 0
	v_mov_b32_e32 v39, 0
	v_mov_b32_e32 v40, 0
	v_mov_b32_e32 v41, 0
	v_mov_b32_e32 v42, 0
	v_mov_b32_e32 v43, 0
	v_mov_b32_e32 v44, 0
	v_mov_b32_e32 v45, 0
	v_mov_b32_e32 v46, 0
	v_mov_b32_e32 v47, 0
	v_mov_b32_e32 v48, 0
	v_mov_b32_e32 v49, 0
	v_mov_b32_e32 v50, 0
	v_mov_b32_e32 v51, 0
	v_mov_b32_e32 v52, 0
	v_mov_b32_e32 v53, 0
	v_mov_b32_e32 v54, 0
	v_mov_b32_e32 v55, 0
	v_mov_b32_e32 v56, 0
	v_mov_b32_e32 v57, 0
	v_mov_b32_e32 v58, 0
	v_mov_b32_e32 v59, 0
	v_mov_b32_e32 v60, 0
	v_mov_b32_e32 v61, 0
	v_mov_b32_e32 v62, 0
	v_mov_b32_e32 v63, 0
	v_mov_b32_e32 v167, 0
	v_mov_b32_e32 v175, 0
	v_mov_b32_e32 v174, 1.0
	s_waitcnt vmcnt(8)
	s_barrier
	ds_read_b128 v[96:99], v182 offset:0
	ds_read_b128 v[100:103], v182 offset:4096
	ds_read_b128 v[104:107], v183 offset:0
	ds_read_b128 v[108:111], v183 offset:4096
	ds_read_b128 v[112:115], v184 offset:0
	ds_read_b128 v[116:119], v184 offset:4096
	ds_read_b128 v[120:123], v185 offset:0
	ds_read_b128 v[124:127], v185 offset:4096
	s_waitcnt lgkmcnt(0)
	v_mfma_f32_32x32x16_bf16 v[64:79], v[96:99], v[128:131], 0
	v_mfma_f32_32x32x16_bf16 v[80:95], v[100:103], v[128:131], 0
	v_mfma_f32_32x32x16_bf16 v[64:79], v[104:107], v[132:135], v[64:79]
	v_mfma_f32_32x32x16_bf16 v[80:95], v[108:111], v[132:135], v[80:95]
	v_mfma_f32_32x32x16_bf16 v[64:79], v[112:115], v[136:139], v[64:79]
	v_mfma_f32_32x32x16_bf16 v[80:95], v[116:119], v[136:139], v[80:95]
	v_mfma_f32_32x32x16_bf16 v[64:79], v[120:123], v[140:143], v[64:79]
	v_mfma_f32_32x32x16_bf16 v[80:95], v[124:127], v[140:143], v[80:95]
	s_waitcnt vmcnt(4)
	s_barrier
	ds_read_b128 v[208:211], v182 offset:16384
	ds_read_b128 v[212:215], v182 offset:20480
	ds_read_b128 v[216:219], v183 offset:16384
	ds_read_b128 v[220:223], v183 offset:20480
	ds_read_b128 v[224:227], v184 offset:16384
	ds_read_b128 v[228:231], v184 offset:20480
	s_nop 7
	s_waitcnt lgkmcnt(5)
	v_mfma_f32_32x32x16_bf16 v[96:111], v[208:211], v[128:131], 0
	ds_read_b128 v[208:211], v185 offset:16384
	s_add_i32 s2, s42, 3
	v_max3_f32 v254, v64, v65, v66
	s_and_b32 s2, s2, 31
	v_max3_f32 v255, v80, v81, v82
	s_mul_i32 s2, s2, 0x44000
	v_max3_f32 v254, v254, v67, v68
	s_add_i32 m0, s5, 49152
	v_max3_f32 v255, v255, v83, v84
	s_waitcnt lgkmcnt(5)
	v_mfma_f32_32x32x16_bf16 v[112:127], v[212:215], v[128:131], 0
	ds_read_b128 v[212:215], v185 offset:20480
	v_lshl_add_u64 v[232:233], v[170:171], 0, s[2:3]
	v_max3_f32 v254, v254, v69, v70
	v_lshl_add_u64 v[234:235], v[232:233], 0, s[18:19]
	v_max3_f32 v255, v255, v85, v86
	global_load_lds_dwordx4 v[234:235], off
	v_max3_f32 v254, v254, v71, v72
	s_add_i32 m0, s5, 57344
	v_max3_f32 v255, v255, v87, v88
	s_waitcnt lgkmcnt(5)
	v_mfma_f32_32x32x16_bf16 v[96:111], v[216:219], v[132:135], v[96:111]
	ds_read_b128 v[216:219], v187 offset:0
	v_lshl_add_u64 v[232:233], v[232:233], 0, s[20:21]
	v_max3_f32 v254, v254, v73, v74
	global_load_lds_dwordx4 v[232:233], off
	v_max3_f32 v255, v255, v89, v90
	s_add_i32 s2, s42, 2
	v_max3_f32 v254, v254, v75, v76
	s_and_b32 s2, s2, 31
	v_max3_f32 v255, v255, v91, v92
	s_waitcnt lgkmcnt(5)
	v_mfma_f32_32x32x16_bf16 v[112:127], v[220:223], v[132:135], v[112:127]
	ds_read_b128 v[220:223], v187 offset:4096
	s_lshl_b32 s2, s2, 7
	v_max3_f32 v254, v254, v77, v78
	v_max3_f32 v255, v255, v93, v94
	v_max3_f32 v254, v254, v79, v95
	v_max_f32_e32 v254, v254, v255
	v_mov_b32_e32 v180, 0xc2800000
	v_cmp_lt_f32_e32 vcc, 0x4138aa3b, v254
	v_cmp_gt_f32_e64 s[40:41], v180, v254
	s_waitcnt lgkmcnt(5)
	v_mfma_f32_32x32x16_bf16 v[96:111], v[224:227], v[136:139], v[96:111]
	ds_read_b128 v[224:227], v187 offset:8192
	s_add_i32 m0, s5, 98304
	v_lshl_add_u64 v[232:233], v[172:173], 0, s[2:3]
	global_load_lds_dwordx4 v[232:233], off
	s_add_i32 m0, s5, 106496
	v_lshl_add_u64 v[234:235], v[232:233], 0, s[22:23]
	global_load_lds_dwordx4 v[234:235], off
	s_or_b64 vcc, vcc, s[40:41]
	s_nop 0
	s_cbranch_vccnz .Lattn_sp_t0
	v_exp_f32_e32 v64, v64
	v_exp_f32_e32 v65, v65
	v_exp_f32_e32 v66, v66
	v_exp_f32_e32 v67, v67
	v_exp_f32_e32 v68, v68
	v_exp_f32_e32 v69, v69
	v_exp_f32_e32 v70, v70
	v_exp_f32_e32 v71, v71
	v_add_f32_e32 v190, v64, v65
	v_add_f32_e32 v191, v66, v67
	v_add_f32_e32 v190, v190, v68
	v_add_f32_e32 v191, v191, v69
	v_add_f32_e32 v190, v190, v70
	v_add_f32_e32 v191, v191, v71
	v_cvt_pk_bf16_f32 v144, v64, v65
	v_cvt_pk_bf16_f32 v145, v66, v67
	v_cvt_pk_bf16_f32 v146, v68, v69
	v_cvt_pk_bf16_f32 v147, v70, v71
	s_waitcnt lgkmcnt(5)
	v_mfma_f32_32x32x16_bf16 v[112:127], v[228:231], v[136:139], v[112:127]
	ds_read_b128 v[228:231], v187 offset:12288
	s_waitcnt lgkmcnt(5)
	v_mfma_f32_32x32x16_bf16 v[96:111], v[208:211], v[140:143], v[96:111]
	ds_read_b128 v[208:211], v188 offset:0
	s_waitcnt lgkmcnt(5)
	v_mfma_f32_32x32x16_bf16 v[112:127], v[212:215], v[140:143], v[112:127]
	ds_read_b128 v[212:215], v188 offset:4096
	v_exp_f32_e32 v72, v72
	v_exp_f32_e32 v73, v73
	v_exp_f32_e32 v74, v74
	v_exp_f32_e32 v75, v75
	v_exp_f32_e32 v76, v76
	v_exp_f32_e32 v77, v77
	v_exp_f32_e32 v78, v78
	v_exp_f32_e32 v79, v79
	v_add_f32_e32 v190, v190, v72
	v_add_f32_e32 v191, v191, v73
	v_add_f32_e32 v190, v190, v74
	v_add_f32_e32 v191, v191, v75
	v_add_f32_e32 v190, v190, v76
	v_add_f32_e32 v191, v191, v77
	v_add_f32_e32 v190, v190, v78
	v_add_f32_e32 v191, v191, v79
	v_cvt_pk_bf16_f32 v148, v72, v73
	v_cvt_pk_bf16_f32 v149, v74, v75
	v_cvt_pk_bf16_f32 v150, v76, v77
	v_cvt_pk_bf16_f32 v151, v78, v79
	v_exp_f32_e32 v80, v80
	v_exp_f32_e32 v81, v81
	v_exp_f32_e32 v82, v82
	v_exp_f32_e32 v83, v83
	v_exp_f32_e32 v84, v84
	v_exp_f32_e32 v85, v85
	v_exp_f32_e32 v86, v86
	v_exp_f32_e32 v87, v87
	v_add_f32_e32 v190, v190, v80
	v_add_f32_e32 v191, v191, v81
	v_add_f32_e32 v190, v190, v82
	v_add_f32_e32 v191, v191, v83
	v_add_f32_e32 v190, v190, v84
	v_add_f32_e32 v191, v191, v85
	v_add_f32_e32 v190, v190, v86
	v_add_f32_e32 v191, v191, v87
	v_cvt_pk_bf16_f32 v152, v80, v81
	v_cvt_pk_bf16_f32 v153, v82, v83
	v_cvt_pk_bf16_f32 v154, v84, v85
	v_cvt_pk_bf16_f32 v155, v86, v87
	v_exp_f32_e32 v88, v88
	v_exp_f32_e32 v89, v89
	v_exp_f32_e32 v90, v90
	v_exp_f32_e32 v91, v91
	v_exp_f32_e32 v92, v92
	v_exp_f32_e32 v93, v93
	v_exp_f32_e32 v94, v94
	v_exp_f32_e32 v95, v95
	v_add_f32_e32 v190, v190, v88
	v_add_f32_e32 v191, v191, v89
	v_add_f32_e32 v190, v190, v90
	v_add_f32_e32 v191, v191, v91
	v_add_f32_e32 v190, v190, v92
	v_add_f32_e32 v191, v191, v93
	v_add_f32_e32 v190, v190, v94
	v_add_f32_e32 v191, v191, v95
	v_cvt_pk_bf16_f32 v156, v88, v89
	v_cvt_pk_bf16_f32 v157, v90, v91
	v_cvt_pk_bf16_f32 v158, v92, v93
	v_cvt_pk_bf16_f32 v159, v94, v95
	v_add_f32_e32 v190, v190, v191
	v_add_f32_e32 v167, v167, v190
	s_add_i32 s42, s31, 1
	s_movk_i32 s47, 7
.Lattn_loop_f:
	s_waitcnt vmcnt(4)
	s_barrier
	s_waitcnt lgkmcnt(5)
	v_mfma_f32_32x32x16_bf16 v[48:63], v[216:219], v[144:147], v[48:63]
	ds_read_b128 v[216:219], v188 offset:8192
	s_add_i32 s2, s42, 3
	v_max3_f32 v254, v96, v97, v98
	s_and_b32 s2, s2, 31
	v_max3_f32 v255, v112, v113, v114
	s_mul_i32 s2, s2, 0x44000
	v_max3_f32 v254, v254, v99, v100
	s_add_i32 m0, s5, 0
	v_max3_f32 v255, v255, v115, v116
	s_waitcnt lgkmcnt(5)
	v_mfma_f32_32x32x16_bf16 v[32:47], v[220:223], v[144:147], v[32:47]
	ds_read_b128 v[220:223], v188 offset:12288
	v_lshl_add_u64 v[232:233], v[170:171], 0, s[2:3]
	v_max3_f32 v254, v254, v101, v102
	v_lshl_add_u64 v[234:235], v[232:233], 0, s[18:19]
	v_max3_f32 v255, v255, v117, v118
	global_load_lds_dwordx4 v[234:235], off
	v_max3_f32 v254, v254, v103, v104
	s_add_i32 m0, s5, 8192
	v_max3_f32 v255, v255, v119, v120
	s_waitcnt lgkmcnt(5)
	v_mfma_f32_32x32x16_bf16 v[16:31], v[224:227], v[144:147], v[16:31]
	ds_read_b128 v[224:227], v186 offset:0
	v_lshl_add_u64 v[232:233], v[232:233], 0, s[20:21]
	v_max3_f32 v254, v254, v105, v106
	global_load_lds_dwordx4 v[232:233], off
	v_max3_f32 v255, v255, v121, v122
	s_add_i32 s2, s42, 2
	v_max3_f32 v254, v254, v107, v108
	s_and_b32 s2, s2, 31
	v_max3_f32 v255, v255, v123, v124
	s_waitcnt lgkmcnt(5)
	v_mfma_f32_32x32x16_bf16 v[0:15], v[228:231], v[144:147], v[0:15]
	ds_read_b128 v[228:231], v186 offset:4096
	s_lshl_b32 s2, s2, 7
	v_max3_f32 v254, v254, v109, v110
	v_max3_f32 v255, v255, v125, v126
	v_max3_f32 v254, v254, v111, v127
	v_max_f32_e32 v254, v254, v255
	v_cmp_lt_f32_e32 vcc, 0x4138aa3b, v254
	s_add_i32 m0, s5, 114688
	v_lshl_add_u64 v[232:233], v[172:173], 0, s[2:3]
	s_waitcnt lgkmcnt(5)
	v_mfma_f32_32x32x16_bf16 v[48:63], v[208:211], v[148:151], v[48:63]
	ds_read_b128 v[208:211], v186 offset:8192
	global_load_lds_dwordx4 v[232:233], off
	s_add_i32 m0, s5, 122880
	v_lshl_add_u64 v[234:235], v[232:233], 0, s[22:23]
	global_load_lds_dwordx4 v[234:235], off
	s_cbranch_vccnz .Lattn_sp_L0
	v_exp_f32_e32 v96, v96
	v_exp_f32_e32 v97, v97
	v_exp_f32_e32 v98, v98
	v_exp_f32_e32 v99, v99
	s_waitcnt lgkmcnt(5)
	v_mfma_f32_32x32x16_bf16 v[32:47], v[212:215], v[148:151], v[32:47]
	ds_read_b128 v[212:215], v186 offset:12288
	v_exp_f32_e32 v100, v100
	v_exp_f32_e32 v101, v101
	v_exp_f32_e32 v102, v102
	v_exp_f32_e32 v103, v103
	s_waitcnt lgkmcnt(5)
	v_mfma_f32_32x32x16_bf16 v[16:31], v[216:219], v[148:151], v[16:31]
	ds_read_b128 v[216:219], v189 offset:0
	v_add_f32_e32 v190, v96, v97
	v_add_f32_e32 v191, v98, v99
	v_add_f32_e32 v190, v190, v100
	v_add_f32_e32 v191, v191, v101
	s_waitcnt lgkmcnt(5)
	v_mfma_f32_32x32x16_bf16 v[0:15], v[220:223], v[148:151], v[0:15]
	ds_read_b128 v[220:223], v189 offset:4096
	v_add_f32_e32 v190, v190, v102
	v_add_f32_e32 v191, v191, v103
	v_cvt_pk_bf16_f32 v144, v96, v97
	v_cvt_pk_bf16_f32 v145, v98, v99
	s_waitcnt lgkmcnt(5)
	v_mfma_f32_32x32x16_bf16 v[48:63], v[224:227], v[152:155], v[48:63]
	ds_read_b128 v[224:227], v189 offset:8192
	v_cvt_pk_bf16_f32 v146, v100, v101
	v_cvt_pk_bf16_f32 v147, v102, v103
	v_exp_f32_e32 v104, v104
	v_exp_f32_e32 v105, v105
	s_waitcnt lgkmcnt(5)
	v_mfma_f32_32x32x16_bf16 v[32:47], v[228:231], v[152:155], v[32:47]
	ds_read_b128 v[228:231], v189 offset:12288
	v_exp_f32_e32 v106, v106
	v_exp_f32_e32 v107, v107
	v_exp_f32_e32 v108, v108
	v_exp_f32_e32 v109, v109
	s_waitcnt lgkmcnt(5)
	v_mfma_f32_32x32x16_bf16 v[16:31], v[208:211], v[152:155], v[16:31]
	ds_read_b128 v[208:211], v182 offset:32768
	v_exp_f32_e32 v110, v110
	v_exp_f32_e32 v111, v111
	v_add_f32_e32 v190, v190, v104
	v_add_f32_e32 v191, v191, v105
	s_waitcnt lgkmcnt(5)
	v_mfma_f32_32x32x16_bf16 v[0:15], v[212:215], v[152:155], v[0:15]
	ds_read_b128 v[212:215], v182 offset:36864
	v_add_f32_e32 v190, v190, v106
	v_add_f32_e32 v191, v191, v107
	v_add_f32_e32 v190, v190, v108
	v_add_f32_e32 v191, v191, v109
	s_waitcnt lgkmcnt(5)
	v_mfma_f32_32x32x16_bf16 v[48:63], v[216:219], v[156:159], v[48:63]
	ds_read_b128 v[216:219], v183 offset:32768
	v_add_f32_e32 v190, v190, v110
	v_add_f32_e32 v191, v191, v111
	v_cvt_pk_bf16_f32 v148, v104, v105
	v_cvt_pk_bf16_f32 v149, v106, v107
	s_waitcnt lgkmcnt(5)
	v_mfma_f32_32x32x16_bf16 v[32:47], v[220:223], v[156:159], v[32:47]
	ds_read_b128 v[220:223], v183 offset:36864
	v_cvt_pk_bf16_f32 v150, v108, v109
	v_cvt_pk_bf16_f32 v151, v110, v111
	v_exp_f32_e32 v112, v112
	v_exp_f32_e32 v113, v113
	s_waitcnt lgkmcnt(5)
	v_mfma_f32_32x32x16_bf16 v[16:31], v[224:227], v[156:159], v[16:31]
	ds_read_b128 v[224:227], v184 offset:32768
	v_exp_f32_e32 v114, v114
	v_exp_f32_e32 v115, v115
	v_exp_f32_e32 v116, v116
	v_exp_f32_e32 v117, v117
	s_waitcnt lgkmcnt(5)
	v_mfma_f32_32x32x16_bf16 v[0:15], v[228:231], v[156:159], v[0:15]
	ds_read_b128 v[228:231], v184 offset:36864
	v_exp_f32_e32 v118, v118
	v_exp_f32_e32 v119, v119
	v_add_f32_e32 v190, v190, v112
	v_add_f32_e32 v191, v191, v113
	s_waitcnt lgkmcnt(5)
	v_mfma_f32_32x32x16_bf16 v[64:79], v[208:211], v[128:131], 0
	ds_read_b128 v[208:211], v185 offset:32768
	v_add_f32_e32 v190, v190, v114
	v_add_f32_e32 v191, v191, v115
	v_add_f32_e32 v190, v190, v116
	v_add_f32_e32 v191, v191, v117
	s_waitcnt lgkmcnt(5)
	v_mfma_f32_32x32x16_bf16 v[80:95], v[212:215], v[128:131], 0
	ds_read_b128 v[212:215], v185 offset:36864
	v_add_f32_e32 v190, v190, v118
	v_add_f32_e32 v191, v191, v119
	v_cvt_pk_bf16_f32 v152, v112, v113
	v_cvt_pk_bf16_f32 v153, v114, v115
	s_waitcnt lgkmcnt(5)
	v_mfma_f32_32x32x16_bf16 v[64:79], v[216:219], v[132:135], v[64:79]
	ds_read_b128 v[216:219], v187 offset:16384
	v_cvt_pk_bf16_f32 v154, v116, v117
	v_cvt_pk_bf16_f32 v155, v118, v119
	v_exp_f32_e32 v120, v120
	v_exp_f32_e32 v121, v121
	s_waitcnt lgkmcnt(5)
	v_mfma_f32_32x32x16_bf16 v[80:95], v[220:223], v[132:135], v[80:95]
	ds_read_b128 v[220:223], v187 offset:20480
	v_exp_f32_e32 v122, v122
	v_exp_f32_e32 v123, v123
	v_exp_f32_e32 v124, v124
	v_exp_f32_e32 v125, v125
	s_waitcnt lgkmcnt(5)
	v_mfma_f32_32x32x16_bf16 v[64:79], v[224:227], v[136:139], v[64:79]
	ds_read_b128 v[224:227], v187 offset:24576
	v_exp_f32_e32 v126, v126
	v_exp_f32_e32 v127, v127
	v_add_f32_e32 v190, v190, v120
	v_add_f32_e32 v191, v191, v121
	s_waitcnt lgkmcnt(5)
	v_mfma_f32_32x32x16_bf16 v[80:95], v[228:231], v[136:139], v[80:95]
	ds_read_b128 v[228:231], v187 offset:28672
	v_add_f32_e32 v190, v190, v122
	v_add_f32_e32 v191, v191, v123
	v_add_f32_e32 v190, v190, v124
	v_add_f32_e32 v191, v191, v125
	s_waitcnt lgkmcnt(5)
	v_mfma_f32_32x32x16_bf16 v[64:79], v[208:211], v[140:143], v[64:79]
	ds_read_b128 v[208:211], v188 offset:16384
	v_add_f32_e32 v190, v190, v126
	v_add_f32_e32 v191, v191, v127
	v_cvt_pk_bf16_f32 v156, v120, v121
	v_cvt_pk_bf16_f32 v157, v122, v123
	s_waitcnt lgkmcnt(5)
	v_mfma_f32_32x32x16_bf16 v[80:95], v[212:215], v[140:143], v[80:95]
	ds_read_b128 v[212:215], v188 offset:20480
	v_cvt_pk_bf16_f32 v158, v124, v125
	v_cvt_pk_bf16_f32 v159, v126, v127
	v_add_f32_e32 v190, v190, v191
	v_add_f32_e32 v167, v167, v190
	s_waitcnt vmcnt(4)
	s_barrier
	s_waitcnt lgkmcnt(5)
	v_mfma_f32_32x32x16_bf16 v[48:63], v[216:219], v[144:147], v[48:63]
	ds_read_b128 v[216:219], v188 offset:24576
	s_add_i32 s2, s42, 4
	v_max3_f32 v254, v64, v65, v66
	s_and_b32 s2, s2, 31
	v_max3_f32 v255, v80, v81, v82
	s_mul_i32 s2, s2, 0x44000
	v_max3_f32 v254, v254, v67, v68
	s_add_i32 m0, s5, 16384
	v_max3_f32 v255, v255, v83, v84
	s_waitcnt lgkmcnt(5)
	v_mfma_f32_32x32x16_bf16 v[32:47], v[220:223], v[144:147], v[32:47]
	ds_read_b128 v[220:223], v188 offset:28672
	v_lshl_add_u64 v[232:233], v[170:171], 0, s[2:3]
	v_max3_f32 v254, v254, v69, v70
	v_lshl_add_u64 v[234:235], v[232:233], 0, s[18:19]
	v_max3_f32 v255, v255, v85, v86
	global_load_lds_dwordx4 v[234:235], off
	v_max3_f32 v254, v254, v71, v72
	s_add_i32 m0, s5, 24576
	v_max3_f32 v255, v255, v87, v88
	s_waitcnt lgkmcnt(5)
	v_mfma_f32_32x32x16_bf16 v[16:31], v[224:227], v[144:147], v[16:31]
	ds_read_b128 v[224:227], v186 offset:16384
	v_lshl_add_u64 v[232:233], v[232:233], 0, s[20:21]
	v_max3_f32 v254, v254, v73, v74
	global_load_lds_dwordx4 v[232:233], off
	v_max3_f32 v255, v255, v89, v90
	s_add_i32 s2, s42, 3
	v_max3_f32 v254, v254, v75, v76
	s_and_b32 s2, s2, 31
	v_max3_f32 v255, v255, v91, v92
	s_waitcnt lgkmcnt(5)
	v_mfma_f32_32x32x16_bf16 v[0:15], v[228:231], v[144:147], v[0:15]
	ds_read_b128 v[228:231], v186 offset:20480
	s_lshl_b32 s2, s2, 7
	v_max3_f32 v254, v254, v77, v78
	v_max3_f32 v255, v255, v93, v94
	v_max3_f32 v254, v254, v79, v95
	v_max_f32_e32 v254, v254, v255
	v_cmp_lt_f32_e32 vcc, 0x4138aa3b, v254
	s_add_i32 m0, s5, 65536
	v_lshl_add_u64 v[232:233], v[172:173], 0, s[2:3]
	s_waitcnt lgkmcnt(5)
	v_mfma_f32_32x32x16_bf16 v[48:63], v[208:211], v[148:151], v[48:63]
	ds_read_b128 v[208:211], v186 offset:24576
	global_load_lds_dwordx4 v[232:233], off
	s_add_i32 m0, s5, 73728
	v_lshl_add_u64 v[234:235], v[232:233], 0, s[22:23]
	global_load_lds_dwordx4 v[234:235], off
	s_cbranch_vccnz .Lattn_sp_L1
	v_exp_f32_e32 v64, v64
	v_exp_f32_e32 v65, v65
	v_exp_f32_e32 v66, v66
	v_exp_f32_e32 v67, v67
	s_waitcnt lgkmcnt(5)
	v_mfma_f32_32x32x16_bf16 v[32:47], v[212:215], v[148:151], v[32:47]
	ds_read_b128 v[212:215], v186 offset:28672
	v_exp_f32_e32 v68, v68
	v_exp_f32_e32 v69, v69
	v_exp_f32_e32 v70, v70
	v_exp_f32_e32 v71, v71
	s_waitcnt lgkmcnt(5)
	v_mfma_f32_32x32x16_bf16 v[16:31], v[216:219], v[148:151], v[16:31]
	ds_read_b128 v[216:219], v189 offset:16384
	v_add_f32_e32 v190, v64, v65
	v_add_f32_e32 v191, v66, v67
	v_add_f32_e32 v190, v190, v68
	v_add_f32_e32 v191, v191, v69
	s_waitcnt lgkmcnt(5)
	v_mfma_f32_32x32x16_bf16 v[0:15], v[220:223], v[148:151], v[0:15]
	ds_read_b128 v[220:223], v189 offset:20480
	v_add_f32_e32 v190, v190, v70
	v_add_f32_e32 v191, v191, v71
	v_cvt_pk_bf16_f32 v144, v64, v65
	v_cvt_pk_bf16_f32 v145, v66, v67
	s_waitcnt lgkmcnt(5)
	v_mfma_f32_32x32x16_bf16 v[48:63], v[224:227], v[152:155], v[48:63]
	ds_read_b128 v[224:227], v189 offset:24576
	v_cvt_pk_bf16_f32 v146, v68, v69
	v_cvt_pk_bf16_f32 v147, v70, v71
	v_exp_f32_e32 v72, v72
	v_exp_f32_e32 v73, v73
	s_waitcnt lgkmcnt(5)
	v_mfma_f32_32x32x16_bf16 v[32:47], v[228:231], v[152:155], v[32:47]
	ds_read_b128 v[228:231], v189 offset:28672
	v_exp_f32_e32 v74, v74
	v_exp_f32_e32 v75, v75
	v_exp_f32_e32 v76, v76
	v_exp_f32_e32 v77, v77
	s_waitcnt lgkmcnt(5)
	v_mfma_f32_32x32x16_bf16 v[16:31], v[208:211], v[152:155], v[16:31]
	ds_read_b128 v[208:211], v182 offset:49152
	v_exp_f32_e32 v78, v78
	v_exp_f32_e32 v79, v79
	v_add_f32_e32 v190, v190, v72
	v_add_f32_e32 v191, v191, v73
	s_waitcnt lgkmcnt(5)
	v_mfma_f32_32x32x16_bf16 v[0:15], v[212:215], v[152:155], v[0:15]
	ds_read_b128 v[212:215], v182 offset:53248
	v_add_f32_e32 v190, v190, v74
	v_add_f32_e32 v191, v191, v75
	v_add_f32_e32 v190, v190, v76
	v_add_f32_e32 v191, v191, v77
	s_waitcnt lgkmcnt(5)
	v_mfma_f32_32x32x16_bf16 v[48:63], v[216:219], v[156:159], v[48:63]
	ds_read_b128 v[216:219], v183 offset:49152
	v_add_f32_e32 v190, v190, v78
	v_add_f32_e32 v191, v191, v79
	v_cvt_pk_bf16_f32 v148, v72, v73
	v_cvt_pk_bf16_f32 v149, v74, v75
	s_waitcnt lgkmcnt(5)
	v_mfma_f32_32x32x16_bf16 v[32:47], v[220:223], v[156:159], v[32:47]
	ds_read_b128 v[220:223], v183 offset:53248
	v_cvt_pk_bf16_f32 v150, v76, v77
	v_cvt_pk_bf16_f32 v151, v78, v79
	v_exp_f32_e32 v80, v80
	v_exp_f32_e32 v81, v81
	s_waitcnt lgkmcnt(5)
	v_mfma_f32_32x32x16_bf16 v[16:31], v[224:227], v[156:159], v[16:31]
	ds_read_b128 v[224:227], v184 offset:49152
	v_exp_f32_e32 v82, v82
	v_exp_f32_e32 v83, v83
	v_exp_f32_e32 v84, v84
	v_exp_f32_e32 v85, v85
	s_waitcnt lgkmcnt(5)
	v_mfma_f32_32x32x16_bf16 v[0:15], v[228:231], v[156:159], v[0:15]
	ds_read_b128 v[228:231], v184 offset:53248
	v_exp_f32_e32 v86, v86
	v_exp_f32_e32 v87, v87
	v_add_f32_e32 v190, v190, v80
	v_add_f32_e32 v191, v191, v81
	s_waitcnt lgkmcnt(5)
	v_mfma_f32_32x32x16_bf16 v[96:111], v[208:211], v[128:131], 0
	ds_read_b128 v[208:211], v185 offset:49152
	v_add_f32_e32 v190, v190, v82
	v_add_f32_e32 v191, v191, v83
	v_add_f32_e32 v190, v190, v84
	v_add_f32_e32 v191, v191, v85
	s_waitcnt lgkmcnt(5)
	v_mfma_f32_32x32x16_bf16 v[112:127], v[212:215], v[128:131], 0
	ds_read_b128 v[212:215], v185 offset:53248
	v_add_f32_e32 v190, v190, v86
	v_add_f32_e32 v191, v191, v87
	v_cvt_pk_bf16_f32 v152, v80, v81
	v_cvt_pk_bf16_f32 v153, v82, v83
	s_waitcnt lgkmcnt(5)
	v_mfma_f32_32x32x16_bf16 v[96:111], v[216:219], v[132:135], v[96:111]
	ds_read_b128 v[216:219], v187 offset:32768
	v_cvt_pk_bf16_f32 v154, v84, v85
	v_cvt_pk_bf16_f32 v155, v86, v87
	v_exp_f32_e32 v88, v88
	v_exp_f32_e32 v89, v89
	s_waitcnt lgkmcnt(5)
	v_mfma_f32_32x32x16_bf16 v[112:127], v[220:223], v[132:135], v[112:127]
	ds_read_b128 v[220:223], v187 offset:36864
	v_exp_f32_e32 v90, v90
	v_exp_f32_e32 v91, v91
	v_exp_f32_e32 v92, v92
	v_exp_f32_e32 v93, v93
	s_waitcnt lgkmcnt(5)
	v_mfma_f32_32x32x16_bf16 v[96:111], v[224:227], v[136:139], v[96:111]
	ds_read_b128 v[224:227], v187 offset:40960
	v_exp_f32_e32 v94, v94
	v_exp_f32_e32 v95, v95
	v_add_f32_e32 v190, v190, v88
	v_add_f32_e32 v191, v191, v89
	s_waitcnt lgkmcnt(5)
	v_mfma_f32_32x32x16_bf16 v[112:127], v[228:231], v[136:139], v[112:127]
	ds_read_b128 v[228:231], v187 offset:45056
	v_add_f32_e32 v190, v190, v90
	v_add_f32_e32 v191, v191, v91
	v_add_f32_e32 v190, v190, v92
	v_add_f32_e32 v191, v191, v93
	s_waitcnt lgkmcnt(5)
	v_mfma_f32_32x32x16_bf16 v[96:111], v[208:211], v[140:143], v[96:111]
	ds_read_b128 v[208:211], v188 offset:32768
	v_add_f32_e32 v190, v190, v94
	v_add_f32_e32 v191, v191, v95
	v_cvt_pk_bf16_f32 v156, v88, v89
	v_cvt_pk_bf16_f32 v157, v90, v91
	s_waitcnt lgkmcnt(5)
	v_mfma_f32_32x32x16_bf16 v[112:127], v[212:215], v[140:143], v[112:127]
	ds_read_b128 v[212:215], v188 offset:36864
	v_cvt_pk_bf16_f32 v158, v92, v93
	v_cvt_pk_bf16_f32 v159, v94, v95
	v_add_f32_e32 v190, v190, v191
	v_add_f32_e32 v167, v167, v190
	s_waitcnt vmcnt(4)
	s_barrier
	s_waitcnt lgkmcnt(5)
	v_mfma_f32_32x32x16_bf16 v[48:63], v[216:219], v[144:147], v[48:63]
	ds_read_b128 v[216:219], v188 offset:40960
	s_add_i32 s2, s42, 5
	v_max3_f32 v254, v96, v97, v98
	s_and_b32 s2, s2, 31
	v_max3_f32 v255, v112, v113, v114
	s_mul_i32 s2, s2, 0x44000
	v_max3_f32 v254, v254, v99, v100
	s_add_i32 m0, s5, 32768
	v_max3_f32 v255, v255, v115, v116
	s_waitcnt lgkmcnt(5)
	v_mfma_f32_32x32x16_bf16 v[32:47], v[220:223], v[144:147], v[32:47]
	ds_read_b128 v[220:223], v188 offset:45056
	v_lshl_add_u64 v[232:233], v[170:171], 0, s[2:3]
	v_max3_f32 v254, v254, v101, v102
	v_lshl_add_u64 v[234:235], v[232:233], 0, s[18:19]
	v_max3_f32 v255, v255, v117, v118
	global_load_lds_dwordx4 v[234:235], off
	v_max3_f32 v254, v254, v103, v104
	s_add_i32 m0, s5, 40960
	v_max3_f32 v255, v255, v119, v120
	s_waitcnt lgkmcnt(5)
	v_mfma_f32_32x32x16_bf16 v[16:31], v[224:227], v[144:147], v[16:31]
	ds_read_b128 v[224:227], v186 offset:32768
	v_lshl_add_u64 v[232:233], v[232:233], 0, s[20:21]
	v_max3_f32 v254, v254, v105, v106
	global_load_lds_dwordx4 v[232:233], off
	v_max3_f32 v255, v255, v121, v122
	s_add_i32 s2, s42, 4
	v_max3_f32 v254, v254, v107, v108
	s_and_b32 s2, s2, 31
	v_max3_f32 v255, v255, v123, v124
	s_waitcnt lgkmcnt(5)
	v_mfma_f32_32x32x16_bf16 v[0:15], v[228:231], v[144:147], v[0:15]
	ds_read_b128 v[228:231], v186 offset:36864
	s_lshl_b32 s2, s2, 7
	v_max3_f32 v254, v254, v109, v110
	v_max3_f32 v255, v255, v125, v126
	v_max3_f32 v254, v254, v111, v127
	v_max_f32_e32 v254, v254, v255
	v_cmp_lt_f32_e32 vcc, 0x4138aa3b, v254
	s_add_i32 m0, s5, 81920
	v_lshl_add_u64 v[232:233], v[172:173], 0, s[2:3]
	s_waitcnt lgkmcnt(5)
	v_mfma_f32_32x32x16_bf16 v[48:63], v[208:211], v[148:151], v[48:63]
	ds_read_b128 v[208:211], v186 offset:40960
	global_load_lds_dwordx4 v[232:233], off
	s_add_i32 m0, s5, 90112
	v_lshl_add_u64 v[234:235], v[232:233], 0, s[22:23]
	global_load_lds_dwordx4 v[234:235], off
	s_cbranch_vccnz .Lattn_sp_L2
	v_exp_f32_e32 v96, v96
	v_exp_f32_e32 v97, v97
	v_exp_f32_e32 v98, v98
	v_exp_f32_e32 v99, v99
	s_waitcnt lgkmcnt(5)
	v_mfma_f32_32x32x16_bf16 v[32:47], v[212:215], v[148:151], v[32:47]
	ds_read_b128 v[212:215], v186 offset:45056
	v_exp_f32_e32 v100, v100
	v_exp_f32_e32 v101, v101
	v_exp_f32_e32 v102, v102
	v_exp_f32_e32 v103, v103
	s_waitcnt lgkmcnt(5)
	v_mfma_f32_32x32x16_bf16 v[16:31], v[216:219], v[148:151], v[16:31]
	ds_read_b128 v[216:219], v189 offset:32768
	v_add_f32_e32 v190, v96, v97
	v_add_f32_e32 v191, v98, v99
	v_add_f32_e32 v190, v190, v100
	v_add_f32_e32 v191, v191, v101
	s_waitcnt lgkmcnt(5)
	v_mfma_f32_32x32x16_bf16 v[0:15], v[220:223], v[148:151], v[0:15]
	ds_read_b128 v[220:223], v189 offset:36864
	v_add_f32_e32 v190, v190, v102
	v_add_f32_e32 v191, v191, v103
	v_cvt_pk_bf16_f32 v144, v96, v97
	v_cvt_pk_bf16_f32 v145, v98, v99
	s_waitcnt lgkmcnt(5)
	v_mfma_f32_32x32x16_bf16 v[48:63], v[224:227], v[152:155], v[48:63]
	ds_read_b128 v[224:227], v189 offset:40960
	v_cvt_pk_bf16_f32 v146, v100, v101
	v_cvt_pk_bf16_f32 v147, v102, v103
	v_exp_f32_e32 v104, v104
	v_exp_f32_e32 v105, v105
	s_waitcnt lgkmcnt(5)
	v_mfma_f32_32x32x16_bf16 v[32:47], v[228:231], v[152:155], v[32:47]
	ds_read_b128 v[228:231], v189 offset:45056
	v_exp_f32_e32 v106, v106
	v_exp_f32_e32 v107, v107
	v_exp_f32_e32 v108, v108
	v_exp_f32_e32 v109, v109
	s_waitcnt lgkmcnt(5)
	v_mfma_f32_32x32x16_bf16 v[16:31], v[208:211], v[152:155], v[16:31]
	ds_read_b128 v[208:211], v182 offset:0
	v_exp_f32_e32 v110, v110
	v_exp_f32_e32 v111, v111
	v_add_f32_e32 v190, v190, v104
	v_add_f32_e32 v191, v191, v105
	s_waitcnt lgkmcnt(5)
	v_mfma_f32_32x32x16_bf16 v[0:15], v[212:215], v[152:155], v[0:15]
	ds_read_b128 v[212:215], v182 offset:4096
	v_add_f32_e32 v190, v190, v106
	v_add_f32_e32 v191, v191, v107
	v_add_f32_e32 v190, v190, v108
	v_add_f32_e32 v191, v191, v109
	s_waitcnt lgkmcnt(5)
	v_mfma_f32_32x32x16_bf16 v[48:63], v[216:219], v[156:159], v[48:63]
	ds_read_b128 v[216:219], v183 offset:0
	v_add_f32_e32 v190, v190, v110
	v_add_f32_e32 v191, v191, v111
	v_cvt_pk_bf16_f32 v148, v104, v105
	v_cvt_pk_bf16_f32 v149, v106, v107
	s_waitcnt lgkmcnt(5)
	v_mfma_f32_32x32x16_bf16 v[32:47], v[220:223], v[156:159], v[32:47]
	ds_read_b128 v[220:223], v183 offset:4096
	v_cvt_pk_bf16_f32 v150, v108, v109
	v_cvt_pk_bf16_f32 v151, v110, v111
	v_exp_f32_e32 v112, v112
	v_exp_f32_e32 v113, v113
	s_waitcnt lgkmcnt(5)
	v_mfma_f32_32x32x16_bf16 v[16:31], v[224:227], v[156:159], v[16:31]
	ds_read_b128 v[224:227], v184 offset:0
	v_exp_f32_e32 v114, v114
	v_exp_f32_e32 v115, v115
	v_exp_f32_e32 v116, v116
	v_exp_f32_e32 v117, v117
	s_waitcnt lgkmcnt(5)
	v_mfma_f32_32x32x16_bf16 v[0:15], v[228:231], v[156:159], v[0:15]
	ds_read_b128 v[228:231], v184 offset:4096
	v_exp_f32_e32 v118, v118
	v_exp_f32_e32 v119, v119
	v_add_f32_e32 v190, v190, v112
	v_add_f32_e32 v191, v191, v113
	s_waitcnt lgkmcnt(5)
	v_mfma_f32_32x32x16_bf16 v[64:79], v[208:211], v[128:131], 0
	ds_read_b128 v[208:211], v185 offset:0
	v_add_f32_e32 v190, v190, v114
	v_add_f32_e32 v191, v191, v115
	v_add_f32_e32 v190, v190, v116
	v_add_f32_e32 v191, v191, v117
	s_waitcnt lgkmcnt(5)
	v_mfma_f32_32x32x16_bf16 v[80:95], v[212:215], v[128:131], 0
	ds_read_b128 v[212:215], v185 offset:4096
	v_add_f32_e32 v190, v190, v118
	v_add_f32_e32 v191, v191, v119
	v_cvt_pk_bf16_f32 v152, v112, v113
	v_cvt_pk_bf16_f32 v153, v114, v115
	s_waitcnt lgkmcnt(5)
	v_mfma_f32_32x32x16_bf16 v[64:79], v[216:219], v[132:135], v[64:79]
	ds_read_b128 v[216:219], v187 offset:49152
	v_cvt_pk_bf16_f32 v154, v116, v117
	v_cvt_pk_bf16_f32 v155, v118, v119
	v_exp_f32_e32 v120, v120
	v_exp_f32_e32 v121, v121
	s_waitcnt lgkmcnt(5)
	v_mfma_f32_32x32x16_bf16 v[80:95], v[220:223], v[132:135], v[80:95]
	ds_read_b128 v[220:223], v187 offset:53248
	v_exp_f32_e32 v122, v122
	v_exp_f32_e32 v123, v123
	v_exp_f32_e32 v124, v124
	v_exp_f32_e32 v125, v125
	s_waitcnt lgkmcnt(5)
	v_mfma_f32_32x32x16_bf16 v[64:79], v[224:227], v[136:139], v[64:79]
	ds_read_b128 v[224:227], v187 offset:57344
	v_exp_f32_e32 v126, v126
	v_exp_f32_e32 v127, v127
	v_add_f32_e32 v190, v190, v120
	v_add_f32_e32 v191, v191, v121
	s_waitcnt lgkmcnt(5)
	v_mfma_f32_32x32x16_bf16 v[80:95], v[228:231], v[136:139], v[80:95]
	ds_read_b128 v[228:231], v187 offset:61440
	v_add_f32_e32 v190, v190, v122
	v_add_f32_e32 v191, v191, v123
	v_add_f32_e32 v190, v190, v124
	v_add_f32_e32 v191, v191, v125
	s_waitcnt lgkmcnt(5)
	v_mfma_f32_32x32x16_bf16 v[64:79], v[208:211], v[140:143], v[64:79]
	ds_read_b128 v[208:211], v188 offset:49152
	v_add_f32_e32 v190, v190, v126
	v_add_f32_e32 v191, v191, v127
	v_cvt_pk_bf16_f32 v156, v120, v121
	v_cvt_pk_bf16_f32 v157, v122, v123
	s_waitcnt lgkmcnt(5)
	v_mfma_f32_32x32x16_bf16 v[80:95], v[212:215], v[140:143], v[80:95]
	ds_read_b128 v[212:215], v188 offset:53248
	v_cvt_pk_bf16_f32 v158, v124, v125
	v_cvt_pk_bf16_f32 v159, v126, v127
	v_add_f32_e32 v190, v190, v191
	v_add_f32_e32 v167, v167, v190
	s_waitcnt vmcnt(4)
	s_barrier
	s_waitcnt lgkmcnt(5)
	v_mfma_f32_32x32x16_bf16 v[48:63], v[216:219], v[144:147], v[48:63]
	ds_read_b128 v[216:219], v188 offset:57344
	s_add_i32 s2, s42, 6
	v_max3_f32 v254, v64, v65, v66
	s_and_b32 s2, s2, 31
	v_max3_f32 v255, v80, v81, v82
	s_mul_i32 s2, s2, 0x44000
	v_max3_f32 v254, v254, v67, v68
	s_add_i32 m0, s5, 49152
	v_max3_f32 v255, v255, v83, v84
	s_waitcnt lgkmcnt(5)
	v_mfma_f32_32x32x16_bf16 v[32:47], v[220:223], v[144:147], v[32:47]
	ds_read_b128 v[220:223], v188 offset:61440
	v_lshl_add_u64 v[232:233], v[170:171], 0, s[2:3]
	v_max3_f32 v254, v254, v69, v70
	v_lshl_add_u64 v[234:235], v[232:233], 0, s[18:19]
	v_max3_f32 v255, v255, v85, v86
	global_load_lds_dwordx4 v[234:235], off
	v_max3_f32 v254, v254, v71, v72
	s_add_i32 m0, s5, 57344
	v_max3_f32 v255, v255, v87, v88
	s_waitcnt lgkmcnt(5)
	v_mfma_f32_32x32x16_bf16 v[16:31], v[224:227], v[144:147], v[16:31]
	ds_read_b128 v[224:227], v186 offset:49152
	v_lshl_add_u64 v[232:233], v[232:233], 0, s[20:21]
	v_max3_f32 v254, v254, v73, v74
	global_load_lds_dwordx4 v[232:233], off
	v_max3_f32 v255, v255, v89, v90
	s_add_i32 s2, s42, 5
	v_max3_f32 v254, v254, v75, v76
	s_and_b32 s2, s2, 31
	v_max3_f32 v255, v255, v91, v92
	s_waitcnt lgkmcnt(5)
	v_mfma_f32_32x32x16_bf16 v[0:15], v[228:231], v[144:147], v[0:15]
	ds_read_b128 v[228:231], v186 offset:53248
	s_lshl_b32 s2, s2, 7
	v_max3_f32 v254, v254, v77, v78
	v_max3_f32 v255, v255, v93, v94
	v_max3_f32 v254, v254, v79, v95
	v_max_f32_e32 v254, v254, v255
	v_cmp_lt_f32_e32 vcc, 0x4138aa3b, v254
	s_add_i32 m0, s5, 98304
	v_lshl_add_u64 v[232:233], v[172:173], 0, s[2:3]
	s_waitcnt lgkmcnt(5)
	v_mfma_f32_32x32x16_bf16 v[48:63], v[208:211], v[148:151], v[48:63]
	ds_read_b128 v[208:211], v186 offset:57344
	global_load_lds_dwordx4 v[232:233], off
	s_add_i32 m0, s5, 106496
	v_lshl_add_u64 v[234:235], v[232:233], 0, s[22:23]
	global_load_lds_dwordx4 v[234:235], off
	s_cbranch_vccnz .Lattn_sp_L3
	v_exp_f32_e32 v64, v64
	v_exp_f32_e32 v65, v65
	v_exp_f32_e32 v66, v66
	v_exp_f32_e32 v67, v67
	s_waitcnt lgkmcnt(5)
	v_mfma_f32_32x32x16_bf16 v[32:47], v[212:215], v[148:151], v[32:47]
	ds_read_b128 v[212:215], v186 offset:61440
	v_exp_f32_e32 v68, v68
	v_exp_f32_e32 v69, v69
	v_exp_f32_e32 v70, v70
	v_exp_f32_e32 v71, v71
	s_waitcnt lgkmcnt(5)
	v_mfma_f32_32x32x16_bf16 v[16:31], v[216:219], v[148:151], v[16:31]
	ds_read_b128 v[216:219], v189 offset:49152
	v_add_f32_e32 v190, v64, v65
	v_add_f32_e32 v191, v66, v67
	v_add_f32_e32 v190, v190, v68
	v_add_f32_e32 v191, v191, v69
	s_waitcnt lgkmcnt(5)
	v_mfma_f32_32x32x16_bf16 v[0:15], v[220:223], v[148:151], v[0:15]
	ds_read_b128 v[220:223], v189 offset:53248
	v_add_f32_e32 v190, v190, v70
	v_add_f32_e32 v191, v191, v71
	v_cvt_pk_bf16_f32 v144, v64, v65
	v_cvt_pk_bf16_f32 v145, v66, v67
	s_waitcnt lgkmcnt(5)
	v_mfma_f32_32x32x16_bf16 v[48:63], v[224:227], v[152:155], v[48:63]
	ds_read_b128 v[224:227], v189 offset:57344
	v_cvt_pk_bf16_f32 v146, v68, v69
	v_cvt_pk_bf16_f32 v147, v70, v71
	v_exp_f32_e32 v72, v72
	v_exp_f32_e32 v73, v73
	s_waitcnt lgkmcnt(5)
	v_mfma_f32_32x32x16_bf16 v[32:47], v[228:231], v[152:155], v[32:47]
	ds_read_b128 v[228:231], v189 offset:61440
	v_exp_f32_e32 v74, v74
	v_exp_f32_e32 v75, v75
	v_exp_f32_e32 v76, v76
	v_exp_f32_e32 v77, v77
	s_waitcnt lgkmcnt(5)
	v_mfma_f32_32x32x16_bf16 v[16:31], v[208:211], v[152:155], v[16:31]
	ds_read_b128 v[208:211], v182 offset:16384
	v_exp_f32_e32 v78, v78
	v_exp_f32_e32 v79, v79
	v_add_f32_e32 v190, v190, v72
	v_add_f32_e32 v191, v191, v73
	s_waitcnt lgkmcnt(5)
	v_mfma_f32_32x32x16_bf16 v[0:15], v[212:215], v[152:155], v[0:15]
	ds_read_b128 v[212:215], v182 offset:20480
	v_add_f32_e32 v190, v190, v74
	v_add_f32_e32 v191, v191, v75
	v_add_f32_e32 v190, v190, v76
	v_add_f32_e32 v191, v191, v77
	s_waitcnt lgkmcnt(5)
	v_mfma_f32_32x32x16_bf16 v[48:63], v[216:219], v[156:159], v[48:63]
	ds_read_b128 v[216:219], v183 offset:16384
	v_add_f32_e32 v190, v190, v78
	v_add_f32_e32 v191, v191, v79
	v_cvt_pk_bf16_f32 v148, v72, v73
	v_cvt_pk_bf16_f32 v149, v74, v75
	s_waitcnt lgkmcnt(5)
	v_mfma_f32_32x32x16_bf16 v[32:47], v[220:223], v[156:159], v[32:47]
	ds_read_b128 v[220:223], v183 offset:20480
	v_cvt_pk_bf16_f32 v150, v76, v77
	v_cvt_pk_bf16_f32 v151, v78, v79
	v_exp_f32_e32 v80, v80
	v_exp_f32_e32 v81, v81
	s_waitcnt lgkmcnt(5)
	v_mfma_f32_32x32x16_bf16 v[16:31], v[224:227], v[156:159], v[16:31]
	ds_read_b128 v[224:227], v184 offset:16384
	v_exp_f32_e32 v82, v82
	v_exp_f32_e32 v83, v83
	v_exp_f32_e32 v84, v84
	v_exp_f32_e32 v85, v85
	s_waitcnt lgkmcnt(5)
	v_mfma_f32_32x32x16_bf16 v[0:15], v[228:231], v[156:159], v[0:15]
	ds_read_b128 v[228:231], v184 offset:20480
	v_exp_f32_e32 v86, v86
	v_exp_f32_e32 v87, v87
	v_add_f32_e32 v190, v190, v80
	v_add_f32_e32 v191, v191, v81
	s_waitcnt lgkmcnt(5)
	v_mfma_f32_32x32x16_bf16 v[96:111], v[208:211], v[128:131], 0
	ds_read_b128 v[208:211], v185 offset:16384
	v_add_f32_e32 v190, v190, v82
	v_add_f32_e32 v191, v191, v83
	v_add_f32_e32 v190, v190, v84
	v_add_f32_e32 v191, v191, v85
	s_waitcnt lgkmcnt(5)
	v_mfma_f32_32x32x16_bf16 v[112:127], v[212:215], v[128:131], 0
	ds_read_b128 v[212:215], v185 offset:20480
	v_add_f32_e32 v190, v190, v86
	v_add_f32_e32 v191, v191, v87
	v_cvt_pk_bf16_f32 v152, v80, v81
	v_cvt_pk_bf16_f32 v153, v82, v83
	s_waitcnt lgkmcnt(5)
	v_mfma_f32_32x32x16_bf16 v[96:111], v[216:219], v[132:135], v[96:111]
	ds_read_b128 v[216:219], v187 offset:0
	v_cvt_pk_bf16_f32 v154, v84, v85
	v_cvt_pk_bf16_f32 v155, v86, v87
	v_exp_f32_e32 v88, v88
	v_exp_f32_e32 v89, v89
	s_waitcnt lgkmcnt(5)
	v_mfma_f32_32x32x16_bf16 v[112:127], v[220:223], v[132:135], v[112:127]
	ds_read_b128 v[220:223], v187 offset:4096
	v_exp_f32_e32 v90, v90
	v_exp_f32_e32 v91, v91
	v_exp_f32_e32 v92, v92
	v_exp_f32_e32 v93, v93
	s_waitcnt lgkmcnt(5)
	v_mfma_f32_32x32x16_bf16 v[96:111], v[224:227], v[136:139], v[96:111]
	ds_read_b128 v[224:227], v187 offset:8192
	v_exp_f32_e32 v94, v94
	v_exp_f32_e32 v95, v95
	v_add_f32_e32 v190, v190, v88
	v_add_f32_e32 v191, v191, v89
	s_waitcnt lgkmcnt(5)
	v_mfma_f32_32x32x16_bf16 v[112:127], v[228:231], v[136:139], v[112:127]
	ds_read_b128 v[228:231], v187 offset:12288
	v_add_f32_e32 v190, v190, v90
	v_add_f32_e32 v191, v191, v91
	v_add_f32_e32 v190, v190, v92
	v_add_f32_e32 v191, v191, v93
	s_waitcnt lgkmcnt(5)
	v_mfma_f32_32x32x16_bf16 v[96:111], v[208:211], v[140:143], v[96:111]
	ds_read_b128 v[208:211], v188 offset:0
	v_add_f32_e32 v190, v190, v94
	v_add_f32_e32 v191, v191, v95
	v_cvt_pk_bf16_f32 v156, v88, v89
	v_cvt_pk_bf16_f32 v157, v90, v91
	s_waitcnt lgkmcnt(5)
	v_mfma_f32_32x32x16_bf16 v[112:127], v[212:215], v[140:143], v[112:127]
	ds_read_b128 v[212:215], v188 offset:4096
	v_cvt_pk_bf16_f32 v158, v92, v93
	v_cvt_pk_bf16_f32 v159, v94, v95
	v_add_f32_e32 v190, v190, v191
	v_add_f32_e32 v167, v167, v190
	s_add_i32 s42, s42, 4
	s_add_i32 s47, s47, -1
	s_cmp_lg_u32 s47, 0
	s_cbranch_scc1 .Lattn_loop_f
	s_waitcnt vmcnt(4)
	s_barrier
	s_waitcnt lgkmcnt(5)
	v_mfma_f32_32x32x16_bf16 v[48:63], v[216:219], v[144:147], v[48:63]
	ds_read_b128 v[216:219], v188 offset:8192
	s_nop 3
	s_add_i32 s2, s42, 2
	v_max3_f32 v254, v96, v97, v98
	s_and_b32 s2, s2, 31
	v_max3_f32 v255, v112, v113, v114
	s_lshl_b32 s2, s2, 7
	v_max3_f32 v254, v254, v99, v100
	v_max3_f32 v255, v255, v115, v116
	s_waitcnt lgkmcnt(5)
	v_mfma_f32_32x32x16_bf16 v[32:47], v[220:223], v[144:147], v[32:47]
	ds_read_b128 v[220:223], v188 offset:12288
	v_max3_f32 v254, v254, v101, v102
	v_max3_f32 v255, v255, v117, v118
	v_max3_f32 v254, v254, v103, v104
	v_max3_f32 v255, v255, v119, v120
	v_max3_f32 v254, v254, v105, v106
	v_max3_f32 v255, v255, v121, v122
	v_max3_f32 v254, v254, v107, v108
	v_max3_f32 v255, v255, v123, v124
	s_waitcnt lgkmcnt(5)
	v_mfma_f32_32x32x16_bf16 v[16:31], v[224:227], v[144:147], v[16:31]
	ds_read_b128 v[224:227], v186 offset:0
	v_max3_f32 v254, v254, v109, v110
	v_max3_f32 v255, v255, v125, v126
	v_max3_f32 v254, v254, v111, v127
	v_max_f32_e32 v254, v254, v255
	v_cmp_lt_f32_e32 vcc, 0x4138aa3b, v254
	s_add_i32 m0, s5, 114688
	v_lshl_add_u64 v[232:233], v[172:173], 0, s[2:3]
	global_load_lds_dwordx4 v[232:233], off
	s_waitcnt lgkmcnt(5)
	v_mfma_f32_32x32x16_bf16 v[0:15], v[228:231], v[144:147], v[0:15]
	ds_read_b128 v[228:231], v186 offset:4096
	s_add_i32 m0, s5, 122880
	v_lshl_add_u64 v[234:235], v[232:233], 0, s[22:23]
	global_load_lds_dwordx4 v[234:235], off
	s_cbranch_vccnz .Lattn_sp_T29
	v_exp_f32_e32 v96, v96
	v_exp_f32_e32 v97, v97
	v_exp_f32_e32 v98, v98
	v_exp_f32_e32 v99, v99
	s_waitcnt lgkmcnt(5)
	v_mfma_f32_32x32x16_bf16 v[48:63], v[208:211], v[148:151], v[48:63]
	ds_read_b128 v[208:211], v186 offset:8192
	v_exp_f32_e32 v100, v100
	v_exp_f32_e32 v101, v101
	v_exp_f32_e32 v102, v102
	v_exp_f32_e32 v103, v103
	s_waitcnt lgkmcnt(5)
	v_mfma_f32_32x32x16_bf16 v[32:47], v[212:215], v[148:151], v[32:47]
	ds_read_b128 v[212:215], v186 offset:12288
	v_add_f32_e32 v190, v96, v97
	v_add_f32_e32 v191, v98, v99
	v_add_f32_e32 v190, v190, v100
	v_add_f32_e32 v191, v191, v101
	s_waitcnt lgkmcnt(5)
	v_mfma_f32_32x32x16_bf16 v[16:31], v[216:219], v[148:151], v[16:31]
	ds_read_b128 v[216:219], v189 offset:0
	v_add_f32_e32 v190, v190, v102
	v_add_f32_e32 v191, v191, v103
	v_cvt_pk_bf16_f32 v144, v96, v97
	v_cvt_pk_bf16_f32 v145, v98, v99
	s_waitcnt lgkmcnt(5)
	v_mfma_f32_32x32x16_bf16 v[0:15], v[220:223], v[148:151], v[0:15]
	ds_read_b128 v[220:223], v189 offset:4096
	v_cvt_pk_bf16_f32 v146, v100, v101
	v_cvt_pk_bf16_f32 v147, v102, v103
	v_exp_f32_e32 v104, v104
	v_exp_f32_e32 v105, v105
	s_waitcnt lgkmcnt(5)
	v_mfma_f32_32x32x16_bf16 v[48:63], v[224:227], v[152:155], v[48:63]
	ds_read_b128 v[224:227], v189 offset:8192
	v_exp_f32_e32 v106, v106
	v_exp_f32_e32 v107, v107
	v_exp_f32_e32 v108, v108
	v_exp_f32_e32 v109, v109
	s_waitcnt lgkmcnt(5)
	v_mfma_f32_32x32x16_bf16 v[32:47], v[228:231], v[152:155], v[32:47]
	ds_read_b128 v[228:231], v189 offset:12288
	v_exp_f32_e32 v110, v110
	v_exp_f32_e32 v111, v111
	v_add_f32_e32 v190, v190, v104
	v_add_f32_e32 v191, v191, v105
	s_waitcnt lgkmcnt(5)
	v_mfma_f32_32x32x16_bf16 v[16:31], v[208:211], v[152:155], v[16:31]
	ds_read_b128 v[208:211], v182 offset:32768
	v_add_f32_e32 v190, v190, v106
	v_add_f32_e32 v191, v191, v107
	v_add_f32_e32 v190, v190, v108
	v_add_f32_e32 v191, v191, v109
	s_waitcnt lgkmcnt(5)
	v_mfma_f32_32x32x16_bf16 v[0:15], v[212:215], v[152:155], v[0:15]
	ds_read_b128 v[212:215], v182 offset:36864
	v_add_f32_e32 v190, v190, v110
	v_add_f32_e32 v191, v191, v111
	v_cvt_pk_bf16_f32 v148, v104, v105
	v_cvt_pk_bf16_f32 v149, v106, v107
	s_waitcnt lgkmcnt(5)
	v_mfma_f32_32x32x16_bf16 v[48:63], v[216:219], v[156:159], v[48:63]
	ds_read_b128 v[216:219], v183 offset:32768
	v_cvt_pk_bf16_f32 v150, v108, v109
	v_cvt_pk_bf16_f32 v151, v110, v111
	v_exp_f32_e32 v112, v112
	v_exp_f32_e32 v113, v113
	s_waitcnt lgkmcnt(5)
	v_mfma_f32_32x32x16_bf16 v[32:47], v[220:223], v[156:159], v[32:47]
	ds_read_b128 v[220:223], v183 offset:36864
	v_exp_f32_e32 v114, v114
	v_exp_f32_e32 v115, v115
	v_exp_f32_e32 v116, v116
	v_exp_f32_e32 v117, v117
	s_waitcnt lgkmcnt(5)
	v_mfma_f32_32x32x16_bf16 v[16:31], v[224:227], v[156:159], v[16:31]
	ds_read_b128 v[224:227], v184 offset:32768
	v_exp_f32_e32 v118, v118
	v_exp_f32_e32 v119, v119
	v_add_f32_e32 v190, v190, v112
	v_add_f32_e32 v191, v191, v113
	s_waitcnt lgkmcnt(5)
	v_mfma_f32_32x32x16_bf16 v[0:15], v[228:231], v[156:159], v[0:15]
	ds_read_b128 v[228:231], v184 offset:36864
	v_add_f32_e32 v190, v190, v114
	v_add_f32_e32 v191, v191, v115
	v_add_f32_e32 v190, v190, v116
	v_add_f32_e32 v191, v191, v117
	s_waitcnt lgkmcnt(5)
	v_mfma_f32_32x32x16_bf16 v[64:79], v[208:211], v[128:131], 0
	ds_read_b128 v[208:211], v185 offset:32768
	v_add_f32_e32 v190, v190, v118
	v_add_f32_e32 v191, v191, v119
	v_cvt_pk_bf16_f32 v152, v112, v113
	v_cvt_pk_bf16_f32 v153, v114, v115
	s_waitcnt lgkmcnt(5)
	v_mfma_f32_32x32x16_bf16 v[80:95], v[212:215], v[128:131], 0
	ds_read_b128 v[212:215], v185 offset:36864
	v_cvt_pk_bf16_f32 v154, v116, v117
	v_cvt_pk_bf16_f32 v155, v118, v119
	v_exp_f32_e32 v120, v120
	v_exp_f32_e32 v121, v121
	s_waitcnt lgkmcnt(5)
	v_mfma_f32_32x32x16_bf16 v[64:79], v[216:219], v[132:135], v[64:79]
	ds_read_b128 v[216:219], v187 offset:16384
	v_exp_f32_e32 v122, v122
	v_exp_f32_e32 v123, v123
	v_exp_f32_e32 v124, v124
	v_exp_f32_e32 v125, v125
	s_waitcnt lgkmcnt(5)
	v_mfma_f32_32x32x16_bf16 v[80:95], v[220:223], v[132:135], v[80:95]
	ds_read_b128 v[220:223], v187 offset:20480
	v_exp_f32_e32 v126, v126
	v_exp_f32_e32 v127, v127
	v_add_f32_e32 v190, v190, v120
	v_add_f32_e32 v191, v191, v121
	s_waitcnt lgkmcnt(5)
	v_mfma_f32_32x32x16_bf16 v[64:79], v[224:227], v[136:139], v[64:79]
	ds_read_b128 v[224:227], v187 offset:24576
	v_add_f32_e32 v190, v190, v122
	v_add_f32_e32 v191, v191, v123
	v_add_f32_e32 v190, v190, v124
	s_waitcnt lgkmcnt(5)
	v_mfma_f32_32x32x16_bf16 v[80:95], v[228:231], v[136:139], v[80:95]
	ds_read_b128 v[228:231], v187 offset:28672
	v_add_f32_e32 v191, v191, v125
	v_add_f32_e32 v190, v190, v126
	v_add_f32_e32 v191, v191, v127
	s_waitcnt lgkmcnt(5)
	v_mfma_f32_32x32x16_bf16 v[64:79], v[208:211], v[140:143], v[64:79]
	ds_read_b128 v[208:211], v188 offset:16384
	v_cvt_pk_bf16_f32 v156, v120, v121
	v_cvt_pk_bf16_f32 v157, v122, v123
	v_cvt_pk_bf16_f32 v158, v124, v125
	s_waitcnt lgkmcnt(5)
	v_mfma_f32_32x32x16_bf16 v[80:95], v[212:215], v[140:143], v[80:95]
	ds_read_b128 v[212:215], v188 offset:20480
	v_cvt_pk_bf16_f32 v159, v126, v127
	v_add_f32_e32 v190, v190, v191
	v_add_f32_e32 v167, v167, v190
	s_waitcnt vmcnt(2)
	s_barrier
	s_waitcnt lgkmcnt(5)
	v_mfma_f32_32x32x16_bf16 v[48:63], v[216:219], v[144:147], v[48:63]
	ds_read_b128 v[216:219], v188 offset:24576
	s_nop 3
	v_max3_f32 v254, v64, v65, v66
	v_max3_f32 v255, v80, v81, v82
	v_max3_f32 v254, v254, v67, v68
	v_max3_f32 v255, v255, v83, v84
	v_max3_f32 v254, v254, v69, v70
	v_max3_f32 v255, v255, v85, v86
	v_max3_f32 v254, v254, v71, v72
	s_waitcnt lgkmcnt(5)
	v_mfma_f32_32x32x16_bf16 v[32:47], v[220:223], v[144:147], v[32:47]
	ds_read_b128 v[220:223], v188 offset:28672
	v_max3_f32 v255, v255, v87, v88
	v_max3_f32 v254, v254, v73, v74
	v_max3_f32 v255, v255, v89, v90
	v_max3_f32 v254, v254, v75, v76
	v_max3_f32 v255, v255, v91, v92
	v_max3_f32 v254, v254, v77, v78
	v_max3_f32 v255, v255, v93, v94
	v_max3_f32 v254, v254, v79, v95
	s_waitcnt lgkmcnt(5)
	v_mfma_f32_32x32x16_bf16 v[16:31], v[224:227], v[144:147], v[16:31]
	ds_read_b128 v[224:227], v186 offset:16384
	v_max_f32_e32 v254, v254, v255
	v_cmp_lt_f32_e32 vcc, 0x4138aa3b, v254
	s_nop 4
	s_cbranch_vccnz .Lattn_sp_T30
	s_waitcnt lgkmcnt(5)
	v_mfma_f32_32x32x16_bf16 v[0:15], v[228:231], v[144:147], v[0:15]
	ds_read_b128 v[228:231], v186 offset:20480
	v_exp_f32_e32 v64, v64
	v_exp_f32_e32 v65, v65
	v_exp_f32_e32 v66, v66
	v_exp_f32_e32 v67, v67
	s_waitcnt lgkmcnt(5)
	v_mfma_f32_32x32x16_bf16 v[48:63], v[208:211], v[148:151], v[48:63]
	ds_read_b128 v[208:211], v186 offset:24576
	v_exp_f32_e32 v68, v68
	v_exp_f32_e32 v69, v69
	v_exp_f32_e32 v70, v70
	v_exp_f32_e32 v71, v71
	s_waitcnt lgkmcnt(5)
	v_mfma_f32_32x32x16_bf16 v[32:47], v[212:215], v[148:151], v[32:47]
	ds_read_b128 v[212:215], v186 offset:28672
	v_add_f32_e32 v190, v64, v65
	v_add_f32_e32 v191, v66, v67
	v_add_f32_e32 v190, v190, v68
	v_add_f32_e32 v191, v191, v69
	s_waitcnt lgkmcnt(5)
	v_mfma_f32_32x32x16_bf16 v[16:31], v[216:219], v[148:151], v[16:31]
	ds_read_b128 v[216:219], v189 offset:16384
	v_add_f32_e32 v190, v190, v70
	v_add_f32_e32 v191, v191, v71
	v_cvt_pk_bf16_f32 v144, v64, v65
	v_cvt_pk_bf16_f32 v145, v66, v67
	s_waitcnt lgkmcnt(5)
	v_mfma_f32_32x32x16_bf16 v[0:15], v[220:223], v[148:151], v[0:15]
	ds_read_b128 v[220:223], v189 offset:20480
	v_cvt_pk_bf16_f32 v146, v68, v69
	v_cvt_pk_bf16_f32 v147, v70, v71
	v_exp_f32_e32 v72, v72
	v_exp_f32_e32 v73, v73
	s_waitcnt lgkmcnt(5)
	v_mfma_f32_32x32x16_bf16 v[48:63], v[224:227], v[152:155], v[48:63]
	ds_read_b128 v[224:227], v189 offset:24576
	v_exp_f32_e32 v74, v74
	v_exp_f32_e32 v75, v75
	v_exp_f32_e32 v76, v76
	v_exp_f32_e32 v77, v77
	s_waitcnt lgkmcnt(5)
	v_mfma_f32_32x32x16_bf16 v[32:47], v[228:231], v[152:155], v[32:47]
	ds_read_b128 v[228:231], v189 offset:28672
	v_exp_f32_e32 v78, v78
	v_exp_f32_e32 v79, v79
	v_add_f32_e32 v190, v190, v72
	v_add_f32_e32 v191, v191, v73
	s_waitcnt lgkmcnt(5)
	v_mfma_f32_32x32x16_bf16 v[16:31], v[208:211], v[152:155], v[16:31]
	ds_read_b128 v[208:211], v182 offset:49152
	v_add_f32_e32 v190, v190, v74
	v_add_f32_e32 v191, v191, v75
	v_add_f32_e32 v190, v190, v76
	v_add_f32_e32 v191, v191, v77
	s_waitcnt lgkmcnt(5)
	v_mfma_f32_32x32x16_bf16 v[0:15], v[212:215], v[152:155], v[0:15]
	ds_read_b128 v[212:215], v182 offset:53248
	v_add_f32_e32 v190, v190, v78
	v_add_f32_e32 v191, v191, v79
	v_cvt_pk_bf16_f32 v148, v72, v73
	v_cvt_pk_bf16_f32 v149, v74, v75
	s_waitcnt lgkmcnt(5)
	v_mfma_f32_32x32x16_bf16 v[48:63], v[216:219], v[156:159], v[48:63]
	ds_read_b128 v[216:219], v183 offset:49152
	v_cvt_pk_bf16_f32 v150, v76, v77
	v_cvt_pk_bf16_f32 v151, v78, v79
	v_exp_f32_e32 v80, v80
	v_exp_f32_e32 v81, v81
	s_waitcnt lgkmcnt(5)
	v_mfma_f32_32x32x16_bf16 v[32:47], v[220:223], v[156:159], v[32:47]
	ds_read_b128 v[220:223], v183 offset:53248
	v_exp_f32_e32 v82, v82
	v_exp_f32_e32 v83, v83
	v_exp_f32_e32 v84, v84
	v_exp_f32_e32 v85, v85
	s_waitcnt lgkmcnt(5)
	v_mfma_f32_32x32x16_bf16 v[16:31], v[224:227], v[156:159], v[16:31]
	ds_read_b128 v[224:227], v184 offset:49152
	v_exp_f32_e32 v86, v86
	v_exp_f32_e32 v87, v87
	v_add_f32_e32 v190, v190, v80
	v_add_f32_e32 v191, v191, v81
	s_waitcnt lgkmcnt(5)
	v_mfma_f32_32x32x16_bf16 v[0:15], v[228:231], v[156:159], v[0:15]
	ds_read_b128 v[228:231], v184 offset:53248
	v_add_f32_e32 v190, v190, v82
	v_add_f32_e32 v191, v191, v83
	v_add_f32_e32 v190, v190, v84
	v_add_f32_e32 v191, v191, v85
	s_waitcnt lgkmcnt(5)
	v_mfma_f32_32x32x16_bf16 v[96:111], v[208:211], v[128:131], 0
	ds_read_b128 v[208:211], v185 offset:49152
	v_add_f32_e32 v190, v190, v86
	v_add_f32_e32 v191, v191, v87
	v_cvt_pk_bf16_f32 v152, v80, v81
	v_cvt_pk_bf16_f32 v153, v82, v83
	s_waitcnt lgkmcnt(5)
	v_mfma_f32_32x32x16_bf16 v[112:127], v[212:215], v[128:131], 0
	ds_read_b128 v[212:215], v185 offset:53248
	v_cvt_pk_bf16_f32 v154, v84, v85
	v_cvt_pk_bf16_f32 v155, v86, v87
	v_exp_f32_e32 v88, v88
	v_exp_f32_e32 v89, v89
	s_waitcnt lgkmcnt(5)
	v_mfma_f32_32x32x16_bf16 v[96:111], v[216:219], v[132:135], v[96:111]
	ds_read_b128 v[216:219], v187 offset:32768
	v_exp_f32_e32 v90, v90
	v_exp_f32_e32 v91, v91
	v_exp_f32_e32 v92, v92
	v_exp_f32_e32 v93, v93
	s_waitcnt lgkmcnt(5)
	v_mfma_f32_32x32x16_bf16 v[112:127], v[220:223], v[132:135], v[112:127]
	ds_read_b128 v[220:223], v187 offset:36864
	v_exp_f32_e32 v94, v94
	v_exp_f32_e32 v95, v95
	v_add_f32_e32 v190, v190, v88
	v_add_f32_e32 v191, v191, v89
	s_waitcnt lgkmcnt(5)
	v_mfma_f32_32x32x16_bf16 v[96:111], v[224:227], v[136:139], v[96:111]
	ds_read_b128 v[224:227], v187 offset:40960
	v_add_f32_e32 v190, v190, v90
	v_add_f32_e32 v191, v191, v91
	v_add_f32_e32 v190, v190, v92
	s_waitcnt lgkmcnt(5)
	v_mfma_f32_32x32x16_bf16 v[112:127], v[228:231], v[136:139], v[112:127]
	ds_read_b128 v[228:231], v187 offset:45056
	v_add_f32_e32 v191, v191, v93
	v_add_f32_e32 v190, v190, v94
	v_add_f32_e32 v191, v191, v95
	s_waitcnt lgkmcnt(5)
	v_mfma_f32_32x32x16_bf16 v[96:111], v[208:211], v[140:143], v[96:111]
	ds_read_b128 v[208:211], v188 offset:32768
	v_cvt_pk_bf16_f32 v156, v88, v89
	v_cvt_pk_bf16_f32 v157, v90, v91
	v_cvt_pk_bf16_f32 v158, v92, v93
	s_waitcnt lgkmcnt(5)
	v_mfma_f32_32x32x16_bf16 v[112:127], v[212:215], v[140:143], v[112:127]
	ds_read_b128 v[212:215], v188 offset:36864
	v_cvt_pk_bf16_f32 v159, v94, v95
	v_add_f32_e32 v190, v190, v191
	v_add_f32_e32 v167, v167, v190
	s_waitcnt vmcnt(0)
	s_barrier
	s_waitcnt lgkmcnt(5)
	v_mfma_f32_32x32x16_bf16 v[48:63], v[216:219], v[144:147], v[48:63]
	ds_read_b128 v[216:219], v188 offset:40960
	s_nop 3
	v_max3_f32 v254, v96, v97, v98
	v_max3_f32 v255, v112, v113, v114
	v_max3_f32 v254, v254, v99, v100
	v_max3_f32 v255, v255, v115, v116
	v_max3_f32 v254, v254, v101, v102
	v_max3_f32 v255, v255, v117, v118
	v_max3_f32 v254, v254, v103, v104
	s_waitcnt lgkmcnt(5)
	v_mfma_f32_32x32x16_bf16 v[32:47], v[220:223], v[144:147], v[32:47]
	ds_read_b128 v[220:223], v188 offset:45056
	v_max3_f32 v255, v255, v119, v120
	v_max3_f32 v254, v254, v105, v106
	v_max3_f32 v255, v255, v121, v122
	v_max3_f32 v254, v254, v107, v108
	v_max3_f32 v255, v255, v123, v124
	v_max3_f32 v254, v254, v109, v110
	v_max3_f32 v255, v255, v125, v126
	v_max3_f32 v254, v254, v111, v127
	s_waitcnt lgkmcnt(5)
	v_mfma_f32_32x32x16_bf16 v[16:31], v[224:227], v[144:147], v[16:31]
	ds_read_b128 v[224:227], v186 offset:32768
	v_max_f32_e32 v254, v254, v255
	v_cmp_lt_f32_e32 vcc, 0x4138aa3b, v254
	s_nop 4
	s_cbranch_vccnz .Lattn_sp_T31
	s_waitcnt lgkmcnt(5)
	v_mfma_f32_32x32x16_bf16 v[0:15], v[228:231], v[144:147], v[0:15]
	ds_read_b128 v[228:231], v186 offset:36864
	v_exp_f32_e32 v96, v96
	v_exp_f32_e32 v97, v97
	v_exp_f32_e32 v98, v98
	v_exp_f32_e32 v99, v99
	v_exp_f32_e32 v100, v100
	v_exp_f32_e32 v101, v101
	v_exp_f32_e32 v102, v102
	s_waitcnt lgkmcnt(5)
	v_mfma_f32_32x32x16_bf16 v[48:63], v[208:211], v[148:151], v[48:63]
	ds_read_b128 v[208:211], v186 offset:40960
	v_exp_f32_e32 v103, v103
	v_add_f32_e32 v190, v96, v97
	v_add_f32_e32 v191, v98, v99
	v_add_f32_e32 v190, v190, v100
	v_add_f32_e32 v191, v191, v101
	v_add_f32_e32 v190, v190, v102
	v_add_f32_e32 v191, v191, v103
	s_waitcnt lgkmcnt(5)
	v_mfma_f32_32x32x16_bf16 v[32:47], v[212:215], v[148:151], v[32:47]
	ds_read_b128 v[212:215], v186 offset:45056
	v_cvt_pk_bf16_f32 v144, v96, v97
	v_cvt_pk_bf16_f32 v145, v98, v99
	v_cvt_pk_bf16_f32 v146, v100, v101
	v_cvt_pk_bf16_f32 v147, v102, v103
	s_waitcnt lgkmcnt(5)
	v_mfma_f32_32x32x16_bf16 v[16:31], v[216:219], v[148:151], v[16:31]
	ds_read_b128 v[216:219], v189 offset:32768
	s_waitcnt lgkmcnt(5)
	v_mfma_f32_32x32x16_bf16 v[0:15], v[220:223], v[148:151], v[0:15]
	ds_read_b128 v[220:223], v189 offset:36864
	v_exp_f32_e32 v104, v104
	v_exp_f32_e32 v105, v105
	v_exp_f32_e32 v106, v106
	v_exp_f32_e32 v107, v107
	v_exp_f32_e32 v108, v108
	v_exp_f32_e32 v109, v109
	v_exp_f32_e32 v110, v110
	s_waitcnt lgkmcnt(5)
	v_mfma_f32_32x32x16_bf16 v[48:63], v[224:227], v[152:155], v[48:63]
	ds_read_b128 v[224:227], v189 offset:40960
	v_exp_f32_e32 v111, v111
	v_add_f32_e32 v190, v190, v104
	v_add_f32_e32 v191, v191, v105
	v_add_f32_e32 v190, v190, v106
	v_add_f32_e32 v191, v191, v107
	v_add_f32_e32 v190, v190, v108
	v_add_f32_e32 v191, v191, v109
	s_waitcnt lgkmcnt(5)
	v_mfma_f32_32x32x16_bf16 v[32:47], v[228:231], v[152:155], v[32:47]
	ds_read_b128 v[228:231], v189 offset:45056
	v_add_f32_e32 v190, v190, v110
	v_add_f32_e32 v191, v191, v111
	v_cvt_pk_bf16_f32 v148, v104, v105
	v_cvt_pk_bf16_f32 v149, v106, v107
	v_cvt_pk_bf16_f32 v150, v108, v109
	v_cvt_pk_bf16_f32 v151, v110, v111
	s_waitcnt lgkmcnt(5)
	v_mfma_f32_32x32x16_bf16 v[16:31], v[208:211], v[152:155], v[16:31]
	ds_read_b128 v[208:211], v187 offset:49152
	s_waitcnt lgkmcnt(5)
	v_mfma_f32_32x32x16_bf16 v[0:15], v[212:215], v[152:155], v[0:15]
	ds_read_b128 v[212:215], v187 offset:53248
	v_exp_f32_e32 v112, v112
	v_exp_f32_e32 v113, v113
	v_exp_f32_e32 v114, v114
	v_exp_f32_e32 v115, v115
	v_exp_f32_e32 v116, v116
	v_exp_f32_e32 v117, v117
	v_exp_f32_e32 v118, v118
	v_exp_f32_e32 v119, v119
	v_add_f32_e32 v190, v190, v112
	s_waitcnt lgkmcnt(5)
	v_mfma_f32_32x32x16_bf16 v[48:63], v[216:219], v[156:159], v[48:63]
	ds_read_b128 v[216:219], v187 offset:57344
	v_add_f32_e32 v191, v191, v113
	v_add_f32_e32 v190, v190, v114
	v_add_f32_e32 v191, v191, v115
	v_add_f32_e32 v190, v190, v116
	v_add_f32_e32 v191, v191, v117
	v_add_f32_e32 v190, v190, v118
	v_add_f32_e32 v191, v191, v119
	v_cvt_pk_bf16_f32 v152, v112, v113
	v_cvt_pk_bf16_f32 v153, v114, v115
	s_waitcnt lgkmcnt(5)
	v_mfma_f32_32x32x16_bf16 v[32:47], v[220:223], v[156:159], v[32:47]
	ds_read_b128 v[220:223], v187 offset:61440
	v_cvt_pk_bf16_f32 v154, v116, v117
	v_cvt_pk_bf16_f32 v155, v118, v119
	s_waitcnt lgkmcnt(5)
	v_mfma_f32_32x32x16_bf16 v[16:31], v[224:227], v[156:159], v[16:31]
	ds_read_b128 v[224:227], v188 offset:49152
	s_waitcnt lgkmcnt(5)
	v_mfma_f32_32x32x16_bf16 v[0:15], v[228:231], v[156:159], v[0:15]
	ds_read_b128 v[228:231], v188 offset:53248
	v_exp_f32_e32 v120, v120
	v_exp_f32_e32 v121, v121
	v_exp_f32_e32 v122, v122
	v_exp_f32_e32 v123, v123
	v_exp_f32_e32 v124, v124
	v_exp_f32_e32 v125, v125
	v_exp_f32_e32 v126, v126
	v_exp_f32_e32 v127, v127
	v_add_f32_e32 v190, v190, v120
	v_add_f32_e32 v191, v191, v121
	v_add_f32_e32 v190, v190, v122
	v_add_f32_e32 v191, v191, v123
	v_add_f32_e32 v190, v190, v124
	v_add_f32_e32 v191, v191, v125
	v_add_f32_e32 v190, v190, v126
	v_add_f32_e32 v191, v191, v127
	v_cvt_pk_bf16_f32 v156, v120, v121
	v_cvt_pk_bf16_f32 v157, v122, v123
	v_cvt_pk_bf16_f32 v158, v124, v125
	v_cvt_pk_bf16_f32 v159, v126, v127
	v_add_f32_e32 v190, v190, v191
	v_add_f32_e32 v167, v167, v190
.Lattn_final:
	s_waitcnt lgkmcnt(5)
	v_mfma_f32_32x32x16_bf16 v[48:63], v[208:211], v[144:147], v[48:63]
	ds_read_b128 v[208:211], v188 offset:57344
	s_waitcnt lgkmcnt(5)
	v_mfma_f32_32x32x16_bf16 v[32:47], v[212:215], v[144:147], v[32:47]
	ds_read_b128 v[212:215], v188 offset:61440
	s_waitcnt lgkmcnt(5)
	v_mfma_f32_32x32x16_bf16 v[16:31], v[216:219], v[144:147], v[16:31]
	ds_read_b128 v[216:219], v186 offset:49152
	s_waitcnt lgkmcnt(5)
	v_mfma_f32_32x32x16_bf16 v[0:15], v[220:223], v[144:147], v[0:15]
	ds_read_b128 v[220:223], v186 offset:53248
	s_waitcnt lgkmcnt(5)
	v_mfma_f32_32x32x16_bf16 v[48:63], v[224:227], v[148:151], v[48:63]
	ds_read_b128 v[224:227], v186 offset:57344
	s_waitcnt lgkmcnt(5)
	v_mfma_f32_32x32x16_bf16 v[32:47], v[228:231], v[148:151], v[32:47]
	ds_read_b128 v[228:231], v186 offset:61440
	s_waitcnt lgkmcnt(5)
	v_mfma_f32_32x32x16_bf16 v[16:31], v[208:211], v[148:151], v[16:31]
	ds_read_b128 v[208:211], v189 offset:49152
	s_waitcnt lgkmcnt(5)
	v_mfma_f32_32x32x16_bf16 v[0:15], v[212:215], v[148:151], v[0:15]
	ds_read_b128 v[212:215], v189 offset:53248
	s_waitcnt lgkmcnt(5)
	v_mfma_f32_32x32x16_bf16 v[48:63], v[216:219], v[152:155], v[48:63]
	ds_read_b128 v[216:219], v189 offset:57344
	s_waitcnt lgkmcnt(5)
	v_mfma_f32_32x32x16_bf16 v[32:47], v[220:223], v[152:155], v[32:47]
	ds_read_b128 v[220:223], v189 offset:61440
	s_waitcnt lgkmcnt(5)
	v_mfma_f32_32x32x16_bf16 v[16:31], v[224:227], v[152:155], v[16:31]
	s_waitcnt lgkmcnt(4)
	v_mfma_f32_32x32x16_bf16 v[0:15], v[228:231], v[152:155], v[0:15]
	s_waitcnt lgkmcnt(3)
	v_mfma_f32_32x32x16_bf16 v[48:63], v[208:211], v[156:159], v[48:63]
	s_waitcnt lgkmcnt(2)
	v_mfma_f32_32x32x16_bf16 v[32:47], v[212:215], v[156:159], v[32:47]
	s_waitcnt lgkmcnt(1)
	v_mfma_f32_32x32x16_bf16 v[16:31], v[216:219], v[156:159], v[16:31]
	s_waitcnt lgkmcnt(0)
	v_mfma_f32_32x32x16_bf16 v[0:15], v[220:223], v[156:159], v[0:15]
	s_nop 15
	s_nop 7
	v_mov_b32_e32 v64, v167
	s_branch .Lattn_end
	s_waitcnt lgkmcnt(5)
	v_mfma_f32_32x32x16_bf16 v[96:111], v[208:211], v[128:131], 0
	ds_read_b128 v[208:211], v185 offset:16384
	s_add_i32 s2, s42, 3
	v_max3_f32 v254, v64, v65, v66
	s_and_b32 s2, s2, 31
	v_max3_f32 v255, v80, v81, v82
	s_mul_i32 s2, s2, 0x44000
	v_max3_f32 v254, v254, v67, v68
	s_add_i32 m0, s5, 49152
	v_max3_f32 v255, v255, v83, v84
	s_waitcnt lgkmcnt(5)
	v_mfma_f32_32x32x16_bf16 v[112:127], v[212:215], v[128:131], 0
	ds_read_b128 v[212:215], v185 offset:20480
	v_lshl_add_u64 v[232:233], v[170:171], 0, s[2:3]
	v_max3_f32 v254, v254, v69, v70
	v_lshl_add_u64 v[234:235], v[232:233], 0, s[18:19]
	v_max3_f32 v255, v255, v85, v86
	global_load_lds_dwordx4 v[234:235], off
	v_max3_f32 v254, v254, v71, v72
	s_add_i32 m0, s5, 57344
	v_max3_f32 v255, v255, v87, v88
	s_waitcnt lgkmcnt(5)
	v_mfma_f32_32x32x16_bf16 v[96:111], v[216:219], v[132:135], v[96:111]
	ds_read_b128 v[216:219], v187 offset:0
	v_lshl_add_u64 v[232:233], v[232:233], 0, s[20:21]
	v_max3_f32 v254, v254, v73, v74
	global_load_lds_dwordx4 v[232:233], off
	v_max3_f32 v255, v255, v89, v90
	s_add_i32 s2, s42, 2
	v_max3_f32 v254, v254, v75, v76
	s_and_b32 s2, s2, 31
	v_max3_f32 v255, v255, v91, v92
	s_waitcnt lgkmcnt(5)
	v_mfma_f32_32x32x16_bf16 v[112:127], v[220:223], v[132:135], v[112:127]
	ds_read_b128 v[220:223], v187 offset:4096
	s_lshl_b32 s2, s2, 7
	v_max3_f32 v254, v254, v77, v78
	v_max3_f32 v255, v255, v93, v94
	v_max3_f32 v254, v254, v79, v95
	v_max_f32_e32 v254, v254, v255
	v_mov_b32_e32 v180, 0xc2800000
	v_cmp_lt_f32_e32 vcc, 0x4138aa3b, v254
	v_cmp_gt_f32_e64 s[40:41], v180, v254
	s_waitcnt lgkmcnt(5)
	v_mfma_f32_32x32x16_bf16 v[96:111], v[224:227], v[136:139], v[96:111]
	ds_read_b128 v[224:227], v187 offset:8192
	s_add_i32 m0, s5, 98304
	v_lshl_add_u64 v[232:233], v[172:173], 0, s[2:3]
	global_load_lds_dwordx4 v[232:233], off
	s_add_i32 m0, s5, 106496
	v_lshl_add_u64 v[234:235], v[232:233], 0, s[22:23]
	global_load_lds_dwordx4 v[234:235], off
	s_or_b64 vcc, vcc, s[40:41]
	s_nop 0
.Lattn_sp_t0:
	v_mov_b32_e32 v175, v243
	v_mov_b32_e32 v255, v254
	s_nop 1
	v_permlane32_swap_b32_e32 v254, v255
	v_max_f32_e32 v254, v254, v255
	v_add_f32_e32 v180, 0x4138aa3b, v175
	v_cmp_gt_f32_e32 vcc, v254, v180
	s_nop 1
	v_cndmask_b32_e32 v180, v175, v254, vcc
	v_sub_f32_e32 v255, v175, v180
	v_exp_f32_e32 v174, v255
	v_mov_b32_e32 v175, v180
	v_sub_f32_e32 v64, v64, v175
	v_sub_f32_e32 v65, v65, v175
	v_sub_f32_e32 v66, v66, v175
	v_sub_f32_e32 v67, v67, v175
	v_sub_f32_e32 v68, v68, v175
	v_sub_f32_e32 v69, v69, v175
	v_sub_f32_e32 v70, v70, v175
	v_sub_f32_e32 v71, v71, v175
	v_exp_f32_e32 v64, v64
	v_exp_f32_e32 v65, v65
	v_exp_f32_e32 v66, v66
	v_exp_f32_e32 v67, v67
	v_exp_f32_e32 v68, v68
	v_exp_f32_e32 v69, v69
	v_exp_f32_e32 v70, v70
	v_exp_f32_e32 v71, v71
	v_add_f32_e32 v190, v64, v65
	v_add_f32_e32 v191, v66, v67
	v_add_f32_e32 v190, v190, v68
	v_add_f32_e32 v191, v191, v69
	s_waitcnt lgkmcnt(5)
	v_mfma_f32_32x32x16_bf16 v[112:127], v[228:231], v[136:139], v[112:127]
	ds_read_b128 v[228:231], v187 offset:12288
	v_add_f32_e32 v190, v190, v70
	v_add_f32_e32 v191, v191, v71
	v_cvt_pk_bf16_f32 v144, v64, v65
	v_cvt_pk_bf16_f32 v145, v66, v67
	v_cvt_pk_bf16_f32 v146, v68, v69
	v_cvt_pk_bf16_f32 v147, v70, v71
	s_waitcnt lgkmcnt(5)
	v_mfma_f32_32x32x16_bf16 v[96:111], v[208:211], v[140:143], v[96:111]
	ds_read_b128 v[208:211], v188 offset:0
	s_waitcnt lgkmcnt(5)
	v_mfma_f32_32x32x16_bf16 v[112:127], v[212:215], v[140:143], v[112:127]
	ds_read_b128 v[212:215], v188 offset:4096
	v_sub_f32_e32 v72, v72, v175
	v_sub_f32_e32 v73, v73, v175
	v_sub_f32_e32 v74, v74, v175
	v_sub_f32_e32 v75, v75, v175
	v_sub_f32_e32 v76, v76, v175
	v_sub_f32_e32 v77, v77, v175
	v_sub_f32_e32 v78, v78, v175
	v_sub_f32_e32 v79, v79, v175
	v_exp_f32_e32 v72, v72
	v_exp_f32_e32 v73, v73
	v_exp_f32_e32 v74, v74
	v_exp_f32_e32 v75, v75
	v_exp_f32_e32 v76, v76
	v_exp_f32_e32 v77, v77
	v_exp_f32_e32 v78, v78
	v_exp_f32_e32 v79, v79
	v_add_f32_e32 v190, v190, v72
	v_add_f32_e32 v191, v191, v73
	v_add_f32_e32 v190, v190, v74
	v_add_f32_e32 v191, v191, v75
	v_add_f32_e32 v190, v190, v76
	v_add_f32_e32 v191, v191, v77
	v_add_f32_e32 v190, v190, v78
	v_add_f32_e32 v191, v191, v79
	v_cvt_pk_bf16_f32 v148, v72, v73
	v_cvt_pk_bf16_f32 v149, v74, v75
	v_cvt_pk_bf16_f32 v150, v76, v77
	v_cvt_pk_bf16_f32 v151, v78, v79
	v_sub_f32_e32 v80, v80, v175
	v_sub_f32_e32 v81, v81, v175
	v_sub_f32_e32 v82, v82, v175
	v_sub_f32_e32 v83, v83, v175
	v_sub_f32_e32 v84, v84, v175
	v_sub_f32_e32 v85, v85, v175
	v_sub_f32_e32 v86, v86, v175
	v_sub_f32_e32 v87, v87, v175
	v_exp_f32_e32 v80, v80
	v_exp_f32_e32 v81, v81
	v_exp_f32_e32 v82, v82
	v_exp_f32_e32 v83, v83
	v_exp_f32_e32 v84, v84
	v_exp_f32_e32 v85, v85
	v_exp_f32_e32 v86, v86
	v_exp_f32_e32 v87, v87
	v_add_f32_e32 v190, v190, v80
	v_add_f32_e32 v191, v191, v81
	v_add_f32_e32 v190, v190, v82
	v_add_f32_e32 v191, v191, v83
	v_add_f32_e32 v190, v190, v84
	v_add_f32_e32 v191, v191, v85
	v_add_f32_e32 v190, v190, v86
	v_add_f32_e32 v191, v191, v87
	v_cvt_pk_bf16_f32 v152, v80, v81
	v_cvt_pk_bf16_f32 v153, v82, v83
	v_cvt_pk_bf16_f32 v154, v84, v85
	v_cvt_pk_bf16_f32 v155, v86, v87
	v_sub_f32_e32 v88, v88, v175
	v_sub_f32_e32 v89, v89, v175
	v_sub_f32_e32 v90, v90, v175
	v_sub_f32_e32 v91, v91, v175
	v_sub_f32_e32 v92, v92, v175
	v_sub_f32_e32 v93, v93, v175
	v_sub_f32_e32 v94, v94, v175
	v_sub_f32_e32 v95, v95, v175
	v_exp_f32_e32 v88, v88
	v_exp_f32_e32 v89, v89
	v_exp_f32_e32 v90, v90
	v_exp_f32_e32 v91, v91
	v_exp_f32_e32 v92, v92
	v_exp_f32_e32 v93, v93
	v_exp_f32_e32 v94, v94
	v_exp_f32_e32 v95, v95
	v_add_f32_e32 v190, v190, v88
	v_add_f32_e32 v191, v191, v89
	v_add_f32_e32 v190, v190, v90
	v_add_f32_e32 v191, v191, v91
	v_add_f32_e32 v190, v190, v92
	v_add_f32_e32 v191, v191, v93
	v_add_f32_e32 v190, v190, v94
	v_add_f32_e32 v191, v191, v95
	v_cvt_pk_bf16_f32 v156, v88, v89
	v_cvt_pk_bf16_f32 v157, v90, v91
	v_cvt_pk_bf16_f32 v158, v92, v93
	v_cvt_pk_bf16_f32 v159, v94, v95
	v_add_f32_e32 v190, v190, v191
	v_fma_f32 v167, v167, v174, v190
	s_cbranch_vccz .Lattn_noresc_t0
	s_nop 7
	s_nop 7
	v_pk_mul_f32 v[0:1], v[0:1], v[174:175] op_sel_hi:[1,0]
	v_pk_mul_f32 v[2:3], v[2:3], v[174:175] op_sel_hi:[1,0]
	v_pk_mul_f32 v[4:5], v[4:5], v[174:175] op_sel_hi:[1,0]
	v_pk_mul_f32 v[6:7], v[6:7], v[174:175] op_sel_hi:[1,0]
	v_pk_mul_f32 v[8:9], v[8:9], v[174:175] op_sel_hi:[1,0]
	v_pk_mul_f32 v[10:11], v[10:11], v[174:175] op_sel_hi:[1,0]
	v_pk_mul_f32 v[12:13], v[12:13], v[174:175] op_sel_hi:[1,0]
	v_pk_mul_f32 v[14:15], v[14:15], v[174:175] op_sel_hi:[1,0]
	v_pk_mul_f32 v[16:17], v[16:17], v[174:175] op_sel_hi:[1,0]
	v_pk_mul_f32 v[18:19], v[18:19], v[174:175] op_sel_hi:[1,0]
	v_pk_mul_f32 v[20:21], v[20:21], v[174:175] op_sel_hi:[1,0]
	v_pk_mul_f32 v[22:23], v[22:23], v[174:175] op_sel_hi:[1,0]
	v_pk_mul_f32 v[24:25], v[24:25], v[174:175] op_sel_hi:[1,0]
	v_pk_mul_f32 v[26:27], v[26:27], v[174:175] op_sel_hi:[1,0]
	v_pk_mul_f32 v[28:29], v[28:29], v[174:175] op_sel_hi:[1,0]
	v_pk_mul_f32 v[30:31], v[30:31], v[174:175] op_sel_hi:[1,0]
	v_pk_mul_f32 v[32:33], v[32:33], v[174:175] op_sel_hi:[1,0]
	v_pk_mul_f32 v[34:35], v[34:35], v[174:175] op_sel_hi:[1,0]
	v_pk_mul_f32 v[36:37], v[36:37], v[174:175] op_sel_hi:[1,0]
	v_pk_mul_f32 v[38:39], v[38:39], v[174:175] op_sel_hi:[1,0]
	v_pk_mul_f32 v[40:41], v[40:41], v[174:175] op_sel_hi:[1,0]
	v_pk_mul_f32 v[42:43], v[42:43], v[174:175] op_sel_hi:[1,0]
	v_pk_mul_f32 v[44:45], v[44:45], v[174:175] op_sel_hi:[1,0]
	v_pk_mul_f32 v[46:47], v[46:47], v[174:175] op_sel_hi:[1,0]
	v_pk_mul_f32 v[48:49], v[48:49], v[174:175] op_sel_hi:[1,0]
	v_pk_mul_f32 v[50:51], v[50:51], v[174:175] op_sel_hi:[1,0]
	v_pk_mul_f32 v[52:53], v[52:53], v[174:175] op_sel_hi:[1,0]
	v_pk_mul_f32 v[54:55], v[54:55], v[174:175] op_sel_hi:[1,0]
	v_pk_mul_f32 v[56:57], v[56:57], v[174:175] op_sel_hi:[1,0]
	v_pk_mul_f32 v[58:59], v[58:59], v[174:175] op_sel_hi:[1,0]
	v_pk_mul_f32 v[60:61], v[60:61], v[174:175] op_sel_hi:[1,0]
	v_pk_mul_f32 v[62:63], v[62:63], v[174:175] op_sel_hi:[1,0]
	s_nop 1
.Lattn_noresc_t0:
	s_add_i32 s42, s31, 1
	s_movk_i32 s47, 7
.Lattn_loop_s:
	s_waitcnt vmcnt(4)
	s_barrier
	s_waitcnt lgkmcnt(5)
	v_mfma_f32_32x32x16_bf16 v[48:63], v[216:219], v[144:147], v[48:63]
	ds_read_b128 v[216:219], v188 offset:8192
	s_add_i32 s2, s42, 3
	v_max3_f32 v254, v96, v97, v98
	s_and_b32 s2, s2, 31
	v_max3_f32 v255, v112, v113, v114
	s_mul_i32 s2, s2, 0x44000
	v_max3_f32 v254, v254, v99, v100
	s_add_i32 m0, s5, 0
	v_max3_f32 v255, v255, v115, v116
	s_waitcnt lgkmcnt(5)
	v_mfma_f32_32x32x16_bf16 v[32:47], v[220:223], v[144:147], v[32:47]
	ds_read_b128 v[220:223], v188 offset:12288
	v_lshl_add_u64 v[232:233], v[170:171], 0, s[2:3]
	v_max3_f32 v254, v254, v101, v102
	v_lshl_add_u64 v[234:235], v[232:233], 0, s[18:19]
	v_max3_f32 v255, v255, v117, v118
	global_load_lds_dwordx4 v[234:235], off
	v_max3_f32 v254, v254, v103, v104
	s_add_i32 m0, s5, 8192
	v_max3_f32 v255, v255, v119, v120
	s_waitcnt lgkmcnt(5)
	v_mfma_f32_32x32x16_bf16 v[16:31], v[224:227], v[144:147], v[16:31]
	ds_read_b128 v[224:227], v186 offset:0
	v_lshl_add_u64 v[232:233], v[232:233], 0, s[20:21]
	v_max3_f32 v254, v254, v105, v106
	global_load_lds_dwordx4 v[232:233], off
	v_max3_f32 v255, v255, v121, v122
	s_add_i32 s2, s42, 2
	v_max3_f32 v254, v254, v107, v108
	s_and_b32 s2, s2, 31
	v_max3_f32 v255, v255, v123, v124
	s_waitcnt lgkmcnt(5)
	v_mfma_f32_32x32x16_bf16 v[0:15], v[228:231], v[144:147], v[0:15]
	ds_read_b128 v[228:231], v186 offset:4096
	s_lshl_b32 s2, s2, 7
	v_max3_f32 v254, v254, v109, v110
	v_max3_f32 v255, v255, v125, v126
	v_max3_f32 v254, v254, v111, v127
	v_max_f32_e32 v254, v254, v255
	v_cmp_lt_f32_e32 vcc, 0x4138aa3b, v254
	s_add_i32 m0, s5, 114688
	v_lshl_add_u64 v[232:233], v[172:173], 0, s[2:3]
	s_waitcnt lgkmcnt(5)
	v_mfma_f32_32x32x16_bf16 v[48:63], v[208:211], v[148:151], v[48:63]
	ds_read_b128 v[208:211], v186 offset:8192
	global_load_lds_dwordx4 v[232:233], off
	s_add_i32 m0, s5, 122880
	v_lshl_add_u64 v[234:235], v[232:233], 0, s[22:23]
	global_load_lds_dwordx4 v[234:235], off
.Lattn_sp_L0:
	v_mov_b32_e32 v255, v254
	s_nop 1
	v_permlane32_swap_b32_e32 v254, v255
	v_max_f32_e32 v254, v254, v255
	v_add_f32_e32 v180, 0x4138aa3b, v175
	v_cmp_gt_f32_e32 vcc, v254, v180
	s_nop 1
	s_waitcnt lgkmcnt(5)
	v_mfma_f32_32x32x16_bf16 v[32:47], v[212:215], v[148:151], v[32:47]
	ds_read_b128 v[212:215], v186 offset:12288
	v_cndmask_b32_e32 v180, v175, v254, vcc
	v_sub_f32_e32 v255, v175, v180
	v_exp_f32_e32 v174, v255
	v_mov_b32_e32 v175, v180
	v_sub_f32_e32 v96, v96, v175
	v_sub_f32_e32 v97, v97, v175
	v_sub_f32_e32 v98, v98, v175
	s_waitcnt lgkmcnt(5)
	v_mfma_f32_32x32x16_bf16 v[16:31], v[216:219], v[148:151], v[16:31]
	ds_read_b128 v[216:219], v189 offset:0
	v_sub_f32_e32 v99, v99, v175
	v_sub_f32_e32 v100, v100, v175
	v_sub_f32_e32 v101, v101, v175
	v_sub_f32_e32 v102, v102, v175
	v_sub_f32_e32 v103, v103, v175
	v_exp_f32_e32 v96, v96
	v_exp_f32_e32 v97, v97
	s_waitcnt lgkmcnt(5)
	v_mfma_f32_32x32x16_bf16 v[0:15], v[220:223], v[148:151], v[0:15]
	ds_read_b128 v[220:223], v189 offset:4096
	v_exp_f32_e32 v98, v98
	v_exp_f32_e32 v99, v99
	v_exp_f32_e32 v100, v100
	v_exp_f32_e32 v101, v101
	v_exp_f32_e32 v102, v102
	v_exp_f32_e32 v103, v103
	s_waitcnt lgkmcnt(5)
	v_mfma_f32_32x32x16_bf16 v[48:63], v[224:227], v[152:155], v[48:63]
	ds_read_b128 v[224:227], v189 offset:8192
	v_add_f32_e32 v190, v96, v97
	v_add_f32_e32 v191, v98, v99
	v_add_f32_e32 v190, v190, v100
	v_add_f32_e32 v191, v191, v101
	v_add_f32_e32 v190, v190, v102
	v_add_f32_e32 v191, v191, v103
	s_waitcnt lgkmcnt(5)
	v_mfma_f32_32x32x16_bf16 v[32:47], v[228:231], v[152:155], v[32:47]
	ds_read_b128 v[228:231], v189 offset:12288
	v_cvt_pk_bf16_f32 v144, v96, v97
	v_cvt_pk_bf16_f32 v145, v98, v99
	v_cvt_pk_bf16_f32 v146, v100, v101
	v_cvt_pk_bf16_f32 v147, v102, v103
	v_sub_f32_e32 v104, v104, v175
	v_sub_f32_e32 v105, v105, v175
	s_waitcnt lgkmcnt(5)
	v_mfma_f32_32x32x16_bf16 v[16:31], v[208:211], v[152:155], v[16:31]
	ds_read_b128 v[208:211], v182 offset:32768
	v_sub_f32_e32 v106, v106, v175
	v_sub_f32_e32 v107, v107, v175
	v_sub_f32_e32 v108, v108, v175
	v_sub_f32_e32 v109, v109, v175
	v_sub_f32_e32 v110, v110, v175
	v_sub_f32_e32 v111, v111, v175
	s_waitcnt lgkmcnt(5)
	v_mfma_f32_32x32x16_bf16 v[0:15], v[212:215], v[152:155], v[0:15]
	ds_read_b128 v[212:215], v182 offset:36864
	v_exp_f32_e32 v104, v104
	v_exp_f32_e32 v105, v105
	v_exp_f32_e32 v106, v106
	v_exp_f32_e32 v107, v107
	v_exp_f32_e32 v108, v108
	v_exp_f32_e32 v109, v109
	s_waitcnt lgkmcnt(5)
	v_mfma_f32_32x32x16_bf16 v[48:63], v[216:219], v[156:159], v[48:63]
	ds_read_b128 v[216:219], v183 offset:32768
	v_exp_f32_e32 v110, v110
	v_exp_f32_e32 v111, v111
	v_add_f32_e32 v190, v190, v104
	v_add_f32_e32 v191, v191, v105
	v_add_f32_e32 v190, v190, v106
	v_add_f32_e32 v191, v191, v107
	s_waitcnt lgkmcnt(5)
	v_mfma_f32_32x32x16_bf16 v[32:47], v[220:223], v[156:159], v[32:47]
	ds_read_b128 v[220:223], v183 offset:36864
	v_add_f32_e32 v190, v190, v108
	v_add_f32_e32 v191, v191, v109
	v_add_f32_e32 v190, v190, v110
	v_add_f32_e32 v191, v191, v111
	v_cvt_pk_bf16_f32 v148, v104, v105
	v_cvt_pk_bf16_f32 v149, v106, v107
	s_waitcnt lgkmcnt(5)
	v_mfma_f32_32x32x16_bf16 v[16:31], v[224:227], v[156:159], v[16:31]
	ds_read_b128 v[224:227], v184 offset:32768
	v_cvt_pk_bf16_f32 v150, v108, v109
	v_cvt_pk_bf16_f32 v151, v110, v111
	v_sub_f32_e32 v112, v112, v175
	v_sub_f32_e32 v113, v113, v175
	v_sub_f32_e32 v114, v114, v175
	v_sub_f32_e32 v115, v115, v175
	s_waitcnt lgkmcnt(5)
	v_mfma_f32_32x32x16_bf16 v[0:15], v[228:231], v[156:159], v[0:15]
	ds_read_b128 v[228:231], v184 offset:36864
	v_sub_f32_e32 v116, v116, v175
	v_sub_f32_e32 v117, v117, v175
	v_sub_f32_e32 v118, v118, v175
	v_sub_f32_e32 v119, v119, v175
	v_exp_f32_e32 v112, v112
	v_exp_f32_e32 v113, v113
	s_waitcnt lgkmcnt(5)
	v_mfma_f32_32x32x16_bf16 v[64:79], v[208:211], v[128:131], 0
	ds_read_b128 v[208:211], v185 offset:32768
	v_exp_f32_e32 v114, v114
	v_exp_f32_e32 v115, v115
	v_exp_f32_e32 v116, v116
	v_exp_f32_e32 v117, v117
	v_exp_f32_e32 v118, v118
	v_exp_f32_e32 v119, v119
	s_waitcnt lgkmcnt(5)
	v_mfma_f32_32x32x16_bf16 v[80:95], v[212:215], v[128:131], 0
	ds_read_b128 v[212:215], v185 offset:36864
	v_add_f32_e32 v190, v190, v112
	v_add_f32_e32 v191, v191, v113
	v_add_f32_e32 v190, v190, v114
	v_add_f32_e32 v191, v191, v115
	v_add_f32_e32 v190, v190, v116
	v_add_f32_e32 v191, v191, v117
	s_waitcnt lgkmcnt(5)
	v_mfma_f32_32x32x16_bf16 v[64:79], v[216:219], v[132:135], v[64:79]
	ds_read_b128 v[216:219], v187 offset:16384
	v_add_f32_e32 v190, v190, v118
	v_add_f32_e32 v191, v191, v119
	v_cvt_pk_bf16_f32 v152, v112, v113
	v_cvt_pk_bf16_f32 v153, v114, v115
	v_cvt_pk_bf16_f32 v154, v116, v117
	v_cvt_pk_bf16_f32 v155, v118, v119
	s_waitcnt lgkmcnt(5)
	v_mfma_f32_32x32x16_bf16 v[80:95], v[220:223], v[132:135], v[80:95]
	ds_read_b128 v[220:223], v187 offset:20480
	v_sub_f32_e32 v120, v120, v175
	v_sub_f32_e32 v121, v121, v175
	v_sub_f32_e32 v122, v122, v175
	v_sub_f32_e32 v123, v123, v175
	v_sub_f32_e32 v124, v124, v175
	v_sub_f32_e32 v125, v125, v175
	s_waitcnt lgkmcnt(5)
	v_mfma_f32_32x32x16_bf16 v[64:79], v[224:227], v[136:139], v[64:79]
	ds_read_b128 v[224:227], v187 offset:24576
	v_sub_f32_e32 v126, v126, v175
	v_sub_f32_e32 v127, v127, v175
	v_exp_f32_e32 v120, v120
	v_exp_f32_e32 v121, v121
	v_exp_f32_e32 v122, v122
	v_exp_f32_e32 v123, v123
	s_waitcnt lgkmcnt(5)
	v_mfma_f32_32x32x16_bf16 v[80:95], v[228:231], v[136:139], v[80:95]
	ds_read_b128 v[228:231], v187 offset:28672
	v_exp_f32_e32 v124, v124
	v_exp_f32_e32 v125, v125
	v_exp_f32_e32 v126, v126
	v_exp_f32_e32 v127, v127
	v_add_f32_e32 v190, v190, v120
	v_add_f32_e32 v191, v191, v121
	s_waitcnt lgkmcnt(5)
	v_mfma_f32_32x32x16_bf16 v[64:79], v[208:211], v[140:143], v[64:79]
	ds_read_b128 v[208:211], v188 offset:16384
	v_add_f32_e32 v190, v190, v122
	v_add_f32_e32 v191, v191, v123
	v_add_f32_e32 v190, v190, v124
	v_add_f32_e32 v191, v191, v125
	v_add_f32_e32 v190, v190, v126
	v_add_f32_e32 v191, v191, v127
	s_waitcnt lgkmcnt(5)
	v_mfma_f32_32x32x16_bf16 v[80:95], v[212:215], v[140:143], v[80:95]
	ds_read_b128 v[212:215], v188 offset:20480
	v_cvt_pk_bf16_f32 v156, v120, v121
	v_cvt_pk_bf16_f32 v157, v122, v123
	v_cvt_pk_bf16_f32 v158, v124, v125
	v_cvt_pk_bf16_f32 v159, v126, v127
	v_add_f32_e32 v190, v190, v191
	v_fma_f32 v167, v167, v174, v190
	s_cbranch_vccz .Lattn_noresc_L0
	s_nop 7
	s_nop 7
	v_pk_mul_f32 v[0:1], v[0:1], v[174:175] op_sel_hi:[1,0]
	v_pk_mul_f32 v[2:3], v[2:3], v[174:175] op_sel_hi:[1,0]
	v_pk_mul_f32 v[4:5], v[4:5], v[174:175] op_sel_hi:[1,0]
	v_pk_mul_f32 v[6:7], v[6:7], v[174:175] op_sel_hi:[1,0]
	v_pk_mul_f32 v[8:9], v[8:9], v[174:175] op_sel_hi:[1,0]
	v_pk_mul_f32 v[10:11], v[10:11], v[174:175] op_sel_hi:[1,0]
	v_pk_mul_f32 v[12:13], v[12:13], v[174:175] op_sel_hi:[1,0]
	v_pk_mul_f32 v[14:15], v[14:15], v[174:175] op_sel_hi:[1,0]
	v_pk_mul_f32 v[16:17], v[16:17], v[174:175] op_sel_hi:[1,0]
	v_pk_mul_f32 v[18:19], v[18:19], v[174:175] op_sel_hi:[1,0]
	v_pk_mul_f32 v[20:21], v[20:21], v[174:175] op_sel_hi:[1,0]
	v_pk_mul_f32 v[22:23], v[22:23], v[174:175] op_sel_hi:[1,0]
	v_pk_mul_f32 v[24:25], v[24:25], v[174:175] op_sel_hi:[1,0]
	v_pk_mul_f32 v[26:27], v[26:27], v[174:175] op_sel_hi:[1,0]
	v_pk_mul_f32 v[28:29], v[28:29], v[174:175] op_sel_hi:[1,0]
	v_pk_mul_f32 v[30:31], v[30:31], v[174:175] op_sel_hi:[1,0]
	v_pk_mul_f32 v[32:33], v[32:33], v[174:175] op_sel_hi:[1,0]
	v_pk_mul_f32 v[34:35], v[34:35], v[174:175] op_sel_hi:[1,0]
	v_pk_mul_f32 v[36:37], v[36:37], v[174:175] op_sel_hi:[1,0]
	v_pk_mul_f32 v[38:39], v[38:39], v[174:175] op_sel_hi:[1,0]
	v_pk_mul_f32 v[40:41], v[40:41], v[174:175] op_sel_hi:[1,0]
	v_pk_mul_f32 v[42:43], v[42:43], v[174:175] op_sel_hi:[1,0]
	v_pk_mul_f32 v[44:45], v[44:45], v[174:175] op_sel_hi:[1,0]
	v_pk_mul_f32 v[46:47], v[46:47], v[174:175] op_sel_hi:[1,0]
	v_pk_mul_f32 v[48:49], v[48:49], v[174:175] op_sel_hi:[1,0]
	v_pk_mul_f32 v[50:51], v[50:51], v[174:175] op_sel_hi:[1,0]
	v_pk_mul_f32 v[52:53], v[52:53], v[174:175] op_sel_hi:[1,0]
	v_pk_mul_f32 v[54:55], v[54:55], v[174:175] op_sel_hi:[1,0]
	v_pk_mul_f32 v[56:57], v[56:57], v[174:175] op_sel_hi:[1,0]
	v_pk_mul_f32 v[58:59], v[58:59], v[174:175] op_sel_hi:[1,0]
	v_pk_mul_f32 v[60:61], v[60:61], v[174:175] op_sel_hi:[1,0]
	v_pk_mul_f32 v[62:63], v[62:63], v[174:175] op_sel_hi:[1,0]
	s_nop 1
.Lattn_noresc_L0:
	s_waitcnt vmcnt(4)
	s_barrier
	s_waitcnt lgkmcnt(5)
	v_mfma_f32_32x32x16_bf16 v[48:63], v[216:219], v[144:147], v[48:63]
	ds_read_b128 v[216:219], v188 offset:24576
	s_add_i32 s2, s42, 4
	v_max3_f32 v254, v64, v65, v66
	s_and_b32 s2, s2, 31
	v_max3_f32 v255, v80, v81, v82
	s_mul_i32 s2, s2, 0x44000
	v_max3_f32 v254, v254, v67, v68
	s_add_i32 m0, s5, 16384
	v_max3_f32 v255, v255, v83, v84
	s_waitcnt lgkmcnt(5)
	v_mfma_f32_32x32x16_bf16 v[32:47], v[220:223], v[144:147], v[32:47]
	ds_read_b128 v[220:223], v188 offset:28672
	v_lshl_add_u64 v[232:233], v[170:171], 0, s[2:3]
	v_max3_f32 v254, v254, v69, v70
	v_lshl_add_u64 v[234:235], v[232:233], 0, s[18:19]
	v_max3_f32 v255, v255, v85, v86
	global_load_lds_dwordx4 v[234:235], off
	v_max3_f32 v254, v254, v71, v72
	s_add_i32 m0, s5, 24576
	v_max3_f32 v255, v255, v87, v88
	s_waitcnt lgkmcnt(5)
	v_mfma_f32_32x32x16_bf16 v[16:31], v[224:227], v[144:147], v[16:31]
	ds_read_b128 v[224:227], v186 offset:16384
	v_lshl_add_u64 v[232:233], v[232:233], 0, s[20:21]
	v_max3_f32 v254, v254, v73, v74
	global_load_lds_dwordx4 v[232:233], off
	v_max3_f32 v255, v255, v89, v90
	s_add_i32 s2, s42, 3
	v_max3_f32 v254, v254, v75, v76
	s_and_b32 s2, s2, 31
	v_max3_f32 v255, v255, v91, v92
	s_waitcnt lgkmcnt(5)
	v_mfma_f32_32x32x16_bf16 v[0:15], v[228:231], v[144:147], v[0:15]
	ds_read_b128 v[228:231], v186 offset:20480
	s_lshl_b32 s2, s2, 7
	v_max3_f32 v254, v254, v77, v78
	v_max3_f32 v255, v255, v93, v94
	v_max3_f32 v254, v254, v79, v95
	v_max_f32_e32 v254, v254, v255
	v_cmp_lt_f32_e32 vcc, 0x4138aa3b, v254
	s_add_i32 m0, s5, 65536
	v_lshl_add_u64 v[232:233], v[172:173], 0, s[2:3]
	s_waitcnt lgkmcnt(5)
	v_mfma_f32_32x32x16_bf16 v[48:63], v[208:211], v[148:151], v[48:63]
	ds_read_b128 v[208:211], v186 offset:24576
	global_load_lds_dwordx4 v[232:233], off
	s_add_i32 m0, s5, 73728
	v_lshl_add_u64 v[234:235], v[232:233], 0, s[22:23]
	global_load_lds_dwordx4 v[234:235], off
.Lattn_sp_L1:
	v_mov_b32_e32 v255, v254
	s_nop 1
	v_permlane32_swap_b32_e32 v254, v255
	v_max_f32_e32 v254, v254, v255
	v_add_f32_e32 v180, 0x4138aa3b, v175
	v_cmp_gt_f32_e32 vcc, v254, v180
	s_nop 1
	s_waitcnt lgkmcnt(5)
	v_mfma_f32_32x32x16_bf16 v[32:47], v[212:215], v[148:151], v[32:47]
	ds_read_b128 v[212:215], v186 offset:28672
	v_cndmask_b32_e32 v180, v175, v254, vcc
	v_sub_f32_e32 v255, v175, v180
	v_exp_f32_e32 v174, v255
	v_mov_b32_e32 v175, v180
	v_sub_f32_e32 v64, v64, v175
	v_sub_f32_e32 v65, v65, v175
	v_sub_f32_e32 v66, v66, v175
	s_waitcnt lgkmcnt(5)
	v_mfma_f32_32x32x16_bf16 v[16:31], v[216:219], v[148:151], v[16:31]
	ds_read_b128 v[216:219], v189 offset:16384
	v_sub_f32_e32 v67, v67, v175
	v_sub_f32_e32 v68, v68, v175
	v_sub_f32_e32 v69, v69, v175
	v_sub_f32_e32 v70, v70, v175
	v_sub_f32_e32 v71, v71, v175
	v_exp_f32_e32 v64, v64
	v_exp_f32_e32 v65, v65
	s_waitcnt lgkmcnt(5)
	v_mfma_f32_32x32x16_bf16 v[0:15], v[220:223], v[148:151], v[0:15]
	ds_read_b128 v[220:223], v189 offset:20480
	v_exp_f32_e32 v66, v66
	v_exp_f32_e32 v67, v67
	v_exp_f32_e32 v68, v68
	v_exp_f32_e32 v69, v69
	v_exp_f32_e32 v70, v70
	v_exp_f32_e32 v71, v71
	s_waitcnt lgkmcnt(5)
	v_mfma_f32_32x32x16_bf16 v[48:63], v[224:227], v[152:155], v[48:63]
	ds_read_b128 v[224:227], v189 offset:24576
	v_add_f32_e32 v190, v64, v65
	v_add_f32_e32 v191, v66, v67
	v_add_f32_e32 v190, v190, v68
	v_add_f32_e32 v191, v191, v69
	v_add_f32_e32 v190, v190, v70
	v_add_f32_e32 v191, v191, v71
	s_waitcnt lgkmcnt(5)
	v_mfma_f32_32x32x16_bf16 v[32:47], v[228:231], v[152:155], v[32:47]
	ds_read_b128 v[228:231], v189 offset:28672
	v_cvt_pk_bf16_f32 v144, v64, v65
	v_cvt_pk_bf16_f32 v145, v66, v67
	v_cvt_pk_bf16_f32 v146, v68, v69
	v_cvt_pk_bf16_f32 v147, v70, v71
	v_sub_f32_e32 v72, v72, v175
	v_sub_f32_e32 v73, v73, v175
	s_waitcnt lgkmcnt(5)
	v_mfma_f32_32x32x16_bf16 v[16:31], v[208:211], v[152:155], v[16:31]
	ds_read_b128 v[208:211], v182 offset:49152
	v_sub_f32_e32 v74, v74, v175
	v_sub_f32_e32 v75, v75, v175
	v_sub_f32_e32 v76, v76, v175
	v_sub_f32_e32 v77, v77, v175
	v_sub_f32_e32 v78, v78, v175
	v_sub_f32_e32 v79, v79, v175
	s_waitcnt lgkmcnt(5)
	v_mfma_f32_32x32x16_bf16 v[0:15], v[212:215], v[152:155], v[0:15]
	ds_read_b128 v[212:215], v182 offset:53248
	v_exp_f32_e32 v72, v72
	v_exp_f32_e32 v73, v73
	v_exp_f32_e32 v74, v74
	v_exp_f32_e32 v75, v75
	v_exp_f32_e32 v76, v76
	v_exp_f32_e32 v77, v77
	s_waitcnt lgkmcnt(5)
	v_mfma_f32_32x32x16_bf16 v[48:63], v[216:219], v[156:159], v[48:63]
	ds_read_b128 v[216:219], v183 offset:49152
	v_exp_f32_e32 v78, v78
	v_exp_f32_e32 v79, v79
	v_add_f32_e32 v190, v190, v72
	v_add_f32_e32 v191, v191, v73
	v_add_f32_e32 v190, v190, v74
	v_add_f32_e32 v191, v191, v75
	s_waitcnt lgkmcnt(5)
	v_mfma_f32_32x32x16_bf16 v[32:47], v[220:223], v[156:159], v[32:47]
	ds_read_b128 v[220:223], v183 offset:53248
	v_add_f32_e32 v190, v190, v76
	v_add_f32_e32 v191, v191, v77
	v_add_f32_e32 v190, v190, v78
	v_add_f32_e32 v191, v191, v79
	v_cvt_pk_bf16_f32 v148, v72, v73
	v_cvt_pk_bf16_f32 v149, v74, v75
	s_waitcnt lgkmcnt(5)
	v_mfma_f32_32x32x16_bf16 v[16:31], v[224:227], v[156:159], v[16:31]
	ds_read_b128 v[224:227], v184 offset:49152
	v_cvt_pk_bf16_f32 v150, v76, v77
	v_cvt_pk_bf16_f32 v151, v78, v79
	v_sub_f32_e32 v80, v80, v175
	v_sub_f32_e32 v81, v81, v175
	v_sub_f32_e32 v82, v82, v175
	v_sub_f32_e32 v83, v83, v175
	s_waitcnt lgkmcnt(5)
	v_mfma_f32_32x32x16_bf16 v[0:15], v[228:231], v[156:159], v[0:15]
	ds_read_b128 v[228:231], v184 offset:53248
	v_sub_f32_e32 v84, v84, v175
	v_sub_f32_e32 v85, v85, v175
	v_sub_f32_e32 v86, v86, v175
	v_sub_f32_e32 v87, v87, v175
	v_exp_f32_e32 v80, v80
	v_exp_f32_e32 v81, v81
	s_waitcnt lgkmcnt(5)
	v_mfma_f32_32x32x16_bf16 v[96:111], v[208:211], v[128:131], 0
	ds_read_b128 v[208:211], v185 offset:49152
	v_exp_f32_e32 v82, v82
	v_exp_f32_e32 v83, v83
	v_exp_f32_e32 v84, v84
	v_exp_f32_e32 v85, v85
	v_exp_f32_e32 v86, v86
	v_exp_f32_e32 v87, v87
	s_waitcnt lgkmcnt(5)
	v_mfma_f32_32x32x16_bf16 v[112:127], v[212:215], v[128:131], 0
	ds_read_b128 v[212:215], v185 offset:53248
	v_add_f32_e32 v190, v190, v80
	v_add_f32_e32 v191, v191, v81
	v_add_f32_e32 v190, v190, v82
	v_add_f32_e32 v191, v191, v83
	v_add_f32_e32 v190, v190, v84
	v_add_f32_e32 v191, v191, v85
	s_waitcnt lgkmcnt(5)
	v_mfma_f32_32x32x16_bf16 v[96:111], v[216:219], v[132:135], v[96:111]
	ds_read_b128 v[216:219], v187 offset:32768
	v_add_f32_e32 v190, v190, v86
	v_add_f32_e32 v191, v191, v87
	v_cvt_pk_bf16_f32 v152, v80, v81
	v_cvt_pk_bf16_f32 v153, v82, v83
	v_cvt_pk_bf16_f32 v154, v84, v85
	v_cvt_pk_bf16_f32 v155, v86, v87
	s_waitcnt lgkmcnt(5)
	v_mfma_f32_32x32x16_bf16 v[112:127], v[220:223], v[132:135], v[112:127]
	ds_read_b128 v[220:223], v187 offset:36864
	v_sub_f32_e32 v88, v88, v175
	v_sub_f32_e32 v89, v89, v175
	v_sub_f32_e32 v90, v90, v175
	v_sub_f32_e32 v91, v91, v175
	v_sub_f32_e32 v92, v92, v175
	v_sub_f32_e32 v93, v93, v175
	s_waitcnt lgkmcnt(5)
	v_mfma_f32_32x32x16_bf16 v[96:111], v[224:227], v[136:139], v[96:111]
	ds_read_b128 v[224:227], v187 offset:40960
	v_sub_f32_e32 v94, v94, v175
	v_sub_f32_e32 v95, v95, v175
	v_exp_f32_e32 v88, v88
	v_exp_f32_e32 v89, v89
	v_exp_f32_e32 v90, v90
	v_exp_f32_e32 v91, v91
	s_waitcnt lgkmcnt(5)
	v_mfma_f32_32x32x16_bf16 v[112:127], v[228:231], v[136:139], v[112:127]
	ds_read_b128 v[228:231], v187 offset:45056
	v_exp_f32_e32 v92, v92
	v_exp_f32_e32 v93, v93
	v_exp_f32_e32 v94, v94
	v_exp_f32_e32 v95, v95
	v_add_f32_e32 v190, v190, v88
	v_add_f32_e32 v191, v191, v89
	s_waitcnt lgkmcnt(5)
	v_mfma_f32_32x32x16_bf16 v[96:111], v[208:211], v[140:143], v[96:111]
	ds_read_b128 v[208:211], v188 offset:32768
	v_add_f32_e32 v190, v190, v90
	v_add_f32_e32 v191, v191, v91
	v_add_f32_e32 v190, v190, v92
	v_add_f32_e32 v191, v191, v93
	v_add_f32_e32 v190, v190, v94
	v_add_f32_e32 v191, v191, v95
	s_waitcnt lgkmcnt(5)
	v_mfma_f32_32x32x16_bf16 v[112:127], v[212:215], v[140:143], v[112:127]
	ds_read_b128 v[212:215], v188 offset:36864
	v_cvt_pk_bf16_f32 v156, v88, v89
	v_cvt_pk_bf16_f32 v157, v90, v91
	v_cvt_pk_bf16_f32 v158, v92, v93
	v_cvt_pk_bf16_f32 v159, v94, v95
	v_add_f32_e32 v190, v190, v191
	v_fma_f32 v167, v167, v174, v190
	s_cbranch_vccz .Lattn_noresc_L1
	s_nop 7
	s_nop 7
	v_pk_mul_f32 v[0:1], v[0:1], v[174:175] op_sel_hi:[1,0]
	v_pk_mul_f32 v[2:3], v[2:3], v[174:175] op_sel_hi:[1,0]
	v_pk_mul_f32 v[4:5], v[4:5], v[174:175] op_sel_hi:[1,0]
	v_pk_mul_f32 v[6:7], v[6:7], v[174:175] op_sel_hi:[1,0]
	v_pk_mul_f32 v[8:9], v[8:9], v[174:175] op_sel_hi:[1,0]
	v_pk_mul_f32 v[10:11], v[10:11], v[174:175] op_sel_hi:[1,0]
	v_pk_mul_f32 v[12:13], v[12:13], v[174:175] op_sel_hi:[1,0]
	v_pk_mul_f32 v[14:15], v[14:15], v[174:175] op_sel_hi:[1,0]
	v_pk_mul_f32 v[16:17], v[16:17], v[174:175] op_sel_hi:[1,0]
	v_pk_mul_f32 v[18:19], v[18:19], v[174:175] op_sel_hi:[1,0]
	v_pk_mul_f32 v[20:21], v[20:21], v[174:175] op_sel_hi:[1,0]
	v_pk_mul_f32 v[22:23], v[22:23], v[174:175] op_sel_hi:[1,0]
	v_pk_mul_f32 v[24:25], v[24:25], v[174:175] op_sel_hi:[1,0]
	v_pk_mul_f32 v[26:27], v[26:27], v[174:175] op_sel_hi:[1,0]
	v_pk_mul_f32 v[28:29], v[28:29], v[174:175] op_sel_hi:[1,0]
	v_pk_mul_f32 v[30:31], v[30:31], v[174:175] op_sel_hi:[1,0]
	v_pk_mul_f32 v[32:33], v[32:33], v[174:175] op_sel_hi:[1,0]
	v_pk_mul_f32 v[34:35], v[34:35], v[174:175] op_sel_hi:[1,0]
	v_pk_mul_f32 v[36:37], v[36:37], v[174:175] op_sel_hi:[1,0]
	v_pk_mul_f32 v[38:39], v[38:39], v[174:175] op_sel_hi:[1,0]
	v_pk_mul_f32 v[40:41], v[40:41], v[174:175] op_sel_hi:[1,0]
	v_pk_mul_f32 v[42:43], v[42:43], v[174:175] op_sel_hi:[1,0]
	v_pk_mul_f32 v[44:45], v[44:45], v[174:175] op_sel_hi:[1,0]
	v_pk_mul_f32 v[46:47], v[46:47], v[174:175] op_sel_hi:[1,0]
	v_pk_mul_f32 v[48:49], v[48:49], v[174:175] op_sel_hi:[1,0]
	v_pk_mul_f32 v[50:51], v[50:51], v[174:175] op_sel_hi:[1,0]
	v_pk_mul_f32 v[52:53], v[52:53], v[174:175] op_sel_hi:[1,0]
	v_pk_mul_f32 v[54:55], v[54:55], v[174:175] op_sel_hi:[1,0]
	v_pk_mul_f32 v[56:57], v[56:57], v[174:175] op_sel_hi:[1,0]
	v_pk_mul_f32 v[58:59], v[58:59], v[174:175] op_sel_hi:[1,0]
	v_pk_mul_f32 v[60:61], v[60:61], v[174:175] op_sel_hi:[1,0]
	v_pk_mul_f32 v[62:63], v[62:63], v[174:175] op_sel_hi:[1,0]
	s_nop 1
.Lattn_noresc_L1:
	s_waitcnt vmcnt(4)
	s_barrier
	s_waitcnt lgkmcnt(5)
	v_mfma_f32_32x32x16_bf16 v[48:63], v[216:219], v[144:147], v[48:63]
	ds_read_b128 v[216:219], v188 offset:40960
	s_add_i32 s2, s42, 5
	v_max3_f32 v254, v96, v97, v98
	s_and_b32 s2, s2, 31
	v_max3_f32 v255, v112, v113, v114
	s_mul_i32 s2, s2, 0x44000
	v_max3_f32 v254, v254, v99, v100
	s_add_i32 m0, s5, 32768
	v_max3_f32 v255, v255, v115, v116
	s_waitcnt lgkmcnt(5)
	v_mfma_f32_32x32x16_bf16 v[32:47], v[220:223], v[144:147], v[32:47]
	ds_read_b128 v[220:223], v188 offset:45056
	v_lshl_add_u64 v[232:233], v[170:171], 0, s[2:3]
	v_max3_f32 v254, v254, v101, v102
	v_lshl_add_u64 v[234:235], v[232:233], 0, s[18:19]
	v_max3_f32 v255, v255, v117, v118
	global_load_lds_dwordx4 v[234:235], off
	v_max3_f32 v254, v254, v103, v104
	s_add_i32 m0, s5, 40960
	v_max3_f32 v255, v255, v119, v120
	s_waitcnt lgkmcnt(5)
	v_mfma_f32_32x32x16_bf16 v[16:31], v[224:227], v[144:147], v[16:31]
	ds_read_b128 v[224:227], v186 offset:32768
	v_lshl_add_u64 v[232:233], v[232:233], 0, s[20:21]
	v_max3_f32 v254, v254, v105, v106
	global_load_lds_dwordx4 v[232:233], off
	v_max3_f32 v255, v255, v121, v122
	s_add_i32 s2, s42, 4
	v_max3_f32 v254, v254, v107, v108
	s_and_b32 s2, s2, 31
	v_max3_f32 v255, v255, v123, v124
	s_waitcnt lgkmcnt(5)
	v_mfma_f32_32x32x16_bf16 v[0:15], v[228:231], v[144:147], v[0:15]
	ds_read_b128 v[228:231], v186 offset:36864
	s_lshl_b32 s2, s2, 7
	v_max3_f32 v254, v254, v109, v110
	v_max3_f32 v255, v255, v125, v126
	v_max3_f32 v254, v254, v111, v127
	v_max_f32_e32 v254, v254, v255
	v_cmp_lt_f32_e32 vcc, 0x4138aa3b, v254
	s_add_i32 m0, s5, 81920
	v_lshl_add_u64 v[232:233], v[172:173], 0, s[2:3]
	s_waitcnt lgkmcnt(5)
	v_mfma_f32_32x32x16_bf16 v[48:63], v[208:211], v[148:151], v[48:63]
	ds_read_b128 v[208:211], v186 offset:40960
	global_load_lds_dwordx4 v[232:233], off
	s_add_i32 m0, s5, 90112
	v_lshl_add_u64 v[234:235], v[232:233], 0, s[22:23]
	global_load_lds_dwordx4 v[234:235], off
.Lattn_sp_L2:
	v_mov_b32_e32 v255, v254
	s_nop 1
	v_permlane32_swap_b32_e32 v254, v255
	v_max_f32_e32 v254, v254, v255
	v_add_f32_e32 v180, 0x4138aa3b, v175
	v_cmp_gt_f32_e32 vcc, v254, v180
	s_nop 1
	s_waitcnt lgkmcnt(5)
	v_mfma_f32_32x32x16_bf16 v[32:47], v[212:215], v[148:151], v[32:47]
	ds_read_b128 v[212:215], v186 offset:45056
	v_cndmask_b32_e32 v180, v175, v254, vcc
	v_sub_f32_e32 v255, v175, v180
	v_exp_f32_e32 v174, v255
	v_mov_b32_e32 v175, v180
	v_sub_f32_e32 v96, v96, v175
	v_sub_f32_e32 v97, v97, v175
	v_sub_f32_e32 v98, v98, v175
	s_waitcnt lgkmcnt(5)
	v_mfma_f32_32x32x16_bf16 v[16:31], v[216:219], v[148:151], v[16:31]
	ds_read_b128 v[216:219], v189 offset:32768
	v_sub_f32_e32 v99, v99, v175
	v_sub_f32_e32 v100, v100, v175
	v_sub_f32_e32 v101, v101, v175
	v_sub_f32_e32 v102, v102, v175
	v_sub_f32_e32 v103, v103, v175
	v_exp_f32_e32 v96, v96
	v_exp_f32_e32 v97, v97
	s_waitcnt lgkmcnt(5)
	v_mfma_f32_32x32x16_bf16 v[0:15], v[220:223], v[148:151], v[0:15]
	ds_read_b128 v[220:223], v189 offset:36864
	v_exp_f32_e32 v98, v98
	v_exp_f32_e32 v99, v99
	v_exp_f32_e32 v100, v100
	v_exp_f32_e32 v101, v101
	v_exp_f32_e32 v102, v102
	v_exp_f32_e32 v103, v103
	s_waitcnt lgkmcnt(5)
	v_mfma_f32_32x32x16_bf16 v[48:63], v[224:227], v[152:155], v[48:63]
	ds_read_b128 v[224:227], v189 offset:40960
	v_add_f32_e32 v190, v96, v97
	v_add_f32_e32 v191, v98, v99
	v_add_f32_e32 v190, v190, v100
	v_add_f32_e32 v191, v191, v101
	v_add_f32_e32 v190, v190, v102
	v_add_f32_e32 v191, v191, v103
	s_waitcnt lgkmcnt(5)
	v_mfma_f32_32x32x16_bf16 v[32:47], v[228:231], v[152:155], v[32:47]
	ds_read_b128 v[228:231], v189 offset:45056
	v_cvt_pk_bf16_f32 v144, v96, v97
	v_cvt_pk_bf16_f32 v145, v98, v99
	v_cvt_pk_bf16_f32 v146, v100, v101
	v_cvt_pk_bf16_f32 v147, v102, v103
	v_sub_f32_e32 v104, v104, v175
	v_sub_f32_e32 v105, v105, v175
	s_waitcnt lgkmcnt(5)
	v_mfma_f32_32x32x16_bf16 v[16:31], v[208:211], v[152:155], v[16:31]
	ds_read_b128 v[208:211], v182 offset:0
	v_sub_f32_e32 v106, v106, v175
	v_sub_f32_e32 v107, v107, v175
	v_sub_f32_e32 v108, v108, v175
	v_sub_f32_e32 v109, v109, v175
	v_sub_f32_e32 v110, v110, v175
	v_sub_f32_e32 v111, v111, v175
	s_waitcnt lgkmcnt(5)
	v_mfma_f32_32x32x16_bf16 v[0:15], v[212:215], v[152:155], v[0:15]
	ds_read_b128 v[212:215], v182 offset:4096
	v_exp_f32_e32 v104, v104
	v_exp_f32_e32 v105, v105
	v_exp_f32_e32 v106, v106
	v_exp_f32_e32 v107, v107
	v_exp_f32_e32 v108, v108
	v_exp_f32_e32 v109, v109
	s_waitcnt lgkmcnt(5)
	v_mfma_f32_32x32x16_bf16 v[48:63], v[216:219], v[156:159], v[48:63]
	ds_read_b128 v[216:219], v183 offset:0
	v_exp_f32_e32 v110, v110
	v_exp_f32_e32 v111, v111
	v_add_f32_e32 v190, v190, v104
	v_add_f32_e32 v191, v191, v105
	v_add_f32_e32 v190, v190, v106
	v_add_f32_e32 v191, v191, v107
	s_waitcnt lgkmcnt(5)
	v_mfma_f32_32x32x16_bf16 v[32:47], v[220:223], v[156:159], v[32:47]
	ds_read_b128 v[220:223], v183 offset:4096
	v_add_f32_e32 v190, v190, v108
	v_add_f32_e32 v191, v191, v109
	v_add_f32_e32 v190, v190, v110
	v_add_f32_e32 v191, v191, v111
	v_cvt_pk_bf16_f32 v148, v104, v105
	v_cvt_pk_bf16_f32 v149, v106, v107
	s_waitcnt lgkmcnt(5)
	v_mfma_f32_32x32x16_bf16 v[16:31], v[224:227], v[156:159], v[16:31]
	ds_read_b128 v[224:227], v184 offset:0
	v_cvt_pk_bf16_f32 v150, v108, v109
	v_cvt_pk_bf16_f32 v151, v110, v111
	v_sub_f32_e32 v112, v112, v175
	v_sub_f32_e32 v113, v113, v175
	v_sub_f32_e32 v114, v114, v175
	v_sub_f32_e32 v115, v115, v175
	s_waitcnt lgkmcnt(5)
	v_mfma_f32_32x32x16_bf16 v[0:15], v[228:231], v[156:159], v[0:15]
	ds_read_b128 v[228:231], v184 offset:4096
	v_sub_f32_e32 v116, v116, v175
	v_sub_f32_e32 v117, v117, v175
	v_sub_f32_e32 v118, v118, v175
	v_sub_f32_e32 v119, v119, v175
	v_exp_f32_e32 v112, v112
	v_exp_f32_e32 v113, v113
	s_waitcnt lgkmcnt(5)
	v_mfma_f32_32x32x16_bf16 v[64:79], v[208:211], v[128:131], 0
	ds_read_b128 v[208:211], v185 offset:0
	v_exp_f32_e32 v114, v114
	v_exp_f32_e32 v115, v115
	v_exp_f32_e32 v116, v116
	v_exp_f32_e32 v117, v117
	v_exp_f32_e32 v118, v118
	v_exp_f32_e32 v119, v119
	s_waitcnt lgkmcnt(5)
	v_mfma_f32_32x32x16_bf16 v[80:95], v[212:215], v[128:131], 0
	ds_read_b128 v[212:215], v185 offset:4096
	v_add_f32_e32 v190, v190, v112
	v_add_f32_e32 v191, v191, v113
	v_add_f32_e32 v190, v190, v114
	v_add_f32_e32 v191, v191, v115
	v_add_f32_e32 v190, v190, v116
	v_add_f32_e32 v191, v191, v117
	s_waitcnt lgkmcnt(5)
	v_mfma_f32_32x32x16_bf16 v[64:79], v[216:219], v[132:135], v[64:79]
	ds_read_b128 v[216:219], v187 offset:49152
	v_add_f32_e32 v190, v190, v118
	v_add_f32_e32 v191, v191, v119
	v_cvt_pk_bf16_f32 v152, v112, v113
	v_cvt_pk_bf16_f32 v153, v114, v115
	v_cvt_pk_bf16_f32 v154, v116, v117
	v_cvt_pk_bf16_f32 v155, v118, v119
	s_waitcnt lgkmcnt(5)
	v_mfma_f32_32x32x16_bf16 v[80:95], v[220:223], v[132:135], v[80:95]
	ds_read_b128 v[220:223], v187 offset:53248
	v_sub_f32_e32 v120, v120, v175
	v_sub_f32_e32 v121, v121, v175
	v_sub_f32_e32 v122, v122, v175
	v_sub_f32_e32 v123, v123, v175
	v_sub_f32_e32 v124, v124, v175
	v_sub_f32_e32 v125, v125, v175
	s_waitcnt lgkmcnt(5)
	v_mfma_f32_32x32x16_bf16 v[64:79], v[224:227], v[136:139], v[64:79]
	ds_read_b128 v[224:227], v187 offset:57344
	v_sub_f32_e32 v126, v126, v175
	v_sub_f32_e32 v127, v127, v175
	v_exp_f32_e32 v120, v120
	v_exp_f32_e32 v121, v121
	v_exp_f32_e32 v122, v122
	v_exp_f32_e32 v123, v123
	s_waitcnt lgkmcnt(5)
	v_mfma_f32_32x32x16_bf16 v[80:95], v[228:231], v[136:139], v[80:95]
	ds_read_b128 v[228:231], v187 offset:61440
	v_exp_f32_e32 v124, v124
	v_exp_f32_e32 v125, v125
	v_exp_f32_e32 v126, v126
	v_exp_f32_e32 v127, v127
	v_add_f32_e32 v190, v190, v120
	v_add_f32_e32 v191, v191, v121
	s_waitcnt lgkmcnt(5)
	v_mfma_f32_32x32x16_bf16 v[64:79], v[208:211], v[140:143], v[64:79]
	ds_read_b128 v[208:211], v188 offset:49152
	v_add_f32_e32 v190, v190, v122
	v_add_f32_e32 v191, v191, v123
	v_add_f32_e32 v190, v190, v124
	v_add_f32_e32 v191, v191, v125
	v_add_f32_e32 v190, v190, v126
	v_add_f32_e32 v191, v191, v127
	s_waitcnt lgkmcnt(5)
	v_mfma_f32_32x32x16_bf16 v[80:95], v[212:215], v[140:143], v[80:95]
	ds_read_b128 v[212:215], v188 offset:53248
	v_cvt_pk_bf16_f32 v156, v120, v121
	v_cvt_pk_bf16_f32 v157, v122, v123
	v_cvt_pk_bf16_f32 v158, v124, v125
	v_cvt_pk_bf16_f32 v159, v126, v127
	v_add_f32_e32 v190, v190, v191
	v_fma_f32 v167, v167, v174, v190
	s_cbranch_vccz .Lattn_noresc_L2
	s_nop 7
	s_nop 7
	v_pk_mul_f32 v[0:1], v[0:1], v[174:175] op_sel_hi:[1,0]
	v_pk_mul_f32 v[2:3], v[2:3], v[174:175] op_sel_hi:[1,0]
	v_pk_mul_f32 v[4:5], v[4:5], v[174:175] op_sel_hi:[1,0]
	v_pk_mul_f32 v[6:7], v[6:7], v[174:175] op_sel_hi:[1,0]
	v_pk_mul_f32 v[8:9], v[8:9], v[174:175] op_sel_hi:[1,0]
	v_pk_mul_f32 v[10:11], v[10:11], v[174:175] op_sel_hi:[1,0]
	v_pk_mul_f32 v[12:13], v[12:13], v[174:175] op_sel_hi:[1,0]
	v_pk_mul_f32 v[14:15], v[14:15], v[174:175] op_sel_hi:[1,0]
	v_pk_mul_f32 v[16:17], v[16:17], v[174:175] op_sel_hi:[1,0]
	v_pk_mul_f32 v[18:19], v[18:19], v[174:175] op_sel_hi:[1,0]
	v_pk_mul_f32 v[20:21], v[20:21], v[174:175] op_sel_hi:[1,0]
	v_pk_mul_f32 v[22:23], v[22:23], v[174:175] op_sel_hi:[1,0]
	v_pk_mul_f32 v[24:25], v[24:25], v[174:175] op_sel_hi:[1,0]
	v_pk_mul_f32 v[26:27], v[26:27], v[174:175] op_sel_hi:[1,0]
	v_pk_mul_f32 v[28:29], v[28:29], v[174:175] op_sel_hi:[1,0]
	v_pk_mul_f32 v[30:31], v[30:31], v[174:175] op_sel_hi:[1,0]
	v_pk_mul_f32 v[32:33], v[32:33], v[174:175] op_sel_hi:[1,0]
	v_pk_mul_f32 v[34:35], v[34:35], v[174:175] op_sel_hi:[1,0]
	v_pk_mul_f32 v[36:37], v[36:37], v[174:175] op_sel_hi:[1,0]
	v_pk_mul_f32 v[38:39], v[38:39], v[174:175] op_sel_hi:[1,0]
	v_pk_mul_f32 v[40:41], v[40:41], v[174:175] op_sel_hi:[1,0]
	v_pk_mul_f32 v[42:43], v[42:43], v[174:175] op_sel_hi:[1,0]
	v_pk_mul_f32 v[44:45], v[44:45], v[174:175] op_sel_hi:[1,0]
	v_pk_mul_f32 v[46:47], v[46:47], v[174:175] op_sel_hi:[1,0]
	v_pk_mul_f32 v[48:49], v[48:49], v[174:175] op_sel_hi:[1,0]
	v_pk_mul_f32 v[50:51], v[50:51], v[174:175] op_sel_hi:[1,0]
	v_pk_mul_f32 v[52:53], v[52:53], v[174:175] op_sel_hi:[1,0]
	v_pk_mul_f32 v[54:55], v[54:55], v[174:175] op_sel_hi:[1,0]
	v_pk_mul_f32 v[56:57], v[56:57], v[174:175] op_sel_hi:[1,0]
	v_pk_mul_f32 v[58:59], v[58:59], v[174:175] op_sel_hi:[1,0]
	v_pk_mul_f32 v[60:61], v[60:61], v[174:175] op_sel_hi:[1,0]
	v_pk_mul_f32 v[62:63], v[62:63], v[174:175] op_sel_hi:[1,0]
	s_nop 1
.Lattn_noresc_L2:
	s_waitcnt vmcnt(4)
	s_barrier
	s_waitcnt lgkmcnt(5)
	v_mfma_f32_32x32x16_bf16 v[48:63], v[216:219], v[144:147], v[48:63]
	ds_read_b128 v[216:219], v188 offset:57344
	s_add_i32 s2, s42, 6
	v_max3_f32 v254, v64, v65, v66
	s_and_b32 s2, s2, 31
	v_max3_f32 v255, v80, v81, v82
	s_mul_i32 s2, s2, 0x44000
	v_max3_f32 v254, v254, v67, v68
	s_add_i32 m0, s5, 49152
	v_max3_f32 v255, v255, v83, v84
	s_waitcnt lgkmcnt(5)
	v_mfma_f32_32x32x16_bf16 v[32:47], v[220:223], v[144:147], v[32:47]
	ds_read_b128 v[220:223], v188 offset:61440
	v_lshl_add_u64 v[232:233], v[170:171], 0, s[2:3]
	v_max3_f32 v254, v254, v69, v70
	v_lshl_add_u64 v[234:235], v[232:233], 0, s[18:19]
	v_max3_f32 v255, v255, v85, v86
	global_load_lds_dwordx4 v[234:235], off
	v_max3_f32 v254, v254, v71, v72
	s_add_i32 m0, s5, 57344
	v_max3_f32 v255, v255, v87, v88
	s_waitcnt lgkmcnt(5)
	v_mfma_f32_32x32x16_bf16 v[16:31], v[224:227], v[144:147], v[16:31]
	ds_read_b128 v[224:227], v186 offset:49152
	v_lshl_add_u64 v[232:233], v[232:233], 0, s[20:21]
	v_max3_f32 v254, v254, v73, v74
	global_load_lds_dwordx4 v[232:233], off
	v_max3_f32 v255, v255, v89, v90
	s_add_i32 s2, s42, 5
	v_max3_f32 v254, v254, v75, v76
	s_and_b32 s2, s2, 31
	v_max3_f32 v255, v255, v91, v92
	s_waitcnt lgkmcnt(5)
	v_mfma_f32_32x32x16_bf16 v[0:15], v[228:231], v[144:147], v[0:15]
	ds_read_b128 v[228:231], v186 offset:53248
	s_lshl_b32 s2, s2, 7
	v_max3_f32 v254, v254, v77, v78
	v_max3_f32 v255, v255, v93, v94
	v_max3_f32 v254, v254, v79, v95
	v_max_f32_e32 v254, v254, v255
	v_cmp_lt_f32_e32 vcc, 0x4138aa3b, v254
	s_add_i32 m0, s5, 98304
	v_lshl_add_u64 v[232:233], v[172:173], 0, s[2:3]
	s_waitcnt lgkmcnt(5)
	v_mfma_f32_32x32x16_bf16 v[48:63], v[208:211], v[148:151], v[48:63]
	ds_read_b128 v[208:211], v186 offset:57344
	global_load_lds_dwordx4 v[232:233], off
	s_add_i32 m0, s5, 106496
	v_lshl_add_u64 v[234:235], v[232:233], 0, s[22:23]
	global_load_lds_dwordx4 v[234:235], off
.Lattn_sp_L3:
	v_mov_b32_e32 v255, v254
	s_nop 1
	v_permlane32_swap_b32_e32 v254, v255
	v_max_f32_e32 v254, v254, v255
	v_add_f32_e32 v180, 0x4138aa3b, v175
	v_cmp_gt_f32_e32 vcc, v254, v180
	s_nop 1
	s_waitcnt lgkmcnt(5)
	v_mfma_f32_32x32x16_bf16 v[32:47], v[212:215], v[148:151], v[32:47]
	ds_read_b128 v[212:215], v186 offset:61440
	v_cndmask_b32_e32 v180, v175, v254, vcc
	v_sub_f32_e32 v255, v175, v180
	v_exp_f32_e32 v174, v255
	v_mov_b32_e32 v175, v180
	v_sub_f32_e32 v64, v64, v175
	v_sub_f32_e32 v65, v65, v175
	v_sub_f32_e32 v66, v66, v175
	s_waitcnt lgkmcnt(5)
	v_mfma_f32_32x32x16_bf16 v[16:31], v[216:219], v[148:151], v[16:31]
	ds_read_b128 v[216:219], v189 offset:49152
	v_sub_f32_e32 v67, v67, v175
	v_sub_f32_e32 v68, v68, v175
	v_sub_f32_e32 v69, v69, v175
	v_sub_f32_e32 v70, v70, v175
	v_sub_f32_e32 v71, v71, v175
	v_exp_f32_e32 v64, v64
	v_exp_f32_e32 v65, v65
	s_waitcnt lgkmcnt(5)
	v_mfma_f32_32x32x16_bf16 v[0:15], v[220:223], v[148:151], v[0:15]
	ds_read_b128 v[220:223], v189 offset:53248
	v_exp_f32_e32 v66, v66
	v_exp_f32_e32 v67, v67
	v_exp_f32_e32 v68, v68
	v_exp_f32_e32 v69, v69
	v_exp_f32_e32 v70, v70
	v_exp_f32_e32 v71, v71
	s_waitcnt lgkmcnt(5)
	v_mfma_f32_32x32x16_bf16 v[48:63], v[224:227], v[152:155], v[48:63]
	ds_read_b128 v[224:227], v189 offset:57344
	v_add_f32_e32 v190, v64, v65
	v_add_f32_e32 v191, v66, v67
	v_add_f32_e32 v190, v190, v68
	v_add_f32_e32 v191, v191, v69
	v_add_f32_e32 v190, v190, v70
	v_add_f32_e32 v191, v191, v71
	s_waitcnt lgkmcnt(5)
	v_mfma_f32_32x32x16_bf16 v[32:47], v[228:231], v[152:155], v[32:47]
	ds_read_b128 v[228:231], v189 offset:61440
	v_cvt_pk_bf16_f32 v144, v64, v65
	v_cvt_pk_bf16_f32 v145, v66, v67
	v_cvt_pk_bf16_f32 v146, v68, v69
	v_cvt_pk_bf16_f32 v147, v70, v71
	v_sub_f32_e32 v72, v72, v175
	v_sub_f32_e32 v73, v73, v175
	s_waitcnt lgkmcnt(5)
	v_mfma_f32_32x32x16_bf16 v[16:31], v[208:211], v[152:155], v[16:31]
	ds_read_b128 v[208:211], v182 offset:16384
	v_sub_f32_e32 v74, v74, v175
	v_sub_f32_e32 v75, v75, v175
	v_sub_f32_e32 v76, v76, v175
	v_sub_f32_e32 v77, v77, v175
	v_sub_f32_e32 v78, v78, v175
	v_sub_f32_e32 v79, v79, v175
	s_waitcnt lgkmcnt(5)
	v_mfma_f32_32x32x16_bf16 v[0:15], v[212:215], v[152:155], v[0:15]
	ds_read_b128 v[212:215], v182 offset:20480
	v_exp_f32_e32 v72, v72
	v_exp_f32_e32 v73, v73
	v_exp_f32_e32 v74, v74
	v_exp_f32_e32 v75, v75
	v_exp_f32_e32 v76, v76
	v_exp_f32_e32 v77, v77
	s_waitcnt lgkmcnt(5)
	v_mfma_f32_32x32x16_bf16 v[48:63], v[216:219], v[156:159], v[48:63]
	ds_read_b128 v[216:219], v183 offset:16384
	v_exp_f32_e32 v78, v78
	v_exp_f32_e32 v79, v79
	v_add_f32_e32 v190, v190, v72
	v_add_f32_e32 v191, v191, v73
	v_add_f32_e32 v190, v190, v74
	v_add_f32_e32 v191, v191, v75
	s_waitcnt lgkmcnt(5)
	v_mfma_f32_32x32x16_bf16 v[32:47], v[220:223], v[156:159], v[32:47]
	ds_read_b128 v[220:223], v183 offset:20480
	v_add_f32_e32 v190, v190, v76
	v_add_f32_e32 v191, v191, v77
	v_add_f32_e32 v190, v190, v78
	v_add_f32_e32 v191, v191, v79
	v_cvt_pk_bf16_f32 v148, v72, v73
	v_cvt_pk_bf16_f32 v149, v74, v75
	s_waitcnt lgkmcnt(5)
	v_mfma_f32_32x32x16_bf16 v[16:31], v[224:227], v[156:159], v[16:31]
	ds_read_b128 v[224:227], v184 offset:16384
	v_cvt_pk_bf16_f32 v150, v76, v77
	v_cvt_pk_bf16_f32 v151, v78, v79
	v_sub_f32_e32 v80, v80, v175
	v_sub_f32_e32 v81, v81, v175
	v_sub_f32_e32 v82, v82, v175
	v_sub_f32_e32 v83, v83, v175
	s_waitcnt lgkmcnt(5)
	v_mfma_f32_32x32x16_bf16 v[0:15], v[228:231], v[156:159], v[0:15]
	ds_read_b128 v[228:231], v184 offset:20480
	v_sub_f32_e32 v84, v84, v175
	v_sub_f32_e32 v85, v85, v175
	v_sub_f32_e32 v86, v86, v175
	v_sub_f32_e32 v87, v87, v175
	v_exp_f32_e32 v80, v80
	v_exp_f32_e32 v81, v81
	s_waitcnt lgkmcnt(5)
	v_mfma_f32_32x32x16_bf16 v[96:111], v[208:211], v[128:131], 0
	ds_read_b128 v[208:211], v185 offset:16384
	v_exp_f32_e32 v82, v82
	v_exp_f32_e32 v83, v83
	v_exp_f32_e32 v84, v84
	v_exp_f32_e32 v85, v85
	v_exp_f32_e32 v86, v86
	v_exp_f32_e32 v87, v87
	s_waitcnt lgkmcnt(5)
	v_mfma_f32_32x32x16_bf16 v[112:127], v[212:215], v[128:131], 0
	ds_read_b128 v[212:215], v185 offset:20480
	v_add_f32_e32 v190, v190, v80
	v_add_f32_e32 v191, v191, v81
	v_add_f32_e32 v190, v190, v82
	v_add_f32_e32 v191, v191, v83
	v_add_f32_e32 v190, v190, v84
	v_add_f32_e32 v191, v191, v85
	s_waitcnt lgkmcnt(5)
	v_mfma_f32_32x32x16_bf16 v[96:111], v[216:219], v[132:135], v[96:111]
	ds_read_b128 v[216:219], v187 offset:0
	v_add_f32_e32 v190, v190, v86
	v_add_f32_e32 v191, v191, v87
	v_cvt_pk_bf16_f32 v152, v80, v81
	v_cvt_pk_bf16_f32 v153, v82, v83
	v_cvt_pk_bf16_f32 v154, v84, v85
	v_cvt_pk_bf16_f32 v155, v86, v87
	s_waitcnt lgkmcnt(5)
	v_mfma_f32_32x32x16_bf16 v[112:127], v[220:223], v[132:135], v[112:127]
	ds_read_b128 v[220:223], v187 offset:4096
	v_sub_f32_e32 v88, v88, v175
	v_sub_f32_e32 v89, v89, v175
	v_sub_f32_e32 v90, v90, v175
	v_sub_f32_e32 v91, v91, v175
	v_sub_f32_e32 v92, v92, v175
	v_sub_f32_e32 v93, v93, v175
	s_waitcnt lgkmcnt(5)
	v_mfma_f32_32x32x16_bf16 v[96:111], v[224:227], v[136:139], v[96:111]
	ds_read_b128 v[224:227], v187 offset:8192
	v_sub_f32_e32 v94, v94, v175
	v_sub_f32_e32 v95, v95, v175
	v_exp_f32_e32 v88, v88
	v_exp_f32_e32 v89, v89
	v_exp_f32_e32 v90, v90
	v_exp_f32_e32 v91, v91
	s_waitcnt lgkmcnt(5)
	v_mfma_f32_32x32x16_bf16 v[112:127], v[228:231], v[136:139], v[112:127]
	ds_read_b128 v[228:231], v187 offset:12288
	v_exp_f32_e32 v92, v92
	v_exp_f32_e32 v93, v93
	v_exp_f32_e32 v94, v94
	v_exp_f32_e32 v95, v95
	v_add_f32_e32 v190, v190, v88
	v_add_f32_e32 v191, v191, v89
	s_waitcnt lgkmcnt(5)
	v_mfma_f32_32x32x16_bf16 v[96:111], v[208:211], v[140:143], v[96:111]
	ds_read_b128 v[208:211], v188 offset:0
	v_add_f32_e32 v190, v190, v90
	v_add_f32_e32 v191, v191, v91
	v_add_f32_e32 v190, v190, v92
	v_add_f32_e32 v191, v191, v93
	v_add_f32_e32 v190, v190, v94
	v_add_f32_e32 v191, v191, v95
	s_waitcnt lgkmcnt(5)
	v_mfma_f32_32x32x16_bf16 v[112:127], v[212:215], v[140:143], v[112:127]
	ds_read_b128 v[212:215], v188 offset:4096
	v_cvt_pk_bf16_f32 v156, v88, v89
	v_cvt_pk_bf16_f32 v157, v90, v91
	v_cvt_pk_bf16_f32 v158, v92, v93
	v_cvt_pk_bf16_f32 v159, v94, v95
	v_add_f32_e32 v190, v190, v191
	v_fma_f32 v167, v167, v174, v190
	s_cbranch_vccz .Lattn_noresc_L3
	s_nop 7
	s_nop 7
	v_pk_mul_f32 v[0:1], v[0:1], v[174:175] op_sel_hi:[1,0]
	v_pk_mul_f32 v[2:3], v[2:3], v[174:175] op_sel_hi:[1,0]
	v_pk_mul_f32 v[4:5], v[4:5], v[174:175] op_sel_hi:[1,0]
	v_pk_mul_f32 v[6:7], v[6:7], v[174:175] op_sel_hi:[1,0]
	v_pk_mul_f32 v[8:9], v[8:9], v[174:175] op_sel_hi:[1,0]
	v_pk_mul_f32 v[10:11], v[10:11], v[174:175] op_sel_hi:[1,0]
	v_pk_mul_f32 v[12:13], v[12:13], v[174:175] op_sel_hi:[1,0]
	v_pk_mul_f32 v[14:15], v[14:15], v[174:175] op_sel_hi:[1,0]
	v_pk_mul_f32 v[16:17], v[16:17], v[174:175] op_sel_hi:[1,0]
	v_pk_mul_f32 v[18:19], v[18:19], v[174:175] op_sel_hi:[1,0]
	v_pk_mul_f32 v[20:21], v[20:21], v[174:175] op_sel_hi:[1,0]
	v_pk_mul_f32 v[22:23], v[22:23], v[174:175] op_sel_hi:[1,0]
	v_pk_mul_f32 v[24:25], v[24:25], v[174:175] op_sel_hi:[1,0]
	v_pk_mul_f32 v[26:27], v[26:27], v[174:175] op_sel_hi:[1,0]
	v_pk_mul_f32 v[28:29], v[28:29], v[174:175] op_sel_hi:[1,0]
	v_pk_mul_f32 v[30:31], v[30:31], v[174:175] op_sel_hi:[1,0]
	v_pk_mul_f32 v[32:33], v[32:33], v[174:175] op_sel_hi:[1,0]
	v_pk_mul_f32 v[34:35], v[34:35], v[174:175] op_sel_hi:[1,0]
	v_pk_mul_f32 v[36:37], v[36:37], v[174:175] op_sel_hi:[1,0]
	v_pk_mul_f32 v[38:39], v[38:39], v[174:175] op_sel_hi:[1,0]
	v_pk_mul_f32 v[40:41], v[40:41], v[174:175] op_sel_hi:[1,0]
	v_pk_mul_f32 v[42:43], v[42:43], v[174:175] op_sel_hi:[1,0]
	v_pk_mul_f32 v[44:45], v[44:45], v[174:175] op_sel_hi:[1,0]
	v_pk_mul_f32 v[46:47], v[46:47], v[174:175] op_sel_hi:[1,0]
	v_pk_mul_f32 v[48:49], v[48:49], v[174:175] op_sel_hi:[1,0]
	v_pk_mul_f32 v[50:51], v[50:51], v[174:175] op_sel_hi:[1,0]
	v_pk_mul_f32 v[52:53], v[52:53], v[174:175] op_sel_hi:[1,0]
	v_pk_mul_f32 v[54:55], v[54:55], v[174:175] op_sel_hi:[1,0]
	v_pk_mul_f32 v[56:57], v[56:57], v[174:175] op_sel_hi:[1,0]
	v_pk_mul_f32 v[58:59], v[58:59], v[174:175] op_sel_hi:[1,0]
	v_pk_mul_f32 v[60:61], v[60:61], v[174:175] op_sel_hi:[1,0]
	v_pk_mul_f32 v[62:63], v[62:63], v[174:175] op_sel_hi:[1,0]
	s_nop 1
.Lattn_noresc_L3:
	s_add_i32 s42, s42, 4
	s_add_i32 s47, s47, -1
	s_cmp_lg_u32 s47, 0
	s_cbranch_scc1 .Lattn_loop_s
	s_waitcnt vmcnt(4)
	s_barrier
	s_waitcnt lgkmcnt(5)
	v_mfma_f32_32x32x16_bf16 v[48:63], v[216:219], v[144:147], v[48:63]
	ds_read_b128 v[216:219], v188 offset:8192
	s_nop 3
	s_add_i32 s2, s42, 2
	v_max3_f32 v254, v96, v97, v98
	s_and_b32 s2, s2, 31
	v_max3_f32 v255, v112, v113, v114
	s_lshl_b32 s2, s2, 7
	v_max3_f32 v254, v254, v99, v100
	v_max3_f32 v255, v255, v115, v116
	s_waitcnt lgkmcnt(5)
	v_mfma_f32_32x32x16_bf16 v[32:47], v[220:223], v[144:147], v[32:47]
	ds_read_b128 v[220:223], v188 offset:12288
	v_max3_f32 v254, v254, v101, v102
	v_max3_f32 v255, v255, v117, v118
	v_max3_f32 v254, v254, v103, v104
	v_max3_f32 v255, v255, v119, v120
	v_max3_f32 v254, v254, v105, v106
	v_max3_f32 v255, v255, v121, v122
	v_max3_f32 v254, v254, v107, v108
	v_max3_f32 v255, v255, v123, v124
	s_waitcnt lgkmcnt(5)
	v_mfma_f32_32x32x16_bf16 v[16:31], v[224:227], v[144:147], v[16:31]
	ds_read_b128 v[224:227], v186 offset:0
	v_max3_f32 v254, v254, v109, v110
	v_max3_f32 v255, v255, v125, v126
	v_max3_f32 v254, v254, v111, v127
	v_max_f32_e32 v254, v254, v255
	v_cmp_lt_f32_e32 vcc, 0x4138aa3b, v254
	s_add_i32 m0, s5, 114688
	v_lshl_add_u64 v[232:233], v[172:173], 0, s[2:3]
	global_load_lds_dwordx4 v[232:233], off
	s_waitcnt lgkmcnt(5)
	v_mfma_f32_32x32x16_bf16 v[0:15], v[228:231], v[144:147], v[0:15]
	ds_read_b128 v[228:231], v186 offset:4096
	s_add_i32 m0, s5, 122880
	v_lshl_add_u64 v[234:235], v[232:233], 0, s[22:23]
	global_load_lds_dwordx4 v[234:235], off
.Lattn_sp_T29:
	v_mov_b32_e32 v255, v254
	s_nop 1
	v_permlane32_swap_b32_e32 v254, v255
	v_max_f32_e32 v254, v254, v255
	v_add_f32_e32 v180, 0x4138aa3b, v175
	v_cmp_gt_f32_e32 vcc, v254, v180
	s_waitcnt lgkmcnt(5)
	v_mfma_f32_32x32x16_bf16 v[48:63], v[208:211], v[148:151], v[48:63]
	ds_read_b128 v[208:211], v186 offset:8192
	s_nop 1
	v_cndmask_b32_e32 v180, v175, v254, vcc
	v_sub_f32_e32 v255, v175, v180
	v_exp_f32_e32 v174, v255
	v_mov_b32_e32 v175, v180
	v_sub_f32_e32 v96, v96, v175
	s_waitcnt lgkmcnt(5)
	v_mfma_f32_32x32x16_bf16 v[32:47], v[212:215], v[148:151], v[32:47]
	ds_read_b128 v[212:215], v186 offset:12288
	v_sub_f32_e32 v97, v97, v175
	v_sub_f32_e32 v98, v98, v175
	v_sub_f32_e32 v99, v99, v175
	v_sub_f32_e32 v100, v100, v175
	v_sub_f32_e32 v101, v101, v175
	v_sub_f32_e32 v102, v102, v175
	s_waitcnt lgkmcnt(5)
	v_mfma_f32_32x32x16_bf16 v[16:31], v[216:219], v[148:151], v[16:31]
	ds_read_b128 v[216:219], v189 offset:0
	v_sub_f32_e32 v103, v103, v175
	v_exp_f32_e32 v96, v96
	v_exp_f32_e32 v97, v97
	v_exp_f32_e32 v98, v98
	v_exp_f32_e32 v99, v99
	v_exp_f32_e32 v100, v100
	s_waitcnt lgkmcnt(5)
	v_mfma_f32_32x32x16_bf16 v[0:15], v[220:223], v[148:151], v[0:15]
	ds_read_b128 v[220:223], v189 offset:4096
	v_exp_f32_e32 v101, v101
	v_exp_f32_e32 v102, v102
	v_exp_f32_e32 v103, v103
	v_add_f32_e32 v190, v96, v97
	v_add_f32_e32 v191, v98, v99
	v_add_f32_e32 v190, v190, v100
	s_waitcnt lgkmcnt(5)
	v_mfma_f32_32x32x16_bf16 v[48:63], v[224:227], v[152:155], v[48:63]
	ds_read_b128 v[224:227], v189 offset:8192
	v_add_f32_e32 v191, v191, v101
	v_add_f32_e32 v190, v190, v102
	v_add_f32_e32 v191, v191, v103
	v_cvt_pk_bf16_f32 v144, v96, v97
	v_cvt_pk_bf16_f32 v145, v98, v99
	v_cvt_pk_bf16_f32 v146, v100, v101
	s_waitcnt lgkmcnt(5)
	v_mfma_f32_32x32x16_bf16 v[32:47], v[228:231], v[152:155], v[32:47]
	ds_read_b128 v[228:231], v189 offset:12288
	v_cvt_pk_bf16_f32 v147, v102, v103
	v_sub_f32_e32 v104, v104, v175
	v_sub_f32_e32 v105, v105, v175
	v_sub_f32_e32 v106, v106, v175
	v_sub_f32_e32 v107, v107, v175
	v_sub_f32_e32 v108, v108, v175
	s_waitcnt lgkmcnt(5)
	v_mfma_f32_32x32x16_bf16 v[16:31], v[208:211], v[152:155], v[16:31]
	ds_read_b128 v[208:211], v182 offset:32768
	v_sub_f32_e32 v109, v109, v175
	v_sub_f32_e32 v110, v110, v175
	v_sub_f32_e32 v111, v111, v175
	v_exp_f32_e32 v104, v104
	v_exp_f32_e32 v105, v105
	v_exp_f32_e32 v106, v106
	s_waitcnt lgkmcnt(5)
	v_mfma_f32_32x32x16_bf16 v[0:15], v[212:215], v[152:155], v[0:15]
	ds_read_b128 v[212:215], v182 offset:36864
	v_exp_f32_e32 v107, v107
	v_exp_f32_e32 v108, v108
	v_exp_f32_e32 v109, v109
	v_exp_f32_e32 v110, v110
	v_exp_f32_e32 v111, v111
	v_add_f32_e32 v190, v190, v104
	s_waitcnt lgkmcnt(5)
	v_mfma_f32_32x32x16_bf16 v[48:63], v[216:219], v[156:159], v[48:63]
	ds_read_b128 v[216:219], v183 offset:32768
	v_add_f32_e32 v191, v191, v105
	v_add_f32_e32 v190, v190, v106
	v_add_f32_e32 v191, v191, v107
	v_add_f32_e32 v190, v190, v108
	v_add_f32_e32 v191, v191, v109
	v_add_f32_e32 v190, v190, v110
	s_waitcnt lgkmcnt(5)
	v_mfma_f32_32x32x16_bf16 v[32:47], v[220:223], v[156:159], v[32:47]
	ds_read_b128 v[220:223], v183 offset:36864
	v_add_f32_e32 v191, v191, v111
	v_cvt_pk_bf16_f32 v148, v104, v105
	v_cvt_pk_bf16_f32 v149, v106, v107
	v_cvt_pk_bf16_f32 v150, v108, v109
	v_cvt_pk_bf16_f32 v151, v110, v111
	v_sub_f32_e32 v112, v112, v175
	s_waitcnt lgkmcnt(5)
	v_mfma_f32_32x32x16_bf16 v[16:31], v[224:227], v[156:159], v[16:31]
	ds_read_b128 v[224:227], v184 offset:32768
	v_sub_f32_e32 v113, v113, v175
	v_sub_f32_e32 v114, v114, v175
	v_sub_f32_e32 v115, v115, v175
	v_sub_f32_e32 v116, v116, v175
	v_sub_f32_e32 v117, v117, v175
	v_sub_f32_e32 v118, v118, v175
	s_waitcnt lgkmcnt(5)
	v_mfma_f32_32x32x16_bf16 v[0:15], v[228:231], v[156:159], v[0:15]
	ds_read_b128 v[228:231], v184 offset:36864
	v_sub_f32_e32 v119, v119, v175
	v_exp_f32_e32 v112, v112
	v_exp_f32_e32 v113, v113
	v_exp_f32_e32 v114, v114
	v_exp_f32_e32 v115, v115
	v_exp_f32_e32 v116, v116
	s_waitcnt lgkmcnt(5)
	v_mfma_f32_32x32x16_bf16 v[64:79], v[208:211], v[128:131], 0
	ds_read_b128 v[208:211], v185 offset:32768
	v_exp_f32_e32 v117, v117
	v_exp_f32_e32 v118, v118
	v_exp_f32_e32 v119, v119
	v_add_f32_e32 v190, v190, v112
	v_add_f32_e32 v191, v191, v113
	v_add_f32_e32 v190, v190, v114
	s_waitcnt lgkmcnt(5)
	v_mfma_f32_32x32x16_bf16 v[80:95], v[212:215], v[128:131], 0
	ds_read_b128 v[212:215], v185 offset:36864
	v_add_f32_e32 v191, v191, v115
	v_add_f32_e32 v190, v190, v116
	v_add_f32_e32 v191, v191, v117
	v_add_f32_e32 v190, v190, v118
	v_add_f32_e32 v191, v191, v119
	v_cvt_pk_bf16_f32 v152, v112, v113
	s_waitcnt lgkmcnt(5)
	v_mfma_f32_32x32x16_bf16 v[64:79], v[216:219], v[132:135], v[64:79]
	ds_read_b128 v[216:219], v187 offset:16384
	v_cvt_pk_bf16_f32 v153, v114, v115
	v_cvt_pk_bf16_f32 v154, v116, v117
	v_cvt_pk_bf16_f32 v155, v118, v119
	v_sub_f32_e32 v120, v120, v175
	v_sub_f32_e32 v121, v121, v175
	v_sub_f32_e32 v122, v122, v175
	s_waitcnt lgkmcnt(5)
	v_mfma_f32_32x32x16_bf16 v[80:95], v[220:223], v[132:135], v[80:95]
	ds_read_b128 v[220:223], v187 offset:20480
	v_sub_f32_e32 v123, v123, v175
	v_sub_f32_e32 v124, v124, v175
	v_sub_f32_e32 v125, v125, v175
	v_sub_f32_e32 v126, v126, v175
	v_sub_f32_e32 v127, v127, v175
	v_exp_f32_e32 v120, v120
	s_waitcnt lgkmcnt(5)
	v_mfma_f32_32x32x16_bf16 v[64:79], v[224:227], v[136:139], v[64:79]
	ds_read_b128 v[224:227], v187 offset:24576
	v_exp_f32_e32 v121, v121
	v_exp_f32_e32 v122, v122
	v_exp_f32_e32 v123, v123
	v_exp_f32_e32 v124, v124
	v_exp_f32_e32 v125, v125
	v_exp_f32_e32 v126, v126
	s_waitcnt lgkmcnt(5)
	v_mfma_f32_32x32x16_bf16 v[80:95], v[228:231], v[136:139], v[80:95]
	ds_read_b128 v[228:231], v187 offset:28672
	v_exp_f32_e32 v127, v127
	v_add_f32_e32 v190, v190, v120
	v_add_f32_e32 v191, v191, v121
	v_add_f32_e32 v190, v190, v122
	v_add_f32_e32 v191, v191, v123
	s_waitcnt lgkmcnt(5)
	v_mfma_f32_32x32x16_bf16 v[64:79], v[208:211], v[140:143], v[64:79]
	ds_read_b128 v[208:211], v188 offset:16384
	v_add_f32_e32 v190, v190, v124
	v_add_f32_e32 v191, v191, v125
	v_add_f32_e32 v190, v190, v126
	v_add_f32_e32 v191, v191, v127
	v_cvt_pk_bf16_f32 v156, v120, v121
	s_waitcnt lgkmcnt(5)
	v_mfma_f32_32x32x16_bf16 v[80:95], v[212:215], v[140:143], v[80:95]
	ds_read_b128 v[212:215], v188 offset:20480
	v_cvt_pk_bf16_f32 v157, v122, v123
	v_cvt_pk_bf16_f32 v158, v124, v125
	v_cvt_pk_bf16_f32 v159, v126, v127
	v_add_f32_e32 v190, v190, v191
	v_fma_f32 v167, v167, v174, v190
	s_cbranch_vccz .Lattn_noresc_T29
	s_nop 7
	s_nop 7
	v_pk_mul_f32 v[0:1], v[0:1], v[174:175] op_sel_hi:[1,0]
	v_pk_mul_f32 v[2:3], v[2:3], v[174:175] op_sel_hi:[1,0]
	v_pk_mul_f32 v[4:5], v[4:5], v[174:175] op_sel_hi:[1,0]
	v_pk_mul_f32 v[6:7], v[6:7], v[174:175] op_sel_hi:[1,0]
	v_pk_mul_f32 v[8:9], v[8:9], v[174:175] op_sel_hi:[1,0]
	v_pk_mul_f32 v[10:11], v[10:11], v[174:175] op_sel_hi:[1,0]
	v_pk_mul_f32 v[12:13], v[12:13], v[174:175] op_sel_hi:[1,0]
	v_pk_mul_f32 v[14:15], v[14:15], v[174:175] op_sel_hi:[1,0]
	v_pk_mul_f32 v[16:17], v[16:17], v[174:175] op_sel_hi:[1,0]
	v_pk_mul_f32 v[18:19], v[18:19], v[174:175] op_sel_hi:[1,0]
	v_pk_mul_f32 v[20:21], v[20:21], v[174:175] op_sel_hi:[1,0]
	v_pk_mul_f32 v[22:23], v[22:23], v[174:175] op_sel_hi:[1,0]
	v_pk_mul_f32 v[24:25], v[24:25], v[174:175] op_sel_hi:[1,0]
	v_pk_mul_f32 v[26:27], v[26:27], v[174:175] op_sel_hi:[1,0]
	v_pk_mul_f32 v[28:29], v[28:29], v[174:175] op_sel_hi:[1,0]
	v_pk_mul_f32 v[30:31], v[30:31], v[174:175] op_sel_hi:[1,0]
	v_pk_mul_f32 v[32:33], v[32:33], v[174:175] op_sel_hi:[1,0]
	v_pk_mul_f32 v[34:35], v[34:35], v[174:175] op_sel_hi:[1,0]
	v_pk_mul_f32 v[36:37], v[36:37], v[174:175] op_sel_hi:[1,0]
	v_pk_mul_f32 v[38:39], v[38:39], v[174:175] op_sel_hi:[1,0]
	v_pk_mul_f32 v[40:41], v[40:41], v[174:175] op_sel_hi:[1,0]
	v_pk_mul_f32 v[42:43], v[42:43], v[174:175] op_sel_hi:[1,0]
	v_pk_mul_f32 v[44:45], v[44:45], v[174:175] op_sel_hi:[1,0]
	v_pk_mul_f32 v[46:47], v[46:47], v[174:175] op_sel_hi:[1,0]
	v_pk_mul_f32 v[48:49], v[48:49], v[174:175] op_sel_hi:[1,0]
	v_pk_mul_f32 v[50:51], v[50:51], v[174:175] op_sel_hi:[1,0]
	v_pk_mul_f32 v[52:53], v[52:53], v[174:175] op_sel_hi:[1,0]
	v_pk_mul_f32 v[54:55], v[54:55], v[174:175] op_sel_hi:[1,0]
	v_pk_mul_f32 v[56:57], v[56:57], v[174:175] op_sel_hi:[1,0]
	v_pk_mul_f32 v[58:59], v[58:59], v[174:175] op_sel_hi:[1,0]
	v_pk_mul_f32 v[60:61], v[60:61], v[174:175] op_sel_hi:[1,0]
	v_pk_mul_f32 v[62:63], v[62:63], v[174:175] op_sel_hi:[1,0]
	s_nop 1
.Lattn_noresc_T29:
	s_waitcnt vmcnt(2)
	s_barrier
	s_waitcnt lgkmcnt(5)
	v_mfma_f32_32x32x16_bf16 v[48:63], v[216:219], v[144:147], v[48:63]
	ds_read_b128 v[216:219], v188 offset:24576
	s_nop 3
	v_max3_f32 v254, v64, v65, v66
	v_max3_f32 v255, v80, v81, v82
	v_max3_f32 v254, v254, v67, v68
	v_max3_f32 v255, v255, v83, v84
	v_max3_f32 v254, v254, v69, v70
	v_max3_f32 v255, v255, v85, v86
	v_max3_f32 v254, v254, v71, v72
	s_waitcnt lgkmcnt(5)
	v_mfma_f32_32x32x16_bf16 v[32:47], v[220:223], v[144:147], v[32:47]
	ds_read_b128 v[220:223], v188 offset:28672
	v_max3_f32 v255, v255, v87, v88
	v_max3_f32 v254, v254, v73, v74
	v_max3_f32 v255, v255, v89, v90
	v_max3_f32 v254, v254, v75, v76
	v_max3_f32 v255, v255, v91, v92
	v_max3_f32 v254, v254, v77, v78
	v_max3_f32 v255, v255, v93, v94
	v_max3_f32 v254, v254, v79, v95
	s_waitcnt lgkmcnt(5)
	v_mfma_f32_32x32x16_bf16 v[16:31], v[224:227], v[144:147], v[16:31]
	ds_read_b128 v[224:227], v186 offset:16384
	v_max_f32_e32 v254, v254, v255
	v_cmp_lt_f32_e32 vcc, 0x4138aa3b, v254
	s_nop 4
.Lattn_sp_T30:
	v_mov_b32_e32 v255, v254
	s_nop 1
	v_permlane32_swap_b32_e32 v254, v255
	v_max_f32_e32 v254, v254, v255
	v_add_f32_e32 v180, 0x4138aa3b, v175
	v_cmp_gt_f32_e32 vcc, v254, v180
	s_waitcnt lgkmcnt(5)
	v_mfma_f32_32x32x16_bf16 v[0:15], v[228:231], v[144:147], v[0:15]
	ds_read_b128 v[228:231], v186 offset:20480
	s_nop 1
	v_cndmask_b32_e32 v180, v175, v254, vcc
	v_sub_f32_e32 v255, v175, v180
	v_exp_f32_e32 v174, v255
	v_mov_b32_e32 v175, v180
	v_sub_f32_e32 v64, v64, v175
	s_waitcnt lgkmcnt(5)
	v_mfma_f32_32x32x16_bf16 v[48:63], v[208:211], v[148:151], v[48:63]
	ds_read_b128 v[208:211], v186 offset:24576
	v_sub_f32_e32 v65, v65, v175
	v_sub_f32_e32 v66, v66, v175
	v_sub_f32_e32 v67, v67, v175
	v_sub_f32_e32 v68, v68, v175
	v_sub_f32_e32 v69, v69, v175
	v_sub_f32_e32 v70, v70, v175
	s_waitcnt lgkmcnt(5)
	v_mfma_f32_32x32x16_bf16 v[32:47], v[212:215], v[148:151], v[32:47]
	ds_read_b128 v[212:215], v186 offset:28672
	v_sub_f32_e32 v71, v71, v175
	v_exp_f32_e32 v64, v64
	v_exp_f32_e32 v65, v65
	v_exp_f32_e32 v66, v66
	v_exp_f32_e32 v67, v67
	v_exp_f32_e32 v68, v68
	s_waitcnt lgkmcnt(5)
	v_mfma_f32_32x32x16_bf16 v[16:31], v[216:219], v[148:151], v[16:31]
	ds_read_b128 v[216:219], v189 offset:16384
	v_exp_f32_e32 v69, v69
	v_exp_f32_e32 v70, v70
	v_exp_f32_e32 v71, v71
	v_add_f32_e32 v190, v64, v65
	v_add_f32_e32 v191, v66, v67
	v_add_f32_e32 v190, v190, v68
	s_waitcnt lgkmcnt(5)
	v_mfma_f32_32x32x16_bf16 v[0:15], v[220:223], v[148:151], v[0:15]
	ds_read_b128 v[220:223], v189 offset:20480
	v_add_f32_e32 v191, v191, v69
	v_add_f32_e32 v190, v190, v70
	v_add_f32_e32 v191, v191, v71
	v_cvt_pk_bf16_f32 v144, v64, v65
	v_cvt_pk_bf16_f32 v145, v66, v67
	v_cvt_pk_bf16_f32 v146, v68, v69
	s_waitcnt lgkmcnt(5)
	v_mfma_f32_32x32x16_bf16 v[48:63], v[224:227], v[152:155], v[48:63]
	ds_read_b128 v[224:227], v189 offset:24576
	v_cvt_pk_bf16_f32 v147, v70, v71
	v_sub_f32_e32 v72, v72, v175
	v_sub_f32_e32 v73, v73, v175
	v_sub_f32_e32 v74, v74, v175
	v_sub_f32_e32 v75, v75, v175
	v_sub_f32_e32 v76, v76, v175
	s_waitcnt lgkmcnt(5)
	v_mfma_f32_32x32x16_bf16 v[32:47], v[228:231], v[152:155], v[32:47]
	ds_read_b128 v[228:231], v189 offset:28672
	v_sub_f32_e32 v77, v77, v175
	v_sub_f32_e32 v78, v78, v175
	v_sub_f32_e32 v79, v79, v175
	v_exp_f32_e32 v72, v72
	v_exp_f32_e32 v73, v73
	v_exp_f32_e32 v74, v74
	s_waitcnt lgkmcnt(5)
	v_mfma_f32_32x32x16_bf16 v[16:31], v[208:211], v[152:155], v[16:31]
	ds_read_b128 v[208:211], v182 offset:49152
	v_exp_f32_e32 v75, v75
	v_exp_f32_e32 v76, v76
	v_exp_f32_e32 v77, v77
	v_exp_f32_e32 v78, v78
	v_exp_f32_e32 v79, v79
	v_add_f32_e32 v190, v190, v72
	s_waitcnt lgkmcnt(5)
	v_mfma_f32_32x32x16_bf16 v[0:15], v[212:215], v[152:155], v[0:15]
	ds_read_b128 v[212:215], v182 offset:53248
	v_add_f32_e32 v191, v191, v73
	v_add_f32_e32 v190, v190, v74
	v_add_f32_e32 v191, v191, v75
	v_add_f32_e32 v190, v190, v76
	v_add_f32_e32 v191, v191, v77
	v_add_f32_e32 v190, v190, v78
	s_waitcnt lgkmcnt(5)
	v_mfma_f32_32x32x16_bf16 v[48:63], v[216:219], v[156:159], v[48:63]
	ds_read_b128 v[216:219], v183 offset:49152
	v_add_f32_e32 v191, v191, v79
	v_cvt_pk_bf16_f32 v148, v72, v73
	v_cvt_pk_bf16_f32 v149, v74, v75
	v_cvt_pk_bf16_f32 v150, v76, v77
	v_cvt_pk_bf16_f32 v151, v78, v79
	v_sub_f32_e32 v80, v80, v175
	s_waitcnt lgkmcnt(5)
	v_mfma_f32_32x32x16_bf16 v[32:47], v[220:223], v[156:159], v[32:47]
	ds_read_b128 v[220:223], v183 offset:53248
	v_sub_f32_e32 v81, v81, v175
	v_sub_f32_e32 v82, v82, v175
	v_sub_f32_e32 v83, v83, v175
	v_sub_f32_e32 v84, v84, v175
	v_sub_f32_e32 v85, v85, v175
	v_sub_f32_e32 v86, v86, v175
	s_waitcnt lgkmcnt(5)
	v_mfma_f32_32x32x16_bf16 v[16:31], v[224:227], v[156:159], v[16:31]
	ds_read_b128 v[224:227], v184 offset:49152
	v_sub_f32_e32 v87, v87, v175
	v_exp_f32_e32 v80, v80
	v_exp_f32_e32 v81, v81
	v_exp_f32_e32 v82, v82
	v_exp_f32_e32 v83, v83
	v_exp_f32_e32 v84, v84
	s_waitcnt lgkmcnt(5)
	v_mfma_f32_32x32x16_bf16 v[0:15], v[228:231], v[156:159], v[0:15]
	ds_read_b128 v[228:231], v184 offset:53248
	v_exp_f32_e32 v85, v85
	v_exp_f32_e32 v86, v86
	v_exp_f32_e32 v87, v87
	v_add_f32_e32 v190, v190, v80
	v_add_f32_e32 v191, v191, v81
	s_waitcnt lgkmcnt(5)
	v_mfma_f32_32x32x16_bf16 v[96:111], v[208:211], v[128:131], 0
	ds_read_b128 v[208:211], v185 offset:49152
	v_add_f32_e32 v190, v190, v82
	v_add_f32_e32 v191, v191, v83
	v_add_f32_e32 v190, v190, v84
	v_add_f32_e32 v191, v191, v85
	v_add_f32_e32 v190, v190, v86
	s_waitcnt lgkmcnt(5)
	v_mfma_f32_32x32x16_bf16 v[112:127], v[212:215], v[128:131], 0
	ds_read_b128 v[212:215], v185 offset:53248
	v_add_f32_e32 v191, v191, v87
	v_cvt_pk_bf16_f32 v152, v80, v81
	v_cvt_pk_bf16_f32 v153, v82, v83
	v_cvt_pk_bf16_f32 v154, v84, v85
	v_cvt_pk_bf16_f32 v155, v86, v87
	s_waitcnt lgkmcnt(5)
	v_mfma_f32_32x32x16_bf16 v[96:111], v[216:219], v[132:135], v[96:111]
	ds_read_b128 v[216:219], v187 offset:32768
	v_sub_f32_e32 v88, v88, v175
	v_sub_f32_e32 v89, v89, v175
	v_sub_f32_e32 v90, v90, v175
	v_sub_f32_e32 v91, v91, v175
	v_sub_f32_e32 v92, v92, v175
	s_waitcnt lgkmcnt(5)
	v_mfma_f32_32x32x16_bf16 v[112:127], v[220:223], v[132:135], v[112:127]
	ds_read_b128 v[220:223], v187 offset:36864
	v_sub_f32_e32 v93, v93, v175
	v_sub_f32_e32 v94, v94, v175
	v_sub_f32_e32 v95, v95, v175
	v_exp_f32_e32 v88, v88
	v_exp_f32_e32 v89, v89
	s_waitcnt lgkmcnt(5)
	v_mfma_f32_32x32x16_bf16 v[96:111], v[224:227], v[136:139], v[96:111]
	ds_read_b128 v[224:227], v187 offset:40960
	v_exp_f32_e32 v90, v90
	v_exp_f32_e32 v91, v91
	v_exp_f32_e32 v92, v92
	v_exp_f32_e32 v93, v93
	v_exp_f32_e32 v94, v94
	s_waitcnt lgkmcnt(5)
	v_mfma_f32_32x32x16_bf16 v[112:127], v[228:231], v[136:139], v[112:127]
	ds_read_b128 v[228:231], v187 offset:45056
	v_exp_f32_e32 v95, v95
	v_add_f32_e32 v190, v190, v88
	v_add_f32_e32 v191, v191, v89
	v_add_f32_e32 v190, v190, v90
	v_add_f32_e32 v191, v191, v91
	s_waitcnt lgkmcnt(5)
	v_mfma_f32_32x32x16_bf16 v[96:111], v[208:211], v[140:143], v[96:111]
	ds_read_b128 v[208:211], v188 offset:32768
	v_add_f32_e32 v190, v190, v92
	v_add_f32_e32 v191, v191, v93
	v_add_f32_e32 v190, v190, v94
	v_add_f32_e32 v191, v191, v95
	v_cvt_pk_bf16_f32 v156, v88, v89
	s_waitcnt lgkmcnt(5)
	v_mfma_f32_32x32x16_bf16 v[112:127], v[212:215], v[140:143], v[112:127]
	ds_read_b128 v[212:215], v188 offset:36864
	v_cvt_pk_bf16_f32 v157, v90, v91
	v_cvt_pk_bf16_f32 v158, v92, v93
	v_cvt_pk_bf16_f32 v159, v94, v95
	v_add_f32_e32 v190, v190, v191
	v_fma_f32 v167, v167, v174, v190
	s_cbranch_vccz .Lattn_noresc_T30
	s_nop 7
	s_nop 7
	v_pk_mul_f32 v[0:1], v[0:1], v[174:175] op_sel_hi:[1,0]
	v_pk_mul_f32 v[2:3], v[2:3], v[174:175] op_sel_hi:[1,0]
	v_pk_mul_f32 v[4:5], v[4:5], v[174:175] op_sel_hi:[1,0]
	v_pk_mul_f32 v[6:7], v[6:7], v[174:175] op_sel_hi:[1,0]
	v_pk_mul_f32 v[8:9], v[8:9], v[174:175] op_sel_hi:[1,0]
	v_pk_mul_f32 v[10:11], v[10:11], v[174:175] op_sel_hi:[1,0]
	v_pk_mul_f32 v[12:13], v[12:13], v[174:175] op_sel_hi:[1,0]
	v_pk_mul_f32 v[14:15], v[14:15], v[174:175] op_sel_hi:[1,0]
	v_pk_mul_f32 v[16:17], v[16:17], v[174:175] op_sel_hi:[1,0]
	v_pk_mul_f32 v[18:19], v[18:19], v[174:175] op_sel_hi:[1,0]
	v_pk_mul_f32 v[20:21], v[20:21], v[174:175] op_sel_hi:[1,0]
	v_pk_mul_f32 v[22:23], v[22:23], v[174:175] op_sel_hi:[1,0]
	v_pk_mul_f32 v[24:25], v[24:25], v[174:175] op_sel_hi:[1,0]
	v_pk_mul_f32 v[26:27], v[26:27], v[174:175] op_sel_hi:[1,0]
	v_pk_mul_f32 v[28:29], v[28:29], v[174:175] op_sel_hi:[1,0]
	v_pk_mul_f32 v[30:31], v[30:31], v[174:175] op_sel_hi:[1,0]
	v_pk_mul_f32 v[32:33], v[32:33], v[174:175] op_sel_hi:[1,0]
	v_pk_mul_f32 v[34:35], v[34:35], v[174:175] op_sel_hi:[1,0]
	v_pk_mul_f32 v[36:37], v[36:37], v[174:175] op_sel_hi:[1,0]
	v_pk_mul_f32 v[38:39], v[38:39], v[174:175] op_sel_hi:[1,0]
	v_pk_mul_f32 v[40:41], v[40:41], v[174:175] op_sel_hi:[1,0]
	v_pk_mul_f32 v[42:43], v[42:43], v[174:175] op_sel_hi:[1,0]
	v_pk_mul_f32 v[44:45], v[44:45], v[174:175] op_sel_hi:[1,0]
	v_pk_mul_f32 v[46:47], v[46:47], v[174:175] op_sel_hi:[1,0]
	v_pk_mul_f32 v[48:49], v[48:49], v[174:175] op_sel_hi:[1,0]
	v_pk_mul_f32 v[50:51], v[50:51], v[174:175] op_sel_hi:[1,0]
	v_pk_mul_f32 v[52:53], v[52:53], v[174:175] op_sel_hi:[1,0]
	v_pk_mul_f32 v[54:55], v[54:55], v[174:175] op_sel_hi:[1,0]
	v_pk_mul_f32 v[56:57], v[56:57], v[174:175] op_sel_hi:[1,0]
	v_pk_mul_f32 v[58:59], v[58:59], v[174:175] op_sel_hi:[1,0]
	v_pk_mul_f32 v[60:61], v[60:61], v[174:175] op_sel_hi:[1,0]
	v_pk_mul_f32 v[62:63], v[62:63], v[174:175] op_sel_hi:[1,0]
	s_nop 1
.Lattn_noresc_T30:
	s_waitcnt vmcnt(0)
	s_barrier
	s_waitcnt lgkmcnt(5)
	v_mfma_f32_32x32x16_bf16 v[48:63], v[216:219], v[144:147], v[48:63]
	ds_read_b128 v[216:219], v188 offset:40960
	s_nop 3
	v_max3_f32 v254, v96, v97, v98
	v_max3_f32 v255, v112, v113, v114
	v_max3_f32 v254, v254, v99, v100
	v_max3_f32 v255, v255, v115, v116
	v_max3_f32 v254, v254, v101, v102
	v_max3_f32 v255, v255, v117, v118
	v_max3_f32 v254, v254, v103, v104
	s_waitcnt lgkmcnt(5)
	v_mfma_f32_32x32x16_bf16 v[32:47], v[220:223], v[144:147], v[32:47]
	ds_read_b128 v[220:223], v188 offset:45056
	v_max3_f32 v255, v255, v119, v120
	v_max3_f32 v254, v254, v105, v106
	v_max3_f32 v255, v255, v121, v122
	v_max3_f32 v254, v254, v107, v108
	v_max3_f32 v255, v255, v123, v124
	v_max3_f32 v254, v254, v109, v110
	v_max3_f32 v255, v255, v125, v126
	v_max3_f32 v254, v254, v111, v127
	s_waitcnt lgkmcnt(5)
	v_mfma_f32_32x32x16_bf16 v[16:31], v[224:227], v[144:147], v[16:31]
	ds_read_b128 v[224:227], v186 offset:32768
	v_max_f32_e32 v254, v254, v255
	v_cmp_lt_f32_e32 vcc, 0x4138aa3b, v254
	s_nop 4
.Lattn_sp_T31:
	v_mov_b32_e32 v255, v254
	s_nop 1
	v_permlane32_swap_b32_e32 v254, v255
	v_max_f32_e32 v254, v254, v255
	v_add_f32_e32 v180, 0x4138aa3b, v175
	v_cmp_gt_f32_e32 vcc, v254, v180
	s_nop 1
	v_cndmask_b32_e32 v180, v175, v254, vcc
	v_sub_f32_e32 v255, v175, v180
	s_waitcnt lgkmcnt(5)
	v_mfma_f32_32x32x16_bf16 v[0:15], v[228:231], v[144:147], v[0:15]
	ds_read_b128 v[228:231], v186 offset:36864
	v_exp_f32_e32 v174, v255
	v_mov_b32_e32 v175, v180
	v_sub_f32_e32 v96, v96, v175
	v_sub_f32_e32 v97, v97, v175
	v_sub_f32_e32 v98, v98, v175
	v_sub_f32_e32 v99, v99, v175
	v_sub_f32_e32 v100, v100, v175
	v_sub_f32_e32 v101, v101, v175
	v_sub_f32_e32 v102, v102, v175
	s_waitcnt lgkmcnt(5)
	v_mfma_f32_32x32x16_bf16 v[48:63], v[208:211], v[148:151], v[48:63]
	ds_read_b128 v[208:211], v186 offset:40960
	v_sub_f32_e32 v103, v103, v175
	v_exp_f32_e32 v96, v96
	v_exp_f32_e32 v97, v97
	v_exp_f32_e32 v98, v98
	v_exp_f32_e32 v99, v99
	v_exp_f32_e32 v100, v100
	v_exp_f32_e32 v101, v101
	v_exp_f32_e32 v102, v102
	v_exp_f32_e32 v103, v103
	s_waitcnt lgkmcnt(5)
	v_mfma_f32_32x32x16_bf16 v[32:47], v[212:215], v[148:151], v[32:47]
	ds_read_b128 v[212:215], v186 offset:45056
	v_add_f32_e32 v190, v96, v97
	v_add_f32_e32 v191, v98, v99
	v_add_f32_e32 v190, v190, v100
	v_add_f32_e32 v191, v191, v101
	v_add_f32_e32 v190, v190, v102
	v_add_f32_e32 v191, v191, v103
	v_cvt_pk_bf16_f32 v144, v96, v97
	v_cvt_pk_bf16_f32 v145, v98, v99
	v_cvt_pk_bf16_f32 v146, v100, v101
	s_waitcnt lgkmcnt(5)
	v_mfma_f32_32x32x16_bf16 v[16:31], v[216:219], v[148:151], v[16:31]
	ds_read_b128 v[216:219], v189 offset:32768
	v_cvt_pk_bf16_f32 v147, v102, v103
	s_waitcnt lgkmcnt(5)
	v_mfma_f32_32x32x16_bf16 v[0:15], v[220:223], v[148:151], v[0:15]
	ds_read_b128 v[220:223], v189 offset:36864
	v_sub_f32_e32 v104, v104, v175
	v_sub_f32_e32 v105, v105, v175
	v_sub_f32_e32 v106, v106, v175
	v_sub_f32_e32 v107, v107, v175
	v_sub_f32_e32 v108, v108, v175
	v_sub_f32_e32 v109, v109, v175
	v_sub_f32_e32 v110, v110, v175
	v_sub_f32_e32 v111, v111, v175
	v_exp_f32_e32 v104, v104
	v_exp_f32_e32 v105, v105
	s_waitcnt lgkmcnt(5)
	v_mfma_f32_32x32x16_bf16 v[48:63], v[224:227], v[152:155], v[48:63]
	ds_read_b128 v[224:227], v189 offset:40960
	v_exp_f32_e32 v106, v106
	v_exp_f32_e32 v107, v107
	v_exp_f32_e32 v108, v108
	v_exp_f32_e32 v109, v109
	v_exp_f32_e32 v110, v110
	v_exp_f32_e32 v111, v111
	v_add_f32_e32 v190, v190, v104
	v_add_f32_e32 v191, v191, v105
	v_add_f32_e32 v190, v190, v106
	v_add_f32_e32 v191, v191, v107
	s_waitcnt lgkmcnt(5)
	v_mfma_f32_32x32x16_bf16 v[32:47], v[228:231], v[152:155], v[32:47]
	ds_read_b128 v[228:231], v189 offset:45056
	v_add_f32_e32 v190, v190, v108
	v_add_f32_e32 v191, v191, v109
	v_add_f32_e32 v190, v190, v110
	v_add_f32_e32 v191, v191, v111
	v_cvt_pk_bf16_f32 v148, v104, v105
	v_cvt_pk_bf16_f32 v149, v106, v107
	v_cvt_pk_bf16_f32 v150, v108, v109
	v_cvt_pk_bf16_f32 v151, v110, v111
	s_waitcnt lgkmcnt(5)
	v_mfma_f32_32x32x16_bf16 v[16:31], v[208:211], v[152:155], v[16:31]
	ds_read_b128 v[208:211], v187 offset:49152
	s_waitcnt lgkmcnt(5)
	v_mfma_f32_32x32x16_bf16 v[0:15], v[212:215], v[152:155], v[0:15]
	ds_read_b128 v[212:215], v187 offset:53248
	v_sub_f32_e32 v112, v112, v175
	v_sub_f32_e32 v113, v113, v175
	v_sub_f32_e32 v114, v114, v175
	v_sub_f32_e32 v115, v115, v175
	v_sub_f32_e32 v116, v116, v175
	v_sub_f32_e32 v117, v117, v175
	v_sub_f32_e32 v118, v118, v175
	v_sub_f32_e32 v119, v119, v175
	v_exp_f32_e32 v112, v112
	v_exp_f32_e32 v113, v113
	v_exp_f32_e32 v114, v114
	v_exp_f32_e32 v115, v115
	s_waitcnt lgkmcnt(5)
	v_mfma_f32_32x32x16_bf16 v[48:63], v[216:219], v[156:159], v[48:63]
	ds_read_b128 v[216:219], v187 offset:57344
	v_exp_f32_e32 v116, v116
	v_exp_f32_e32 v117, v117
	v_exp_f32_e32 v118, v118
	v_exp_f32_e32 v119, v119
	v_add_f32_e32 v190, v190, v112
	v_add_f32_e32 v191, v191, v113
	v_add_f32_e32 v190, v190, v114
	v_add_f32_e32 v191, v191, v115
	v_add_f32_e32 v190, v190, v116
	v_add_f32_e32 v191, v191, v117
	v_add_f32_e32 v190, v190, v118
	v_add_f32_e32 v191, v191, v119
	s_waitcnt lgkmcnt(5)
	v_mfma_f32_32x32x16_bf16 v[32:47], v[220:223], v[156:159], v[32:47]
	ds_read_b128 v[220:223], v187 offset:61440
	v_cvt_pk_bf16_f32 v152, v112, v113
	v_cvt_pk_bf16_f32 v153, v114, v115
	v_cvt_pk_bf16_f32 v154, v116, v117
	v_cvt_pk_bf16_f32 v155, v118, v119
	s_waitcnt lgkmcnt(5)
	v_mfma_f32_32x32x16_bf16 v[16:31], v[224:227], v[156:159], v[16:31]
	ds_read_b128 v[224:227], v188 offset:49152
	s_waitcnt lgkmcnt(5)
	v_mfma_f32_32x32x16_bf16 v[0:15], v[228:231], v[156:159], v[0:15]
	ds_read_b128 v[228:231], v188 offset:53248
	v_sub_f32_e32 v120, v120, v175
	v_sub_f32_e32 v121, v121, v175
	v_sub_f32_e32 v122, v122, v175
	v_sub_f32_e32 v123, v123, v175
	v_sub_f32_e32 v124, v124, v175
	v_sub_f32_e32 v125, v125, v175
	v_sub_f32_e32 v126, v126, v175
	v_sub_f32_e32 v127, v127, v175
	v_exp_f32_e32 v120, v120
	v_exp_f32_e32 v121, v121
	v_exp_f32_e32 v122, v122
	v_exp_f32_e32 v123, v123
	v_exp_f32_e32 v124, v124
	v_exp_f32_e32 v125, v125
	v_exp_f32_e32 v126, v126
	v_exp_f32_e32 v127, v127
	v_add_f32_e32 v190, v190, v120
	v_add_f32_e32 v191, v191, v121
	v_add_f32_e32 v190, v190, v122
	v_add_f32_e32 v191, v191, v123
	v_add_f32_e32 v190, v190, v124
	v_add_f32_e32 v191, v191, v125
	v_add_f32_e32 v190, v190, v126
	v_add_f32_e32 v191, v191, v127
	v_cvt_pk_bf16_f32 v156, v120, v121
	v_cvt_pk_bf16_f32 v157, v122, v123
	v_cvt_pk_bf16_f32 v158, v124, v125
	v_cvt_pk_bf16_f32 v159, v126, v127
	v_add_f32_e32 v190, v190, v191
	v_fma_f32 v167, v167, v174, v190
	s_cbranch_vccz .Lattn_noresc_T31
	s_nop 7
	s_nop 7
	v_pk_mul_f32 v[0:1], v[0:1], v[174:175] op_sel_hi:[1,0]
	v_pk_mul_f32 v[2:3], v[2:3], v[174:175] op_sel_hi:[1,0]
	v_pk_mul_f32 v[4:5], v[4:5], v[174:175] op_sel_hi:[1,0]
	v_pk_mul_f32 v[6:7], v[6:7], v[174:175] op_sel_hi:[1,0]
	v_pk_mul_f32 v[8:9], v[8:9], v[174:175] op_sel_hi:[1,0]
	v_pk_mul_f32 v[10:11], v[10:11], v[174:175] op_sel_hi:[1,0]
	v_pk_mul_f32 v[12:13], v[12:13], v[174:175] op_sel_hi:[1,0]
	v_pk_mul_f32 v[14:15], v[14:15], v[174:175] op_sel_hi:[1,0]
	v_pk_mul_f32 v[16:17], v[16:17], v[174:175] op_sel_hi:[1,0]
	v_pk_mul_f32 v[18:19], v[18:19], v[174:175] op_sel_hi:[1,0]
	v_pk_mul_f32 v[20:21], v[20:21], v[174:175] op_sel_hi:[1,0]
	v_pk_mul_f32 v[22:23], v[22:23], v[174:175] op_sel_hi:[1,0]
	v_pk_mul_f32 v[24:25], v[24:25], v[174:175] op_sel_hi:[1,0]
	v_pk_mul_f32 v[26:27], v[26:27], v[174:175] op_sel_hi:[1,0]
	v_pk_mul_f32 v[28:29], v[28:29], v[174:175] op_sel_hi:[1,0]
	v_pk_mul_f32 v[30:31], v[30:31], v[174:175] op_sel_hi:[1,0]
	v_pk_mul_f32 v[32:33], v[32:33], v[174:175] op_sel_hi:[1,0]
	v_pk_mul_f32 v[34:35], v[34:35], v[174:175] op_sel_hi:[1,0]
	v_pk_mul_f32 v[36:37], v[36:37], v[174:175] op_sel_hi:[1,0]
	v_pk_mul_f32 v[38:39], v[38:39], v[174:175] op_sel_hi:[1,0]
	v_pk_mul_f32 v[40:41], v[40:41], v[174:175] op_sel_hi:[1,0]
	v_pk_mul_f32 v[42:43], v[42:43], v[174:175] op_sel_hi:[1,0]
	v_pk_mul_f32 v[44:45], v[44:45], v[174:175] op_sel_hi:[1,0]
	v_pk_mul_f32 v[46:47], v[46:47], v[174:175] op_sel_hi:[1,0]
	v_pk_mul_f32 v[48:49], v[48:49], v[174:175] op_sel_hi:[1,0]
	v_pk_mul_f32 v[50:51], v[50:51], v[174:175] op_sel_hi:[1,0]
	v_pk_mul_f32 v[52:53], v[52:53], v[174:175] op_sel_hi:[1,0]
	v_pk_mul_f32 v[54:55], v[54:55], v[174:175] op_sel_hi:[1,0]
	v_pk_mul_f32 v[56:57], v[56:57], v[174:175] op_sel_hi:[1,0]
	v_pk_mul_f32 v[58:59], v[58:59], v[174:175] op_sel_hi:[1,0]
	v_pk_mul_f32 v[60:61], v[60:61], v[174:175] op_sel_hi:[1,0]
	v_pk_mul_f32 v[62:63], v[62:63], v[174:175] op_sel_hi:[1,0]
	s_nop 1

.Lattn_end:
	ds_bpermute_b32 v65, v165, v64
	s_and_b64 vcc, exec, s[28:29]
	s_waitcnt lgkmcnt(0)
	v_add_f32_e32 v64, v64, v65
	s_cbranch_vccz .LBB0_651
	v_div_scale_f32 v65, s[40:41], v64, v64, v177
	v_rcp_f32_e32 v66, v65
	v_div_scale_f32 v67, vcc, v177, v64, v177
	v_fma_f32 v68, -v65, v66, 1.0
	v_fmac_f32_e32 v66, v68, v66
	v_mul_f32_e32 v68, v67, v66
	v_fma_f32 v69, -v65, v68, v67
	v_fmac_f32_e32 v68, v69, v66
	v_fma_f32 v65, -v65, v68, v67
	v_div_fmas_f32 v65, v65, v66, v68
	v_div_fixup_f32 v65, v65, v64, v177
	v_mul_f32_e32 v66, v48, v65
	v_mul_f32_e32 v67, v49, v65
	ds_write2st64_b32 v181, v66, v67 offset1:1
	v_mul_f32_e32 v66, v50, v65
	v_mul_f32_e32 v67, v51, v65
	ds_write2st64_b32 v181, v66, v67 offset0:2 offset1:3
	v_mul_f32_e32 v66, v52, v65
	v_mul_f32_e32 v67, v53, v65
	ds_write2st64_b32 v181, v66, v67 offset0:4 offset1:5
	v_mul_f32_e32 v66, v54, v65
	v_mul_f32_e32 v67, v55, v65
	ds_write2st64_b32 v181, v66, v67 offset0:6 offset1:7
	v_mul_f32_e32 v66, v56, v65
	v_mul_f32_e32 v67, v57, v65
	ds_write2st64_b32 v181, v66, v67 offset0:8 offset1:9
	v_mul_f32_e32 v66, v58, v65
	v_mul_f32_e32 v67, v59, v65
	ds_write2st64_b32 v181, v66, v67 offset0:10 offset1:11
	v_mul_f32_e32 v66, v60, v65
	v_mul_f32_e32 v67, v61, v65
	ds_write2st64_b32 v181, v66, v67 offset0:12 offset1:13
	v_mul_f32_e32 v66, v62, v65
	v_mul_f32_e32 v67, v63, v65
	ds_write2st64_b32 v181, v66, v67 offset0:14 offset1:15
	v_mul_f32_e32 v66, v32, v65
	v_mul_f32_e32 v67, v33, v65
	ds_write2st64_b32 v181, v66, v67 offset0:16 offset1:17
	v_mul_f32_e32 v66, v34, v65
	v_mul_f32_e32 v67, v35, v65
	ds_write2st64_b32 v181, v66, v67 offset0:18 offset1:19
	v_mul_f32_e32 v66, v36, v65
	v_mul_f32_e32 v67, v37, v65
	ds_write2st64_b32 v181, v66, v67 offset0:20 offset1:21
	v_mul_f32_e32 v66, v38, v65
	v_mul_f32_e32 v67, v39, v65
	ds_write2st64_b32 v181, v66, v67 offset0:22 offset1:23
	v_mul_f32_e32 v66, v40, v65
	v_mul_f32_e32 v67, v41, v65
	ds_write2st64_b32 v181, v66, v67 offset0:24 offset1:25
	v_mul_f32_e32 v66, v42, v65
	v_mul_f32_e32 v67, v43, v65
	ds_write2st64_b32 v181, v66, v67 offset0:26 offset1:27
	v_mul_f32_e32 v66, v44, v65
	v_mul_f32_e32 v67, v45, v65
	ds_write2st64_b32 v181, v66, v67 offset0:28 offset1:29
	v_mul_f32_e32 v66, v46, v65
	v_mul_f32_e32 v67, v47, v65
	ds_write2st64_b32 v181, v66, v67 offset0:30 offset1:31
	v_mul_f32_e32 v66, v16, v65
	v_mul_f32_e32 v67, v17, v65
	ds_write2st64_b32 v181, v66, v67 offset0:32 offset1:33
	v_mul_f32_e32 v66, v18, v65
	v_mul_f32_e32 v67, v19, v65
	ds_write2st64_b32 v181, v66, v67 offset0:34 offset1:35
	v_mul_f32_e32 v66, v20, v65
	v_mul_f32_e32 v67, v21, v65
	ds_write2st64_b32 v181, v66, v67 offset0:36 offset1:37
	v_mul_f32_e32 v66, v22, v65
	v_mul_f32_e32 v67, v23, v65
	ds_write2st64_b32 v181, v66, v67 offset0:38 offset1:39
	v_mul_f32_e32 v66, v24, v65
	v_mul_f32_e32 v67, v25, v65
	ds_write2st64_b32 v181, v66, v67 offset0:40 offset1:41
	v_mul_f32_e32 v66, v26, v65
	v_mul_f32_e32 v67, v27, v65
	ds_write2st64_b32 v181, v66, v67 offset0:42 offset1:43
	v_mul_f32_e32 v66, v28, v65
	v_mul_f32_e32 v67, v29, v65
	ds_write2st64_b32 v181, v66, v67 offset0:44 offset1:45
	v_mul_f32_e32 v66, v30, v65
	v_mul_f32_e32 v67, v31, v65
	ds_write2st64_b32 v181, v66, v67 offset0:46 offset1:47
	v_mul_f32_e32 v66, v0, v65
	v_mul_f32_e32 v67, v1, v65
	ds_write2st64_b32 v181, v66, v67 offset0:48 offset1:49
	v_mul_f32_e32 v66, v2, v65
	v_mul_f32_e32 v67, v3, v65
	ds_write2st64_b32 v181, v66, v67 offset0:50 offset1:51
	v_mul_f32_e32 v66, v4, v65
	v_mul_f32_e32 v67, v5, v65
	ds_write2st64_b32 v181, v66, v67 offset0:52 offset1:53
	v_mul_f32_e32 v66, v6, v65
	v_mul_f32_e32 v67, v7, v65
	ds_write2st64_b32 v181, v66, v67 offset0:54 offset1:55
	v_mul_f32_e32 v66, v8, v65
	v_mul_f32_e32 v67, v9, v65
	ds_write2st64_b32 v181, v66, v67 offset0:56 offset1:57
	v_mul_f32_e32 v66, v10, v65
	v_mul_f32_e32 v67, v11, v65
	ds_write2st64_b32 v181, v66, v67 offset0:58 offset1:59
	v_mul_f32_e32 v66, v12, v65
	v_mul_f32_e32 v67, v13, v65
	ds_write2st64_b32 v181, v66, v67 offset0:60 offset1:61
	v_mul_f32_e32 v66, v14, v65
	v_mul_f32_e32 v65, v15, v65
	ds_write2st64_b32 v181, v66, v65 offset0:62 offset1:63
